# K-loop priority raised on the loading wave instead of the MFMA wave
# speedup vs baseline: 1.0084x; 1.0084x over previous
.Lrs_i1_pre:
	s_add_u32 s1, s28, 0xfffc0080
	s_addc_u32 s22, s29, -1
	s_add_i32 s23, 0, 0x10000
	v_add_u32_e32 v142, s23, v195
	ds_read_b128 v[130:133], v142
	ds_read_b128 v[134:137], v142 offset:1024
	ds_read_b128 v[138:141], v142 offset:2048
	ds_read_b128 v[142:145], v142 offset:3072
	s_cmp_eq_u32 s69, 12
	s_cselect_b32 s57, s21, s22
	s_cselect_b32 s56, s34, s1
	s_cselect_b32 s31, s47, s68
	s_cselect_b32 s30, s49, s67
	v_lshl_add_u64 v[176:177], s[28:29], 0, v[178:179]
	s_add_i32 m0, s59, 0xc000
	ds_read_b128 v[146:149], v197
	ds_read_b128 v[150:153], v197 offset:1024
	ds_read_b128 v[182:185], v197 offset:2048
	ds_read_b128 v[186:189], v197 offset:3072
	ds_read_b128 v[190:193], v197 offset:4096
	ds_read_b128 v[198:201], v197 offset:5120
	ds_read_b128 v[202:205], v197 offset:6144
	ds_read_b128 v[206:209], v197 offset:7168
	global_load_lds_dwordx4 v[176:177], off
	v_lshl_add_u64 v[176:177], s[28:29], 0, v[180:181]
	s_add_i32 m0, s59, 0xe000
	s_nop 0
	global_load_lds_dwordx4 v[176:177], off
	s_add_i32 s1, 0, 0x14000
	v_add_u32_e32 v168, s1, v195
	ds_read_b128 v[216:219], v168
	ds_read_b128 v[230:233], v168 offset:1024
	ds_read_b128 v[234:237], v168 offset:2048
	ds_read_b128 v[238:241], v168 offset:3072
	s_waitcnt vmcnt(8)
	s_waitcnt lgkmcnt(0)
	s_barrier
	s_setprio 0
	v_mfma_f32_16x16x32_bf16 v[126:129], v[130:133], v[146:149], 0
	v_mfma_f32_16x16x32_bf16 v[122:125], v[138:141], v[146:149], 0
	v_mfma_f32_16x16x32_bf16 v[110:113], v[130:133], v[182:185], 0
	v_mfma_f32_16x16x32_bf16 v[106:109], v[138:141], v[182:185], 0
	v_mfma_f32_16x16x32_bf16 v[94:97], v[130:133], v[190:193], 0
	v_mfma_f32_16x16x32_bf16 v[90:93], v[138:141], v[190:193], 0
	v_mfma_f32_16x16x32_bf16 v[78:81], v[130:133], v[202:205], 0
	v_mfma_f32_16x16x32_bf16 v[74:77], v[138:141], v[202:205], 0
	v_mfma_f32_16x16x32_bf16 v[126:129], v[134:137], v[150:153], v[126:129]
	v_mfma_f32_16x16x32_bf16 v[122:125], v[142:145], v[150:153], v[122:125]
	v_mfma_f32_16x16x32_bf16 v[110:113], v[134:137], v[186:189], v[110:113]
	v_mfma_f32_16x16x32_bf16 v[106:109], v[142:145], v[186:189], v[106:109]
	v_mfma_f32_16x16x32_bf16 v[94:97], v[134:137], v[198:201], v[94:97]
	v_mfma_f32_16x16x32_bf16 v[90:93], v[142:145], v[198:201], v[90:93]
	v_mfma_f32_16x16x32_bf16 v[78:81], v[134:137], v[206:209], v[78:81]
	v_mfma_f32_16x16x32_bf16 v[74:77], v[142:145], v[206:209], v[74:77]
	v_mfma_f32_16x16x32_bf16 v[118:121], v[216:219], v[146:149], 0
	v_mfma_f32_16x16x32_bf16 v[114:117], v[234:237], v[146:149], 0
	v_mfma_f32_16x16x32_bf16 v[102:105], v[216:219], v[182:185], 0
	v_mfma_f32_16x16x32_bf16 v[98:101], v[234:237], v[182:185], 0
	v_mfma_f32_16x16x32_bf16 v[86:89], v[216:219], v[190:193], 0
	v_mfma_f32_16x16x32_bf16 v[82:85], v[234:237], v[190:193], 0
	v_mfma_f32_16x16x32_bf16 v[70:73], v[216:219], v[202:205], 0
	v_mfma_f32_16x16x32_bf16 v[66:69], v[234:237], v[202:205], 0
	v_mfma_f32_16x16x32_bf16 v[118:121], v[230:233], v[150:153], v[118:121]
	v_mfma_f32_16x16x32_bf16 v[114:117], v[238:241], v[150:153], v[114:117]
	v_mfma_f32_16x16x32_bf16 v[102:105], v[230:233], v[186:189], v[102:105]
	v_mfma_f32_16x16x32_bf16 v[98:101], v[238:241], v[186:189], v[98:101]
	v_mfma_f32_16x16x32_bf16 v[86:89], v[230:233], v[198:201], v[86:89]
	v_mfma_f32_16x16x32_bf16 v[82:85], v[238:241], v[198:201], v[82:85]
	v_mfma_f32_16x16x32_bf16 v[70:73], v[230:233], v[206:209], v[70:73]
	v_mfma_f32_16x16x32_bf16 v[66:69], v[238:241], v[206:209], v[66:69]
	s_setprio 1
	s_barrier
	ds_read_b128 v[146:149], v197 offset:16384
	ds_read_b128 v[150:153], v197 offset:17408
	ds_read_b128 v[182:185], v197 offset:18432
	ds_read_b128 v[186:189], v197 offset:19456
	ds_read_b128 v[190:193], v197 offset:20480
	ds_read_b128 v[198:201], v197 offset:21504
	ds_read_b128 v[202:205], v197 offset:22528
	ds_read_b128 v[206:209], v197 offset:23552
	s_add_i32 s22, s23, s58
	v_lshl_add_u64 v[176:177], s[30:31], 0, v[0:1]
	s_mov_b32 m0, s22
	s_nop 0
	global_load_lds_dwordx4 v[176:177], off
	v_lshl_add_u64 v[220:221], s[30:31], 0, v[154:155]
	s_add_i32 m0, s22, 0x2000
	s_nop 0
	global_load_lds_dwordx4 v[220:221], off
	s_mov_b32 m0, s59
	v_lshl_add_u64 v[242:243], s[56:57], 0, v[158:159]
	global_load_lds_dwordx4 v[242:243], off
	v_lshl_add_u64 v[244:245], s[56:57], 0, v[156:157]
	s_mov_b32 m0, s60
	s_nop 0
	global_load_lds_dwordx4 v[244:245], off
	s_add_u32 s22, s30, 0x40000
	s_addc_u32 s23, s31, 0
	s_add_i32 s1, s1, s58
	s_mov_b32 m0, s1
	s_nop 0
	global_load_lds_dwordx4 v0, s[22:23]
	s_add_i32 m0, s1, 0x2000
	s_nop 0
	global_load_lds_dwordx4 v154, s[22:23]
	s_waitcnt vmcnt(8)
	s_waitcnt lgkmcnt(0)
	s_barrier
	s_setprio 0
	v_mfma_f32_16x16x32_bf16 v[62:65], v[130:133], v[146:149], 0
	v_mfma_f32_16x16x32_bf16 v[58:61], v[138:141], v[146:149], 0
	v_mfma_f32_16x16x32_bf16 v[46:49], v[130:133], v[182:185], 0
	v_mfma_f32_16x16x32_bf16 v[42:45], v[138:141], v[182:185], 0
	v_mfma_f32_16x16x32_bf16 v[30:33], v[130:133], v[190:193], 0
	v_mfma_f32_16x16x32_bf16 v[26:29], v[138:141], v[190:193], 0
	v_mfma_f32_16x16x32_bf16 v[14:17], v[130:133], v[202:205], 0
	v_mfma_f32_16x16x32_bf16 v[10:13], v[138:141], v[202:205], 0
	v_mfma_f32_16x16x32_bf16 v[62:65], v[134:137], v[150:153], v[62:65]
	v_mfma_f32_16x16x32_bf16 v[58:61], v[142:145], v[150:153], v[58:61]
	v_mfma_f32_16x16x32_bf16 v[46:49], v[134:137], v[186:189], v[46:49]
	v_mfma_f32_16x16x32_bf16 v[42:45], v[142:145], v[186:189], v[42:45]
	v_mfma_f32_16x16x32_bf16 v[30:33], v[134:137], v[198:201], v[30:33]
	v_mfma_f32_16x16x32_bf16 v[26:29], v[142:145], v[198:201], v[26:29]
	v_mfma_f32_16x16x32_bf16 v[14:17], v[134:137], v[206:209], v[14:17]
	v_mfma_f32_16x16x32_bf16 v[10:13], v[142:145], v[206:209], v[10:13]
	v_mfma_f32_16x16x32_bf16 v[54:57], v[216:219], v[146:149], 0
	v_mfma_f32_16x16x32_bf16 v[50:53], v[234:237], v[146:149], 0
	v_mfma_f32_16x16x32_bf16 v[38:41], v[216:219], v[182:185], 0
	v_mfma_f32_16x16x32_bf16 v[34:37], v[234:237], v[182:185], 0
	v_mfma_f32_16x16x32_bf16 v[22:25], v[216:219], v[190:193], 0
	v_mfma_f32_16x16x32_bf16 v[18:21], v[234:237], v[190:193], 0
	v_mfma_f32_16x16x32_bf16 v[6:9], v[216:219], v[202:205], 0
	v_mfma_f32_16x16x32_bf16 v[2:5], v[234:237], v[202:205], 0
	v_mfma_f32_16x16x32_bf16 v[54:57], v[230:233], v[150:153], v[54:57]
	v_mfma_f32_16x16x32_bf16 v[50:53], v[238:241], v[150:153], v[50:53]
	v_mfma_f32_16x16x32_bf16 v[38:41], v[230:233], v[186:189], v[38:41]
	v_mfma_f32_16x16x32_bf16 v[34:37], v[238:241], v[186:189], v[34:37]
	v_mfma_f32_16x16x32_bf16 v[22:25], v[230:233], v[198:201], v[22:25]
	v_mfma_f32_16x16x32_bf16 v[18:21], v[238:241], v[198:201], v[18:21]
	v_mfma_f32_16x16x32_bf16 v[6:9], v[230:233], v[206:209], v[6:9]
	v_mfma_f32_16x16x32_bf16 v[2:5], v[238:241], v[206:209], v[2:5]
	s_setprio 1
	s_barrier
	s_add_i32 s1, 0, 0x18000
	v_add_u32_e32 v142, s1, v195
	ds_read_b128 v[130:133], v142
	ds_read_b128 v[134:137], v142 offset:1024
	ds_read_b128 v[138:141], v142 offset:2048
	ds_read_b128 v[142:145], v142 offset:3072
	s_add_u32 s22, s56, 0x40000
	s_addc_u32 s23, s57, 0
	s_mov_b32 m0, s61
	v_lshl_add_u64 v[216:217], s[22:23], 0, v[158:159]
	ds_read_b128 v[146:149], v197 offset:32768
	ds_read_b128 v[150:153], v197 offset:33792
	ds_read_b128 v[182:185], v197 offset:34816
	ds_read_b128 v[186:189], v197 offset:35840
	ds_read_b128 v[190:193], v197 offset:36864
	ds_read_b128 v[198:201], v197 offset:37888
	ds_read_b128 v[202:205], v197 offset:38912
	ds_read_b128 v[206:209], v197 offset:39936
	global_load_lds_dwordx4 v[216:217], off
	v_lshl_add_u64 v[216:217], s[22:23], 0, v[156:157]
	s_mov_b32 m0, s62
	s_nop 0
	global_load_lds_dwordx4 v[216:217], off
	s_add_i32 s33, 0, 0x1c000
	v_add_u32_e32 v168, s33, v195
	ds_read_b128 v[216:219], v168
	ds_read_b128 v[230:233], v168 offset:1024
	ds_read_b128 v[234:237], v168 offset:2048
	ds_read_b128 v[238:241], v168 offset:3072
	s_waitcnt vmcnt(8)
	s_waitcnt lgkmcnt(0)
	s_barrier
	s_setprio 0
	v_mfma_f32_16x16x32_bf16 v[126:129], v[130:133], v[146:149], v[126:129]
	v_mfma_f32_16x16x32_bf16 v[122:125], v[138:141], v[146:149], v[122:125]
	v_mfma_f32_16x16x32_bf16 v[110:113], v[130:133], v[182:185], v[110:113]
	v_mfma_f32_16x16x32_bf16 v[106:109], v[138:141], v[182:185], v[106:109]
	v_mfma_f32_16x16x32_bf16 v[94:97], v[130:133], v[190:193], v[94:97]
	v_mfma_f32_16x16x32_bf16 v[90:93], v[138:141], v[190:193], v[90:93]
	v_mfma_f32_16x16x32_bf16 v[78:81], v[130:133], v[202:205], v[78:81]
	v_mfma_f32_16x16x32_bf16 v[74:77], v[138:141], v[202:205], v[74:77]
	v_mfma_f32_16x16x32_bf16 v[126:129], v[134:137], v[150:153], v[126:129]
	v_mfma_f32_16x16x32_bf16 v[122:125], v[142:145], v[150:153], v[122:125]
	v_mfma_f32_16x16x32_bf16 v[110:113], v[134:137], v[186:189], v[110:113]
	v_mfma_f32_16x16x32_bf16 v[106:109], v[142:145], v[186:189], v[106:109]
	v_mfma_f32_16x16x32_bf16 v[94:97], v[134:137], v[198:201], v[94:97]
	v_mfma_f32_16x16x32_bf16 v[90:93], v[142:145], v[198:201], v[90:93]
	v_mfma_f32_16x16x32_bf16 v[78:81], v[134:137], v[206:209], v[78:81]
	v_mfma_f32_16x16x32_bf16 v[74:77], v[142:145], v[206:209], v[74:77]
	v_mfma_f32_16x16x32_bf16 v[118:121], v[216:219], v[146:149], v[118:121]
	v_mfma_f32_16x16x32_bf16 v[114:117], v[234:237], v[146:149], v[114:117]
	v_mfma_f32_16x16x32_bf16 v[102:105], v[216:219], v[182:185], v[102:105]
	v_mfma_f32_16x16x32_bf16 v[98:101], v[234:237], v[182:185], v[98:101]
	v_mfma_f32_16x16x32_bf16 v[86:89], v[216:219], v[190:193], v[86:89]
	v_mfma_f32_16x16x32_bf16 v[82:85], v[234:237], v[190:193], v[82:85]
	v_mfma_f32_16x16x32_bf16 v[70:73], v[216:219], v[202:205], v[70:73]
	v_mfma_f32_16x16x32_bf16 v[66:69], v[234:237], v[202:205], v[66:69]
	v_mfma_f32_16x16x32_bf16 v[118:121], v[230:233], v[150:153], v[118:121]
	v_mfma_f32_16x16x32_bf16 v[114:117], v[238:241], v[150:153], v[114:117]
	v_mfma_f32_16x16x32_bf16 v[102:105], v[230:233], v[186:189], v[102:105]
	v_mfma_f32_16x16x32_bf16 v[98:101], v[238:241], v[186:189], v[98:101]
	v_mfma_f32_16x16x32_bf16 v[86:89], v[230:233], v[198:201], v[86:89]
	v_mfma_f32_16x16x32_bf16 v[82:85], v[238:241], v[198:201], v[82:85]
	v_mfma_f32_16x16x32_bf16 v[70:73], v[230:233], v[206:209], v[70:73]
	v_mfma_f32_16x16x32_bf16 v[66:69], v[238:241], v[206:209], v[66:69]
	s_setprio 1
	s_barrier
	ds_read_b128 v[146:149], v197 offset:49152
	ds_read_b128 v[150:153], v197 offset:50176
	ds_read_b128 v[182:185], v197 offset:51200
	ds_read_b128 v[186:189], v197 offset:52224
	ds_read_b128 v[190:193], v197 offset:53248
	ds_read_b128 v[198:201], v197 offset:54272
	ds_read_b128 v[202:205], v197 offset:55296
	ds_read_b128 v[206:209], v197 offset:56320
	s_add_i32 s1, s1, s58
	v_lshl_add_u64 v[176:177], v[176:177], 0, s[12:13]
	s_mov_b32 m0, s1
	s_nop 0
	global_load_lds_dwordx4 v[176:177], off
	v_lshl_add_u64 v[176:177], v[220:221], 0, s[12:13]
	s_add_i32 m0, s1, 0x2000
	s_nop 0
	global_load_lds_dwordx4 v[176:177], off
	s_mov_b32 m0, s64
	v_lshl_add_u64 v[176:177], v[242:243], 0, s[12:13]
	global_load_lds_dwordx4 v[176:177], off
	v_lshl_add_u64 v[176:177], v[244:245], 0, s[12:13]
	s_mov_b32 m0, s65
	s_nop 0
	global_load_lds_dwordx4 v[176:177], off
	s_add_u32 s22, s30, 0x40080
	s_addc_u32 s23, s31, 0
	s_add_i32 s1, s33, s58
	s_mov_b32 m0, s1
	s_nop 0
	global_load_lds_dwordx4 v0, s[22:23]
	s_add_i32 m0, s1, 0x2000
	s_nop 0
	global_load_lds_dwordx4 v154, s[22:23]
	s_waitcnt vmcnt(8)
	s_waitcnt lgkmcnt(0)
	s_barrier
	s_setprio 0
	v_mfma_f32_16x16x32_bf16 v[62:65], v[130:133], v[146:149], v[62:65]
	v_mfma_f32_16x16x32_bf16 v[58:61], v[138:141], v[146:149], v[58:61]
	v_mfma_f32_16x16x32_bf16 v[46:49], v[130:133], v[182:185], v[46:49]
	v_mfma_f32_16x16x32_bf16 v[42:45], v[138:141], v[182:185], v[42:45]
	v_mfma_f32_16x16x32_bf16 v[30:33], v[130:133], v[190:193], v[30:33]
	v_mfma_f32_16x16x32_bf16 v[26:29], v[138:141], v[190:193], v[26:29]
	v_mfma_f32_16x16x32_bf16 v[14:17], v[130:133], v[202:205], v[14:17]
	v_mfma_f32_16x16x32_bf16 v[10:13], v[138:141], v[202:205], v[10:13]
	v_mfma_f32_16x16x32_bf16 v[62:65], v[134:137], v[150:153], v[62:65]
	v_mfma_f32_16x16x32_bf16 v[58:61], v[142:145], v[150:153], v[58:61]
	v_mfma_f32_16x16x32_bf16 v[46:49], v[134:137], v[186:189], v[46:49]
	v_mfma_f32_16x16x32_bf16 v[42:45], v[142:145], v[186:189], v[42:45]
	v_mfma_f32_16x16x32_bf16 v[30:33], v[134:137], v[198:201], v[30:33]
	v_mfma_f32_16x16x32_bf16 v[26:29], v[142:145], v[198:201], v[26:29]
	v_mfma_f32_16x16x32_bf16 v[14:17], v[134:137], v[206:209], v[14:17]
	v_mfma_f32_16x16x32_bf16 v[10:13], v[142:145], v[206:209], v[10:13]
	v_mfma_f32_16x16x32_bf16 v[54:57], v[216:219], v[146:149], v[54:57]
	v_mfma_f32_16x16x32_bf16 v[50:53], v[234:237], v[146:149], v[50:53]
	v_mfma_f32_16x16x32_bf16 v[38:41], v[216:219], v[182:185], v[38:41]
	v_mfma_f32_16x16x32_bf16 v[34:37], v[234:237], v[182:185], v[34:37]
	v_mfma_f32_16x16x32_bf16 v[22:25], v[216:219], v[190:193], v[22:25]
	v_mfma_f32_16x16x32_bf16 v[18:21], v[234:237], v[190:193], v[18:21]
	v_mfma_f32_16x16x32_bf16 v[6:9], v[216:219], v[202:205], v[6:9]
	v_mfma_f32_16x16x32_bf16 v[2:5], v[234:237], v[202:205], v[2:5]
	v_mfma_f32_16x16x32_bf16 v[54:57], v[230:233], v[150:153], v[54:57]
	v_mfma_f32_16x16x32_bf16 v[50:53], v[238:241], v[150:153], v[50:53]
	v_mfma_f32_16x16x32_bf16 v[38:41], v[230:233], v[186:189], v[38:41]
	v_mfma_f32_16x16x32_bf16 v[34:37], v[238:241], v[186:189], v[34:37]
	v_mfma_f32_16x16x32_bf16 v[22:25], v[230:233], v[198:201], v[22:25]
	v_mfma_f32_16x16x32_bf16 v[18:21], v[238:241], v[198:201], v[18:21]
	v_mfma_f32_16x16x32_bf16 v[6:9], v[230:233], v[206:209], v[6:9]
	v_mfma_f32_16x16x32_bf16 v[2:5], v[238:241], v[206:209], v[2:5]
	s_setprio 1
	s_add_i32 s69, s69, 2
	s_add_u32 s28, s28, 0x100
	s_addc_u32 s29, s29, 0
	s_add_u32 s67, s67, 0x100
	s_addc_u32 s68, s68, 0
	s_cmp_gt_u32 s69, 13
	s_barrier
.LBB0_47:
	s_add_u32 s1, s28, 0xfffc0080
	s_addc_u32 s22, s29, -1
	s_add_i32 s23, 0, 0x10000
	v_add_u32_e32 v142, s23, v195
	ds_read_b128 v[130:133], v142
	ds_read_b128 v[134:137], v142 offset:1024
	ds_read_b128 v[138:141], v142 offset:2048
	ds_read_b128 v[142:145], v142 offset:3072
	s_cmp_eq_u32 s69, 12
	s_cselect_b32 s57, s21, s22
	s_cselect_b32 s56, s34, s1
	s_cselect_b32 s31, s47, s68
	s_cselect_b32 s30, s49, s67
	v_lshl_add_u64 v[176:177], s[28:29], 0, v[178:179]
	s_add_i32 m0, s59, 0xc000
	ds_read_b128 v[146:149], v197
	ds_read_b128 v[150:153], v197 offset:1024
	ds_read_b128 v[182:185], v197 offset:2048
	ds_read_b128 v[186:189], v197 offset:3072
	ds_read_b128 v[190:193], v197 offset:4096
	ds_read_b128 v[198:201], v197 offset:5120
	ds_read_b128 v[202:205], v197 offset:6144
	ds_read_b128 v[206:209], v197 offset:7168
	global_load_lds_dwordx4 v[176:177], off
	v_lshl_add_u64 v[176:177], s[28:29], 0, v[180:181]
	s_add_i32 m0, s59, 0xe000
	s_nop 0
	global_load_lds_dwordx4 v[176:177], off
	s_add_i32 s1, 0, 0x14000
	v_add_u32_e32 v168, s1, v195
	ds_read_b128 v[216:219], v168
	ds_read_b128 v[230:233], v168 offset:1024
	ds_read_b128 v[234:237], v168 offset:2048
	ds_read_b128 v[238:241], v168 offset:3072
	s_waitcnt vmcnt(8)
	s_waitcnt lgkmcnt(0)
	s_barrier
	s_setprio 0
	v_mfma_f32_16x16x32_bf16 v[126:129], v[130:133], v[146:149], v[126:129]
	v_mfma_f32_16x16x32_bf16 v[122:125], v[138:141], v[146:149], v[122:125]
	v_mfma_f32_16x16x32_bf16 v[110:113], v[130:133], v[182:185], v[110:113]
	v_mfma_f32_16x16x32_bf16 v[106:109], v[138:141], v[182:185], v[106:109]
	v_mfma_f32_16x16x32_bf16 v[94:97], v[130:133], v[190:193], v[94:97]
	v_mfma_f32_16x16x32_bf16 v[90:93], v[138:141], v[190:193], v[90:93]
	v_mfma_f32_16x16x32_bf16 v[78:81], v[130:133], v[202:205], v[78:81]
	v_mfma_f32_16x16x32_bf16 v[74:77], v[138:141], v[202:205], v[74:77]
	v_mfma_f32_16x16x32_bf16 v[126:129], v[134:137], v[150:153], v[126:129]
	v_mfma_f32_16x16x32_bf16 v[122:125], v[142:145], v[150:153], v[122:125]
	v_mfma_f32_16x16x32_bf16 v[110:113], v[134:137], v[186:189], v[110:113]
	v_mfma_f32_16x16x32_bf16 v[106:109], v[142:145], v[186:189], v[106:109]
	v_mfma_f32_16x16x32_bf16 v[94:97], v[134:137], v[198:201], v[94:97]
	v_mfma_f32_16x16x32_bf16 v[90:93], v[142:145], v[198:201], v[90:93]
	v_mfma_f32_16x16x32_bf16 v[78:81], v[134:137], v[206:209], v[78:81]
	v_mfma_f32_16x16x32_bf16 v[74:77], v[142:145], v[206:209], v[74:77]
	v_mfma_f32_16x16x32_bf16 v[118:121], v[216:219], v[146:149], v[118:121]
	v_mfma_f32_16x16x32_bf16 v[114:117], v[234:237], v[146:149], v[114:117]
	v_mfma_f32_16x16x32_bf16 v[102:105], v[216:219], v[182:185], v[102:105]
	v_mfma_f32_16x16x32_bf16 v[98:101], v[234:237], v[182:185], v[98:101]
	v_mfma_f32_16x16x32_bf16 v[86:89], v[216:219], v[190:193], v[86:89]
	v_mfma_f32_16x16x32_bf16 v[82:85], v[234:237], v[190:193], v[82:85]
	v_mfma_f32_16x16x32_bf16 v[70:73], v[216:219], v[202:205], v[70:73]
	v_mfma_f32_16x16x32_bf16 v[66:69], v[234:237], v[202:205], v[66:69]
	v_mfma_f32_16x16x32_bf16 v[118:121], v[230:233], v[150:153], v[118:121]
	v_mfma_f32_16x16x32_bf16 v[114:117], v[238:241], v[150:153], v[114:117]
	v_mfma_f32_16x16x32_bf16 v[102:105], v[230:233], v[186:189], v[102:105]
	v_mfma_f32_16x16x32_bf16 v[98:101], v[238:241], v[186:189], v[98:101]
	v_mfma_f32_16x16x32_bf16 v[86:89], v[230:233], v[198:201], v[86:89]
	v_mfma_f32_16x16x32_bf16 v[82:85], v[238:241], v[198:201], v[82:85]
	v_mfma_f32_16x16x32_bf16 v[70:73], v[230:233], v[206:209], v[70:73]
	v_mfma_f32_16x16x32_bf16 v[66:69], v[238:241], v[206:209], v[66:69]
	s_setprio 1
	s_barrier
	ds_read_b128 v[146:149], v197 offset:16384
	ds_read_b128 v[150:153], v197 offset:17408
	ds_read_b128 v[182:185], v197 offset:18432
	ds_read_b128 v[186:189], v197 offset:19456
	ds_read_b128 v[190:193], v197 offset:20480
	ds_read_b128 v[198:201], v197 offset:21504
	ds_read_b128 v[202:205], v197 offset:22528
	ds_read_b128 v[206:209], v197 offset:23552
	s_add_i32 s22, s23, s58
	v_lshl_add_u64 v[176:177], s[30:31], 0, v[0:1]
	s_mov_b32 m0, s22
	s_nop 0
	global_load_lds_dwordx4 v[176:177], off
	v_lshl_add_u64 v[220:221], s[30:31], 0, v[154:155]
	s_add_i32 m0, s22, 0x2000
	s_nop 0
	global_load_lds_dwordx4 v[220:221], off
	s_mov_b32 m0, s59
	v_lshl_add_u64 v[242:243], s[56:57], 0, v[158:159]
	global_load_lds_dwordx4 v[242:243], off
	v_lshl_add_u64 v[244:245], s[56:57], 0, v[156:157]
	s_mov_b32 m0, s60
	s_nop 0
	global_load_lds_dwordx4 v[244:245], off
	s_add_u32 s22, s30, 0x40000
	s_addc_u32 s23, s31, 0
	s_add_i32 s1, s1, s58
	s_mov_b32 m0, s1
	s_nop 0
	global_load_lds_dwordx4 v0, s[22:23]
	s_add_i32 m0, s1, 0x2000
	s_nop 0
	global_load_lds_dwordx4 v154, s[22:23]
	s_waitcnt vmcnt(8)
	s_waitcnt lgkmcnt(0)
	s_barrier
	s_setprio 0
	v_mfma_f32_16x16x32_bf16 v[62:65], v[130:133], v[146:149], v[62:65]
	v_mfma_f32_16x16x32_bf16 v[58:61], v[138:141], v[146:149], v[58:61]
	v_mfma_f32_16x16x32_bf16 v[46:49], v[130:133], v[182:185], v[46:49]
	v_mfma_f32_16x16x32_bf16 v[42:45], v[138:141], v[182:185], v[42:45]
	v_mfma_f32_16x16x32_bf16 v[30:33], v[130:133], v[190:193], v[30:33]
	v_mfma_f32_16x16x32_bf16 v[26:29], v[138:141], v[190:193], v[26:29]
	v_mfma_f32_16x16x32_bf16 v[14:17], v[130:133], v[202:205], v[14:17]
	v_mfma_f32_16x16x32_bf16 v[10:13], v[138:141], v[202:205], v[10:13]
	v_mfma_f32_16x16x32_bf16 v[62:65], v[134:137], v[150:153], v[62:65]
	v_mfma_f32_16x16x32_bf16 v[58:61], v[142:145], v[150:153], v[58:61]
	v_mfma_f32_16x16x32_bf16 v[46:49], v[134:137], v[186:189], v[46:49]
	v_mfma_f32_16x16x32_bf16 v[42:45], v[142:145], v[186:189], v[42:45]
	v_mfma_f32_16x16x32_bf16 v[30:33], v[134:137], v[198:201], v[30:33]
	v_mfma_f32_16x16x32_bf16 v[26:29], v[142:145], v[198:201], v[26:29]
	v_mfma_f32_16x16x32_bf16 v[14:17], v[134:137], v[206:209], v[14:17]
	v_mfma_f32_16x16x32_bf16 v[10:13], v[142:145], v[206:209], v[10:13]
	v_mfma_f32_16x16x32_bf16 v[54:57], v[216:219], v[146:149], v[54:57]
	v_mfma_f32_16x16x32_bf16 v[50:53], v[234:237], v[146:149], v[50:53]
	v_mfma_f32_16x16x32_bf16 v[38:41], v[216:219], v[182:185], v[38:41]
	v_mfma_f32_16x16x32_bf16 v[34:37], v[234:237], v[182:185], v[34:37]
	v_mfma_f32_16x16x32_bf16 v[22:25], v[216:219], v[190:193], v[22:25]
	v_mfma_f32_16x16x32_bf16 v[18:21], v[234:237], v[190:193], v[18:21]
	v_mfma_f32_16x16x32_bf16 v[6:9], v[216:219], v[202:205], v[6:9]
	v_mfma_f32_16x16x32_bf16 v[2:5], v[234:237], v[202:205], v[2:5]
	v_mfma_f32_16x16x32_bf16 v[54:57], v[230:233], v[150:153], v[54:57]
	v_mfma_f32_16x16x32_bf16 v[50:53], v[238:241], v[150:153], v[50:53]
	v_mfma_f32_16x16x32_bf16 v[38:41], v[230:233], v[186:189], v[38:41]
	v_mfma_f32_16x16x32_bf16 v[34:37], v[238:241], v[186:189], v[34:37]
	v_mfma_f32_16x16x32_bf16 v[22:25], v[230:233], v[198:201], v[22:25]
	v_mfma_f32_16x16x32_bf16 v[18:21], v[238:241], v[198:201], v[18:21]
	v_mfma_f32_16x16x32_bf16 v[6:9], v[230:233], v[206:209], v[6:9]
	v_mfma_f32_16x16x32_bf16 v[2:5], v[238:241], v[206:209], v[2:5]
	s_setprio 1
	s_barrier
	s_add_i32 s1, 0, 0x18000
	v_add_u32_e32 v142, s1, v195
	ds_read_b128 v[130:133], v142
	ds_read_b128 v[134:137], v142 offset:1024
	ds_read_b128 v[138:141], v142 offset:2048
	ds_read_b128 v[142:145], v142 offset:3072
	s_add_u32 s22, s56, 0x40000
	s_addc_u32 s23, s57, 0
	s_mov_b32 m0, s61
	v_lshl_add_u64 v[216:217], s[22:23], 0, v[158:159]
	ds_read_b128 v[146:149], v197 offset:32768
	ds_read_b128 v[150:153], v197 offset:33792
	ds_read_b128 v[182:185], v197 offset:34816
	ds_read_b128 v[186:189], v197 offset:35840
	ds_read_b128 v[190:193], v197 offset:36864
	ds_read_b128 v[198:201], v197 offset:37888
	ds_read_b128 v[202:205], v197 offset:38912
	ds_read_b128 v[206:209], v197 offset:39936
	global_load_lds_dwordx4 v[216:217], off
	v_lshl_add_u64 v[216:217], s[22:23], 0, v[156:157]
	s_mov_b32 m0, s62
	s_nop 0
	global_load_lds_dwordx4 v[216:217], off
	s_add_i32 s33, 0, 0x1c000
	v_add_u32_e32 v168, s33, v195
	ds_read_b128 v[216:219], v168
	ds_read_b128 v[230:233], v168 offset:1024
	ds_read_b128 v[234:237], v168 offset:2048
	ds_read_b128 v[238:241], v168 offset:3072
	s_waitcnt vmcnt(8)
	s_waitcnt lgkmcnt(0)
	s_barrier
	s_setprio 0
	v_mfma_f32_16x16x32_bf16 v[126:129], v[130:133], v[146:149], v[126:129]
	v_mfma_f32_16x16x32_bf16 v[122:125], v[138:141], v[146:149], v[122:125]
	v_mfma_f32_16x16x32_bf16 v[110:113], v[130:133], v[182:185], v[110:113]
	v_mfma_f32_16x16x32_bf16 v[106:109], v[138:141], v[182:185], v[106:109]
	v_mfma_f32_16x16x32_bf16 v[94:97], v[130:133], v[190:193], v[94:97]
	v_mfma_f32_16x16x32_bf16 v[90:93], v[138:141], v[190:193], v[90:93]
	v_mfma_f32_16x16x32_bf16 v[78:81], v[130:133], v[202:205], v[78:81]
	v_mfma_f32_16x16x32_bf16 v[74:77], v[138:141], v[202:205], v[74:77]
	v_mfma_f32_16x16x32_bf16 v[126:129], v[134:137], v[150:153], v[126:129]
	v_mfma_f32_16x16x32_bf16 v[122:125], v[142:145], v[150:153], v[122:125]
	v_mfma_f32_16x16x32_bf16 v[110:113], v[134:137], v[186:189], v[110:113]
	v_mfma_f32_16x16x32_bf16 v[106:109], v[142:145], v[186:189], v[106:109]
	v_mfma_f32_16x16x32_bf16 v[94:97], v[134:137], v[198:201], v[94:97]
	v_mfma_f32_16x16x32_bf16 v[90:93], v[142:145], v[198:201], v[90:93]
	v_mfma_f32_16x16x32_bf16 v[78:81], v[134:137], v[206:209], v[78:81]
	v_mfma_f32_16x16x32_bf16 v[74:77], v[142:145], v[206:209], v[74:77]
	v_mfma_f32_16x16x32_bf16 v[118:121], v[216:219], v[146:149], v[118:121]
	v_mfma_f32_16x16x32_bf16 v[114:117], v[234:237], v[146:149], v[114:117]
	v_mfma_f32_16x16x32_bf16 v[102:105], v[216:219], v[182:185], v[102:105]
	v_mfma_f32_16x16x32_bf16 v[98:101], v[234:237], v[182:185], v[98:101]
	v_mfma_f32_16x16x32_bf16 v[86:89], v[216:219], v[190:193], v[86:89]
	v_mfma_f32_16x16x32_bf16 v[82:85], v[234:237], v[190:193], v[82:85]
	v_mfma_f32_16x16x32_bf16 v[70:73], v[216:219], v[202:205], v[70:73]
	v_mfma_f32_16x16x32_bf16 v[66:69], v[234:237], v[202:205], v[66:69]
	v_mfma_f32_16x16x32_bf16 v[118:121], v[230:233], v[150:153], v[118:121]
	v_mfma_f32_16x16x32_bf16 v[114:117], v[238:241], v[150:153], v[114:117]
	v_mfma_f32_16x16x32_bf16 v[102:105], v[230:233], v[186:189], v[102:105]
	v_mfma_f32_16x16x32_bf16 v[98:101], v[238:241], v[186:189], v[98:101]
	v_mfma_f32_16x16x32_bf16 v[86:89], v[230:233], v[198:201], v[86:89]
	v_mfma_f32_16x16x32_bf16 v[82:85], v[238:241], v[198:201], v[82:85]
	v_mfma_f32_16x16x32_bf16 v[70:73], v[230:233], v[206:209], v[70:73]
	v_mfma_f32_16x16x32_bf16 v[66:69], v[238:241], v[206:209], v[66:69]
	s_setprio 1
	s_barrier
	ds_read_b128 v[146:149], v197 offset:49152
	ds_read_b128 v[150:153], v197 offset:50176
	ds_read_b128 v[182:185], v197 offset:51200
	ds_read_b128 v[186:189], v197 offset:52224
	ds_read_b128 v[190:193], v197 offset:53248
	ds_read_b128 v[198:201], v197 offset:54272
	ds_read_b128 v[202:205], v197 offset:55296
	ds_read_b128 v[206:209], v197 offset:56320
	s_add_i32 s1, s1, s58
	v_lshl_add_u64 v[176:177], v[176:177], 0, s[12:13]
	s_mov_b32 m0, s1
	s_nop 0
	global_load_lds_dwordx4 v[176:177], off
	v_lshl_add_u64 v[176:177], v[220:221], 0, s[12:13]
	s_add_i32 m0, s1, 0x2000
	s_nop 0
	global_load_lds_dwordx4 v[176:177], off
	s_mov_b32 m0, s64
	v_lshl_add_u64 v[176:177], v[242:243], 0, s[12:13]
	global_load_lds_dwordx4 v[176:177], off
	v_lshl_add_u64 v[176:177], v[244:245], 0, s[12:13]
	s_mov_b32 m0, s65
	s_nop 0
	global_load_lds_dwordx4 v[176:177], off
	s_add_u32 s22, s30, 0x40080
	s_addc_u32 s23, s31, 0
	s_add_i32 s1, s33, s58
	s_mov_b32 m0, s1
	s_nop 0
	global_load_lds_dwordx4 v0, s[22:23]
	s_add_i32 m0, s1, 0x2000
	s_nop 0
	global_load_lds_dwordx4 v154, s[22:23]
	s_waitcnt vmcnt(8)
	s_waitcnt lgkmcnt(0)
	s_barrier
	s_setprio 0
	v_mfma_f32_16x16x32_bf16 v[62:65], v[130:133], v[146:149], v[62:65]
	v_mfma_f32_16x16x32_bf16 v[58:61], v[138:141], v[146:149], v[58:61]
	v_mfma_f32_16x16x32_bf16 v[46:49], v[130:133], v[182:185], v[46:49]
	v_mfma_f32_16x16x32_bf16 v[42:45], v[138:141], v[182:185], v[42:45]
	v_mfma_f32_16x16x32_bf16 v[30:33], v[130:133], v[190:193], v[30:33]
	v_mfma_f32_16x16x32_bf16 v[26:29], v[138:141], v[190:193], v[26:29]
	v_mfma_f32_16x16x32_bf16 v[14:17], v[130:133], v[202:205], v[14:17]
	v_mfma_f32_16x16x32_bf16 v[10:13], v[138:141], v[202:205], v[10:13]
	v_mfma_f32_16x16x32_bf16 v[62:65], v[134:137], v[150:153], v[62:65]
	v_mfma_f32_16x16x32_bf16 v[58:61], v[142:145], v[150:153], v[58:61]
	v_mfma_f32_16x16x32_bf16 v[46:49], v[134:137], v[186:189], v[46:49]
	v_mfma_f32_16x16x32_bf16 v[42:45], v[142:145], v[186:189], v[42:45]
	v_mfma_f32_16x16x32_bf16 v[30:33], v[134:137], v[198:201], v[30:33]
	v_mfma_f32_16x16x32_bf16 v[26:29], v[142:145], v[198:201], v[26:29]
	v_mfma_f32_16x16x32_bf16 v[14:17], v[134:137], v[206:209], v[14:17]
	v_mfma_f32_16x16x32_bf16 v[10:13], v[142:145], v[206:209], v[10:13]
	v_mfma_f32_16x16x32_bf16 v[54:57], v[216:219], v[146:149], v[54:57]
	v_mfma_f32_16x16x32_bf16 v[50:53], v[234:237], v[146:149], v[50:53]
	v_mfma_f32_16x16x32_bf16 v[38:41], v[216:219], v[182:185], v[38:41]
	v_mfma_f32_16x16x32_bf16 v[34:37], v[234:237], v[182:185], v[34:37]
	v_mfma_f32_16x16x32_bf16 v[22:25], v[216:219], v[190:193], v[22:25]
	v_mfma_f32_16x16x32_bf16 v[18:21], v[234:237], v[190:193], v[18:21]
	v_mfma_f32_16x16x32_bf16 v[6:9], v[216:219], v[202:205], v[6:9]
	v_mfma_f32_16x16x32_bf16 v[2:5], v[234:237], v[202:205], v[2:5]
	v_mfma_f32_16x16x32_bf16 v[54:57], v[230:233], v[150:153], v[54:57]
	v_mfma_f32_16x16x32_bf16 v[50:53], v[238:241], v[150:153], v[50:53]
	v_mfma_f32_16x16x32_bf16 v[38:41], v[230:233], v[186:189], v[38:41]
	v_mfma_f32_16x16x32_bf16 v[34:37], v[238:241], v[186:189], v[34:37]
	v_mfma_f32_16x16x32_bf16 v[22:25], v[230:233], v[198:201], v[22:25]
	v_mfma_f32_16x16x32_bf16 v[18:21], v[238:241], v[198:201], v[18:21]
	v_mfma_f32_16x16x32_bf16 v[6:9], v[230:233], v[206:209], v[6:9]
	v_mfma_f32_16x16x32_bf16 v[2:5], v[238:241], v[206:209], v[2:5]
	s_setprio 1
	s_add_i32 s69, s69, 2
	s_add_u32 s28, s28, 0x100
	s_addc_u32 s29, s29, 0
	s_add_u32 s67, s67, 0x100
	s_addc_u32 s68, s68, 0
	s_cmp_gt_u32 s69, 13
	s_barrier
	s_cbranch_scc0 .LBB0_47
	s_cmpk_gt_u32 s0, 0xff
	s_cbranch_scc1 .Lrs_i1_post
	s_barrier

.Lrs_i2_pre:
	s_add_u32 s1, s28, 0xfffc0080
	s_addc_u32 s22, s29, -1
	s_add_i32 s23, 0, 0x10000
	v_add_u32_e32 v142, s23, v201
	ds_read_b128 v[130:133], v142
	ds_read_b128 v[134:137], v142 offset:1024
	ds_read_b128 v[138:141], v142 offset:2048
	ds_read_b128 v[142:145], v142 offset:3072
	s_cmp_eq_u32 s60, 12
	s_cselect_b32 s43, s27, s22
	s_cselect_b32 s42, s56, s1
	s_cselect_b32 s31, s7, s59
	s_cselect_b32 s30, s57, s58
	v_lshl_add_u64 v[176:177], s[28:29], 0, v[178:179]
	s_add_i32 m0, s46, 0xc000
	ds_read_b128 v[146:149], v205
	ds_read_b128 v[150:153], v205 offset:1024
	ds_read_b128 v[182:185], v205 offset:2048
	ds_read_b128 v[186:189], v205 offset:3072
	ds_read_b128 v[190:193], v205 offset:4096
	ds_read_b128 v[194:197], v205 offset:5120
	ds_read_b128 v[206:209], v205 offset:6144
	ds_read_b128 v[216:219], v205 offset:7168
	global_load_lds_dwordx4 v[176:177], off
	v_lshl_add_u64 v[176:177], s[28:29], 0, v[180:181]
	s_add_i32 m0, s46, 0xe000
	s_nop 0
	global_load_lds_dwordx4 v[176:177], off
	s_add_i32 s1, 0, 0x14000
	v_add_u32_e32 v168, s1, v201
	ds_read_b128 v[230:233], v168
	ds_read_b128 v[234:237], v168 offset:1024
	ds_read_b128 v[238:241], v168 offset:2048
	ds_read_b128 v[242:245], v168 offset:3072
	s_waitcnt vmcnt(8)
	s_waitcnt lgkmcnt(0)
	s_barrier
	s_setprio 0
	v_mfma_f32_16x16x32_bf16 v[126:129], v[130:133], v[146:149], 0
	v_mfma_f32_16x16x32_bf16 v[118:121], v[138:141], v[146:149], 0
	v_mfma_f32_16x16x32_bf16 v[110:113], v[130:133], v[182:185], 0
	v_mfma_f32_16x16x32_bf16 v[102:105], v[138:141], v[182:185], 0
	v_mfma_f32_16x16x32_bf16 v[94:97], v[130:133], v[190:193], 0
	v_mfma_f32_16x16x32_bf16 v[86:89], v[138:141], v[190:193], 0
	v_mfma_f32_16x16x32_bf16 v[78:81], v[130:133], v[206:209], 0
	v_mfma_f32_16x16x32_bf16 v[70:73], v[138:141], v[206:209], 0
	v_mfma_f32_16x16x32_bf16 v[126:129], v[134:137], v[150:153], v[126:129]
	v_mfma_f32_16x16x32_bf16 v[118:121], v[142:145], v[150:153], v[118:121]
	v_mfma_f32_16x16x32_bf16 v[110:113], v[134:137], v[186:189], v[110:113]
	v_mfma_f32_16x16x32_bf16 v[102:105], v[142:145], v[186:189], v[102:105]
	v_mfma_f32_16x16x32_bf16 v[94:97], v[134:137], v[194:197], v[94:97]
	v_mfma_f32_16x16x32_bf16 v[86:89], v[142:145], v[194:197], v[86:89]
	v_mfma_f32_16x16x32_bf16 v[78:81], v[134:137], v[216:219], v[78:81]
	v_mfma_f32_16x16x32_bf16 v[70:73], v[142:145], v[216:219], v[70:73]
	v_mfma_f32_16x16x32_bf16 v[122:125], v[230:233], v[146:149], 0
	v_mfma_f32_16x16x32_bf16 v[114:117], v[238:241], v[146:149], 0
	v_mfma_f32_16x16x32_bf16 v[106:109], v[230:233], v[182:185], 0
	v_mfma_f32_16x16x32_bf16 v[98:101], v[238:241], v[182:185], 0
	v_mfma_f32_16x16x32_bf16 v[90:93], v[230:233], v[190:193], 0
	v_mfma_f32_16x16x32_bf16 v[82:85], v[238:241], v[190:193], 0
	v_mfma_f32_16x16x32_bf16 v[74:77], v[230:233], v[206:209], 0
	v_mfma_f32_16x16x32_bf16 v[66:69], v[238:241], v[206:209], 0
	v_mfma_f32_16x16x32_bf16 v[122:125], v[234:237], v[150:153], v[122:125]
	v_mfma_f32_16x16x32_bf16 v[114:117], v[242:245], v[150:153], v[114:117]
	v_mfma_f32_16x16x32_bf16 v[106:109], v[234:237], v[186:189], v[106:109]
	v_mfma_f32_16x16x32_bf16 v[98:101], v[242:245], v[186:189], v[98:101]
	v_mfma_f32_16x16x32_bf16 v[90:93], v[234:237], v[194:197], v[90:93]
	v_mfma_f32_16x16x32_bf16 v[82:85], v[242:245], v[194:197], v[82:85]
	v_mfma_f32_16x16x32_bf16 v[74:77], v[234:237], v[216:219], v[74:77]
	v_mfma_f32_16x16x32_bf16 v[66:69], v[242:245], v[216:219], v[66:69]
	s_setprio 1
	s_barrier
	ds_read_b128 v[146:149], v205 offset:16384
	ds_read_b128 v[150:153], v205 offset:17408
	ds_read_b128 v[182:185], v205 offset:18432
	ds_read_b128 v[186:189], v205 offset:19456
	ds_read_b128 v[190:193], v205 offset:20480
	ds_read_b128 v[194:197], v205 offset:21504
	ds_read_b128 v[206:209], v205 offset:22528
	ds_read_b128 v[216:219], v205 offset:23552
	s_add_i32 s22, s23, s17
	v_lshl_add_u64 v[176:177], s[30:31], 0, v[0:1]
	s_mov_b32 m0, s22
	s_nop 0
	global_load_lds_dwordx4 v[176:177], off
	v_lshl_add_u64 v[202:203], s[30:31], 0, v[154:155]
	s_add_i32 m0, s22, 0x2000
	s_nop 0
	global_load_lds_dwordx4 v[202:203], off
	s_mov_b32 m0, s46
	v_lshl_add_u64 v[220:221], s[42:43], 0, v[158:159]
	global_load_lds_dwordx4 v[220:221], off
	v_lshl_add_u64 v[246:247], s[42:43], 0, v[156:157]
	s_mov_b32 m0, s47
	s_nop 0
	global_load_lds_dwordx4 v[246:247], off
	s_add_u32 s22, s30, 0x40000
	s_addc_u32 s23, s31, 0
	s_add_i32 s1, s1, s17
	s_mov_b32 m0, s1
	s_nop 0
	global_load_lds_dwordx4 v0, s[22:23]
	s_add_i32 m0, s1, 0x2000
	s_nop 0
	global_load_lds_dwordx4 v154, s[22:23]
	s_waitcnt vmcnt(8)
	s_waitcnt lgkmcnt(0)
	s_barrier
	s_setprio 0
	v_mfma_f32_16x16x32_bf16 v[62:65], v[130:133], v[146:149], 0
	v_mfma_f32_16x16x32_bf16 v[54:57], v[138:141], v[146:149], 0
	v_mfma_f32_16x16x32_bf16 v[46:49], v[130:133], v[182:185], 0
	v_mfma_f32_16x16x32_bf16 v[38:41], v[138:141], v[182:185], 0
	v_mfma_f32_16x16x32_bf16 v[30:33], v[130:133], v[190:193], 0
	v_mfma_f32_16x16x32_bf16 v[22:25], v[138:141], v[190:193], 0
	v_mfma_f32_16x16x32_bf16 v[14:17], v[130:133], v[206:209], 0
	v_mfma_f32_16x16x32_bf16 v[6:9], v[138:141], v[206:209], 0
	v_mfma_f32_16x16x32_bf16 v[62:65], v[134:137], v[150:153], v[62:65]
	v_mfma_f32_16x16x32_bf16 v[54:57], v[142:145], v[150:153], v[54:57]
	v_mfma_f32_16x16x32_bf16 v[46:49], v[134:137], v[186:189], v[46:49]
	v_mfma_f32_16x16x32_bf16 v[38:41], v[142:145], v[186:189], v[38:41]
	v_mfma_f32_16x16x32_bf16 v[30:33], v[134:137], v[194:197], v[30:33]
	v_mfma_f32_16x16x32_bf16 v[22:25], v[142:145], v[194:197], v[22:25]
	v_mfma_f32_16x16x32_bf16 v[14:17], v[134:137], v[216:219], v[14:17]
	v_mfma_f32_16x16x32_bf16 v[6:9], v[142:145], v[216:219], v[6:9]
	v_mfma_f32_16x16x32_bf16 v[58:61], v[230:233], v[146:149], 0
	v_mfma_f32_16x16x32_bf16 v[50:53], v[238:241], v[146:149], 0
	v_mfma_f32_16x16x32_bf16 v[42:45], v[230:233], v[182:185], 0
	v_mfma_f32_16x16x32_bf16 v[34:37], v[238:241], v[182:185], 0
	v_mfma_f32_16x16x32_bf16 v[26:29], v[230:233], v[190:193], 0
	v_mfma_f32_16x16x32_bf16 v[18:21], v[238:241], v[190:193], 0
	v_mfma_f32_16x16x32_bf16 v[10:13], v[230:233], v[206:209], 0
	v_mfma_f32_16x16x32_bf16 v[2:5], v[238:241], v[206:209], 0
	v_mfma_f32_16x16x32_bf16 v[58:61], v[234:237], v[150:153], v[58:61]
	v_mfma_f32_16x16x32_bf16 v[50:53], v[242:245], v[150:153], v[50:53]
	v_mfma_f32_16x16x32_bf16 v[42:45], v[234:237], v[186:189], v[42:45]
	v_mfma_f32_16x16x32_bf16 v[34:37], v[242:245], v[186:189], v[34:37]
	v_mfma_f32_16x16x32_bf16 v[26:29], v[234:237], v[194:197], v[26:29]
	v_mfma_f32_16x16x32_bf16 v[18:21], v[242:245], v[194:197], v[18:21]
	v_mfma_f32_16x16x32_bf16 v[10:13], v[234:237], v[216:219], v[10:13]
	v_mfma_f32_16x16x32_bf16 v[2:5], v[242:245], v[216:219], v[2:5]
	s_setprio 1
	s_barrier
	s_add_i32 s1, 0, 0x18000
	v_add_u32_e32 v142, s1, v201
	ds_read_b128 v[130:133], v142
	ds_read_b128 v[134:137], v142 offset:1024
	ds_read_b128 v[138:141], v142 offset:2048
	ds_read_b128 v[142:145], v142 offset:3072
	s_add_u32 s22, s42, 0x40000
	s_addc_u32 s23, s43, 0
	s_mov_b32 m0, s48
	v_lshl_add_u64 v[230:231], s[22:23], 0, v[158:159]
	ds_read_b128 v[146:149], v205 offset:32768
	ds_read_b128 v[150:153], v205 offset:33792
	ds_read_b128 v[182:185], v205 offset:34816
	ds_read_b128 v[186:189], v205 offset:35840
	ds_read_b128 v[190:193], v205 offset:36864
	ds_read_b128 v[194:197], v205 offset:37888
	ds_read_b128 v[206:209], v205 offset:38912
	ds_read_b128 v[216:219], v205 offset:39936
	global_load_lds_dwordx4 v[230:231], off
	v_lshl_add_u64 v[230:231], s[22:23], 0, v[156:157]
	s_mov_b32 m0, s49
	s_nop 0
	global_load_lds_dwordx4 v[230:231], off
	s_add_i32 s33, 0, 0x1c000
	v_add_u32_e32 v168, s33, v201
	ds_read_b128 v[230:233], v168
	ds_read_b128 v[234:237], v168 offset:1024
	ds_read_b128 v[238:241], v168 offset:2048
	ds_read_b128 v[242:245], v168 offset:3072
	s_waitcnt vmcnt(8)
	s_waitcnt lgkmcnt(0)
	s_barrier
	s_setprio 0
	v_mfma_f32_16x16x32_bf16 v[126:129], v[130:133], v[146:149], v[126:129]
	v_mfma_f32_16x16x32_bf16 v[118:121], v[138:141], v[146:149], v[118:121]
	v_mfma_f32_16x16x32_bf16 v[110:113], v[130:133], v[182:185], v[110:113]
	v_mfma_f32_16x16x32_bf16 v[102:105], v[138:141], v[182:185], v[102:105]
	v_mfma_f32_16x16x32_bf16 v[94:97], v[130:133], v[190:193], v[94:97]
	v_mfma_f32_16x16x32_bf16 v[86:89], v[138:141], v[190:193], v[86:89]
	v_mfma_f32_16x16x32_bf16 v[78:81], v[130:133], v[206:209], v[78:81]
	v_mfma_f32_16x16x32_bf16 v[70:73], v[138:141], v[206:209], v[70:73]
	v_mfma_f32_16x16x32_bf16 v[126:129], v[134:137], v[150:153], v[126:129]
	v_mfma_f32_16x16x32_bf16 v[118:121], v[142:145], v[150:153], v[118:121]
	v_mfma_f32_16x16x32_bf16 v[110:113], v[134:137], v[186:189], v[110:113]
	v_mfma_f32_16x16x32_bf16 v[102:105], v[142:145], v[186:189], v[102:105]
	v_mfma_f32_16x16x32_bf16 v[94:97], v[134:137], v[194:197], v[94:97]
	v_mfma_f32_16x16x32_bf16 v[86:89], v[142:145], v[194:197], v[86:89]
	v_mfma_f32_16x16x32_bf16 v[78:81], v[134:137], v[216:219], v[78:81]
	v_mfma_f32_16x16x32_bf16 v[70:73], v[142:145], v[216:219], v[70:73]
	v_mfma_f32_16x16x32_bf16 v[122:125], v[230:233], v[146:149], v[122:125]
	v_mfma_f32_16x16x32_bf16 v[114:117], v[238:241], v[146:149], v[114:117]
	v_mfma_f32_16x16x32_bf16 v[106:109], v[230:233], v[182:185], v[106:109]
	v_mfma_f32_16x16x32_bf16 v[98:101], v[238:241], v[182:185], v[98:101]
	v_mfma_f32_16x16x32_bf16 v[90:93], v[230:233], v[190:193], v[90:93]
	v_mfma_f32_16x16x32_bf16 v[82:85], v[238:241], v[190:193], v[82:85]
	v_mfma_f32_16x16x32_bf16 v[74:77], v[230:233], v[206:209], v[74:77]
	v_mfma_f32_16x16x32_bf16 v[66:69], v[238:241], v[206:209], v[66:69]
	v_mfma_f32_16x16x32_bf16 v[122:125], v[234:237], v[150:153], v[122:125]
	v_mfma_f32_16x16x32_bf16 v[114:117], v[242:245], v[150:153], v[114:117]
	v_mfma_f32_16x16x32_bf16 v[106:109], v[234:237], v[186:189], v[106:109]
	v_mfma_f32_16x16x32_bf16 v[98:101], v[242:245], v[186:189], v[98:101]
	v_mfma_f32_16x16x32_bf16 v[90:93], v[234:237], v[194:197], v[90:93]
	v_mfma_f32_16x16x32_bf16 v[82:85], v[242:245], v[194:197], v[82:85]
	v_mfma_f32_16x16x32_bf16 v[74:77], v[234:237], v[216:219], v[74:77]
	v_mfma_f32_16x16x32_bf16 v[66:69], v[242:245], v[216:219], v[66:69]
	s_setprio 1
	s_barrier
	ds_read_b128 v[146:149], v205 offset:49152
	ds_read_b128 v[150:153], v205 offset:50176
	ds_read_b128 v[182:185], v205 offset:51200
	ds_read_b128 v[186:189], v205 offset:52224
	ds_read_b128 v[190:193], v205 offset:53248
	ds_read_b128 v[194:197], v205 offset:54272
	ds_read_b128 v[206:209], v205 offset:55296
	ds_read_b128 v[216:219], v205 offset:56320
	s_add_i32 s1, s1, s17
	v_lshl_add_u64 v[176:177], v[176:177], 0, s[12:13]
	s_mov_b32 m0, s1
	s_nop 0
	global_load_lds_dwordx4 v[176:177], off
	v_lshl_add_u64 v[176:177], v[202:203], 0, s[12:13]
	s_add_i32 m0, s1, 0x2000
	s_nop 0
	global_load_lds_dwordx4 v[176:177], off
	s_mov_b32 m0, s20
	v_lshl_add_u64 v[176:177], v[220:221], 0, s[12:13]
	global_load_lds_dwordx4 v[176:177], off
	v_lshl_add_u64 v[176:177], v[246:247], 0, s[12:13]
	s_mov_b32 m0, s21
	s_nop 0
	global_load_lds_dwordx4 v[176:177], off
	s_add_u32 s22, s30, 0x40080
	s_addc_u32 s23, s31, 0
	s_add_i32 s1, s33, s17
	s_mov_b32 m0, s1
	s_nop 0
	global_load_lds_dwordx4 v0, s[22:23]
	s_add_i32 m0, s1, 0x2000
	s_nop 0
	global_load_lds_dwordx4 v154, s[22:23]
	s_waitcnt vmcnt(8)
	s_waitcnt lgkmcnt(0)
	s_barrier
	s_setprio 0
	v_mfma_f32_16x16x32_bf16 v[62:65], v[130:133], v[146:149], v[62:65]
	v_mfma_f32_16x16x32_bf16 v[54:57], v[138:141], v[146:149], v[54:57]
	v_mfma_f32_16x16x32_bf16 v[46:49], v[130:133], v[182:185], v[46:49]
	v_mfma_f32_16x16x32_bf16 v[38:41], v[138:141], v[182:185], v[38:41]
	v_mfma_f32_16x16x32_bf16 v[30:33], v[130:133], v[190:193], v[30:33]
	v_mfma_f32_16x16x32_bf16 v[22:25], v[138:141], v[190:193], v[22:25]
	v_mfma_f32_16x16x32_bf16 v[14:17], v[130:133], v[206:209], v[14:17]
	v_mfma_f32_16x16x32_bf16 v[6:9], v[138:141], v[206:209], v[6:9]
	v_mfma_f32_16x16x32_bf16 v[62:65], v[134:137], v[150:153], v[62:65]
	v_mfma_f32_16x16x32_bf16 v[54:57], v[142:145], v[150:153], v[54:57]
	v_mfma_f32_16x16x32_bf16 v[46:49], v[134:137], v[186:189], v[46:49]
	v_mfma_f32_16x16x32_bf16 v[38:41], v[142:145], v[186:189], v[38:41]
	v_mfma_f32_16x16x32_bf16 v[30:33], v[134:137], v[194:197], v[30:33]
	v_mfma_f32_16x16x32_bf16 v[22:25], v[142:145], v[194:197], v[22:25]
	v_mfma_f32_16x16x32_bf16 v[14:17], v[134:137], v[216:219], v[14:17]
	v_mfma_f32_16x16x32_bf16 v[6:9], v[142:145], v[216:219], v[6:9]
	v_mfma_f32_16x16x32_bf16 v[58:61], v[230:233], v[146:149], v[58:61]
	v_mfma_f32_16x16x32_bf16 v[50:53], v[238:241], v[146:149], v[50:53]
	v_mfma_f32_16x16x32_bf16 v[42:45], v[230:233], v[182:185], v[42:45]
	v_mfma_f32_16x16x32_bf16 v[34:37], v[238:241], v[182:185], v[34:37]
	v_mfma_f32_16x16x32_bf16 v[26:29], v[230:233], v[190:193], v[26:29]
	v_mfma_f32_16x16x32_bf16 v[18:21], v[238:241], v[190:193], v[18:21]
	v_mfma_f32_16x16x32_bf16 v[10:13], v[230:233], v[206:209], v[10:13]
	v_mfma_f32_16x16x32_bf16 v[2:5], v[238:241], v[206:209], v[2:5]
	v_mfma_f32_16x16x32_bf16 v[58:61], v[234:237], v[150:153], v[58:61]
	v_mfma_f32_16x16x32_bf16 v[50:53], v[242:245], v[150:153], v[50:53]
	v_mfma_f32_16x16x32_bf16 v[42:45], v[234:237], v[186:189], v[42:45]
	v_mfma_f32_16x16x32_bf16 v[34:37], v[242:245], v[186:189], v[34:37]
	v_mfma_f32_16x16x32_bf16 v[26:29], v[234:237], v[194:197], v[26:29]
	v_mfma_f32_16x16x32_bf16 v[18:21], v[242:245], v[194:197], v[18:21]
	v_mfma_f32_16x16x32_bf16 v[10:13], v[234:237], v[216:219], v[10:13]
	v_mfma_f32_16x16x32_bf16 v[2:5], v[242:245], v[216:219], v[2:5]
	s_setprio 1
	s_add_i32 s60, s60, 2
	s_add_u32 s28, s28, 0x100
	s_addc_u32 s29, s29, 0
	s_add_u32 s58, s58, 0x100
	s_addc_u32 s59, s59, 0
	s_cmp_gt_u32 s60, 13
	s_barrier
.LBB0_83:
	s_add_u32 s1, s28, 0xfffc0080
	s_addc_u32 s22, s29, -1
	s_add_i32 s23, 0, 0x10000
	v_add_u32_e32 v142, s23, v201
	ds_read_b128 v[130:133], v142
	ds_read_b128 v[134:137], v142 offset:1024
	ds_read_b128 v[138:141], v142 offset:2048
	ds_read_b128 v[142:145], v142 offset:3072
	s_cmp_eq_u32 s60, 12
	s_cselect_b32 s43, s27, s22
	s_cselect_b32 s42, s56, s1
	s_cselect_b32 s31, s7, s59
	s_cselect_b32 s30, s57, s58
	v_lshl_add_u64 v[176:177], s[28:29], 0, v[178:179]
	s_add_i32 m0, s46, 0xc000
	ds_read_b128 v[146:149], v205
	ds_read_b128 v[150:153], v205 offset:1024
	ds_read_b128 v[182:185], v205 offset:2048
	ds_read_b128 v[186:189], v205 offset:3072
	ds_read_b128 v[190:193], v205 offset:4096
	ds_read_b128 v[194:197], v205 offset:5120
	ds_read_b128 v[206:209], v205 offset:6144
	ds_read_b128 v[216:219], v205 offset:7168
	global_load_lds_dwordx4 v[176:177], off
	v_lshl_add_u64 v[176:177], s[28:29], 0, v[180:181]
	s_add_i32 m0, s46, 0xe000
	s_nop 0
	global_load_lds_dwordx4 v[176:177], off
	s_add_i32 s1, 0, 0x14000
	v_add_u32_e32 v168, s1, v201
	ds_read_b128 v[230:233], v168
	ds_read_b128 v[234:237], v168 offset:1024
	ds_read_b128 v[238:241], v168 offset:2048
	ds_read_b128 v[242:245], v168 offset:3072
	s_waitcnt vmcnt(8)
	s_waitcnt lgkmcnt(0)
	s_barrier
	s_setprio 0
	v_mfma_f32_16x16x32_bf16 v[126:129], v[130:133], v[146:149], v[126:129]
	v_mfma_f32_16x16x32_bf16 v[118:121], v[138:141], v[146:149], v[118:121]
	v_mfma_f32_16x16x32_bf16 v[110:113], v[130:133], v[182:185], v[110:113]
	v_mfma_f32_16x16x32_bf16 v[102:105], v[138:141], v[182:185], v[102:105]
	v_mfma_f32_16x16x32_bf16 v[94:97], v[130:133], v[190:193], v[94:97]
	v_mfma_f32_16x16x32_bf16 v[86:89], v[138:141], v[190:193], v[86:89]
	v_mfma_f32_16x16x32_bf16 v[78:81], v[130:133], v[206:209], v[78:81]
	v_mfma_f32_16x16x32_bf16 v[70:73], v[138:141], v[206:209], v[70:73]
	v_mfma_f32_16x16x32_bf16 v[126:129], v[134:137], v[150:153], v[126:129]
	v_mfma_f32_16x16x32_bf16 v[118:121], v[142:145], v[150:153], v[118:121]
	v_mfma_f32_16x16x32_bf16 v[110:113], v[134:137], v[186:189], v[110:113]
	v_mfma_f32_16x16x32_bf16 v[102:105], v[142:145], v[186:189], v[102:105]
	v_mfma_f32_16x16x32_bf16 v[94:97], v[134:137], v[194:197], v[94:97]
	v_mfma_f32_16x16x32_bf16 v[86:89], v[142:145], v[194:197], v[86:89]
	v_mfma_f32_16x16x32_bf16 v[78:81], v[134:137], v[216:219], v[78:81]
	v_mfma_f32_16x16x32_bf16 v[70:73], v[142:145], v[216:219], v[70:73]
	v_mfma_f32_16x16x32_bf16 v[122:125], v[230:233], v[146:149], v[122:125]
	v_mfma_f32_16x16x32_bf16 v[114:117], v[238:241], v[146:149], v[114:117]
	v_mfma_f32_16x16x32_bf16 v[106:109], v[230:233], v[182:185], v[106:109]
	v_mfma_f32_16x16x32_bf16 v[98:101], v[238:241], v[182:185], v[98:101]
	v_mfma_f32_16x16x32_bf16 v[90:93], v[230:233], v[190:193], v[90:93]
	v_mfma_f32_16x16x32_bf16 v[82:85], v[238:241], v[190:193], v[82:85]
	v_mfma_f32_16x16x32_bf16 v[74:77], v[230:233], v[206:209], v[74:77]
	v_mfma_f32_16x16x32_bf16 v[66:69], v[238:241], v[206:209], v[66:69]
	v_mfma_f32_16x16x32_bf16 v[122:125], v[234:237], v[150:153], v[122:125]
	v_mfma_f32_16x16x32_bf16 v[114:117], v[242:245], v[150:153], v[114:117]
	v_mfma_f32_16x16x32_bf16 v[106:109], v[234:237], v[186:189], v[106:109]
	v_mfma_f32_16x16x32_bf16 v[98:101], v[242:245], v[186:189], v[98:101]
	v_mfma_f32_16x16x32_bf16 v[90:93], v[234:237], v[194:197], v[90:93]
	v_mfma_f32_16x16x32_bf16 v[82:85], v[242:245], v[194:197], v[82:85]
	v_mfma_f32_16x16x32_bf16 v[74:77], v[234:237], v[216:219], v[74:77]
	v_mfma_f32_16x16x32_bf16 v[66:69], v[242:245], v[216:219], v[66:69]
	s_setprio 1
	s_barrier
	ds_read_b128 v[146:149], v205 offset:16384
	ds_read_b128 v[150:153], v205 offset:17408
	ds_read_b128 v[182:185], v205 offset:18432
	ds_read_b128 v[186:189], v205 offset:19456
	ds_read_b128 v[190:193], v205 offset:20480
	ds_read_b128 v[194:197], v205 offset:21504
	ds_read_b128 v[206:209], v205 offset:22528
	ds_read_b128 v[216:219], v205 offset:23552
	s_add_i32 s22, s23, s17
	v_lshl_add_u64 v[176:177], s[30:31], 0, v[0:1]
	s_mov_b32 m0, s22
	s_nop 0
	global_load_lds_dwordx4 v[176:177], off
	v_lshl_add_u64 v[202:203], s[30:31], 0, v[154:155]
	s_add_i32 m0, s22, 0x2000
	s_nop 0
	global_load_lds_dwordx4 v[202:203], off
	s_mov_b32 m0, s46
	v_lshl_add_u64 v[220:221], s[42:43], 0, v[158:159]
	global_load_lds_dwordx4 v[220:221], off
	v_lshl_add_u64 v[246:247], s[42:43], 0, v[156:157]
	s_mov_b32 m0, s47
	s_nop 0
	global_load_lds_dwordx4 v[246:247], off
	s_add_u32 s22, s30, 0x40000
	s_addc_u32 s23, s31, 0
	s_add_i32 s1, s1, s17
	s_mov_b32 m0, s1
	s_nop 0
	global_load_lds_dwordx4 v0, s[22:23]
	s_add_i32 m0, s1, 0x2000
	s_nop 0
	global_load_lds_dwordx4 v154, s[22:23]
	s_waitcnt vmcnt(8)
	s_waitcnt lgkmcnt(0)
	s_barrier
	s_setprio 0
	v_mfma_f32_16x16x32_bf16 v[62:65], v[130:133], v[146:149], v[62:65]
	v_mfma_f32_16x16x32_bf16 v[54:57], v[138:141], v[146:149], v[54:57]
	v_mfma_f32_16x16x32_bf16 v[46:49], v[130:133], v[182:185], v[46:49]
	v_mfma_f32_16x16x32_bf16 v[38:41], v[138:141], v[182:185], v[38:41]
	v_mfma_f32_16x16x32_bf16 v[30:33], v[130:133], v[190:193], v[30:33]
	v_mfma_f32_16x16x32_bf16 v[22:25], v[138:141], v[190:193], v[22:25]
	v_mfma_f32_16x16x32_bf16 v[14:17], v[130:133], v[206:209], v[14:17]
	v_mfma_f32_16x16x32_bf16 v[6:9], v[138:141], v[206:209], v[6:9]
	v_mfma_f32_16x16x32_bf16 v[62:65], v[134:137], v[150:153], v[62:65]
	v_mfma_f32_16x16x32_bf16 v[54:57], v[142:145], v[150:153], v[54:57]
	v_mfma_f32_16x16x32_bf16 v[46:49], v[134:137], v[186:189], v[46:49]
	v_mfma_f32_16x16x32_bf16 v[38:41], v[142:145], v[186:189], v[38:41]
	v_mfma_f32_16x16x32_bf16 v[30:33], v[134:137], v[194:197], v[30:33]
	v_mfma_f32_16x16x32_bf16 v[22:25], v[142:145], v[194:197], v[22:25]
	v_mfma_f32_16x16x32_bf16 v[14:17], v[134:137], v[216:219], v[14:17]
	v_mfma_f32_16x16x32_bf16 v[6:9], v[142:145], v[216:219], v[6:9]
	v_mfma_f32_16x16x32_bf16 v[58:61], v[230:233], v[146:149], v[58:61]
	v_mfma_f32_16x16x32_bf16 v[50:53], v[238:241], v[146:149], v[50:53]
	v_mfma_f32_16x16x32_bf16 v[42:45], v[230:233], v[182:185], v[42:45]
	v_mfma_f32_16x16x32_bf16 v[34:37], v[238:241], v[182:185], v[34:37]
	v_mfma_f32_16x16x32_bf16 v[26:29], v[230:233], v[190:193], v[26:29]
	v_mfma_f32_16x16x32_bf16 v[18:21], v[238:241], v[190:193], v[18:21]
	v_mfma_f32_16x16x32_bf16 v[10:13], v[230:233], v[206:209], v[10:13]
	v_mfma_f32_16x16x32_bf16 v[2:5], v[238:241], v[206:209], v[2:5]
	v_mfma_f32_16x16x32_bf16 v[58:61], v[234:237], v[150:153], v[58:61]
	v_mfma_f32_16x16x32_bf16 v[50:53], v[242:245], v[150:153], v[50:53]
	v_mfma_f32_16x16x32_bf16 v[42:45], v[234:237], v[186:189], v[42:45]
	v_mfma_f32_16x16x32_bf16 v[34:37], v[242:245], v[186:189], v[34:37]
	v_mfma_f32_16x16x32_bf16 v[26:29], v[234:237], v[194:197], v[26:29]
	v_mfma_f32_16x16x32_bf16 v[18:21], v[242:245], v[194:197], v[18:21]
	v_mfma_f32_16x16x32_bf16 v[10:13], v[234:237], v[216:219], v[10:13]
	v_mfma_f32_16x16x32_bf16 v[2:5], v[242:245], v[216:219], v[2:5]
	s_setprio 1
	s_barrier
	s_add_i32 s1, 0, 0x18000
	v_add_u32_e32 v142, s1, v201
	ds_read_b128 v[130:133], v142
	ds_read_b128 v[134:137], v142 offset:1024
	ds_read_b128 v[138:141], v142 offset:2048
	ds_read_b128 v[142:145], v142 offset:3072
	s_add_u32 s22, s42, 0x40000
	s_addc_u32 s23, s43, 0
	s_mov_b32 m0, s48
	v_lshl_add_u64 v[230:231], s[22:23], 0, v[158:159]
	ds_read_b128 v[146:149], v205 offset:32768
	ds_read_b128 v[150:153], v205 offset:33792
	ds_read_b128 v[182:185], v205 offset:34816
	ds_read_b128 v[186:189], v205 offset:35840
	ds_read_b128 v[190:193], v205 offset:36864
	ds_read_b128 v[194:197], v205 offset:37888
	ds_read_b128 v[206:209], v205 offset:38912
	ds_read_b128 v[216:219], v205 offset:39936
	global_load_lds_dwordx4 v[230:231], off
	v_lshl_add_u64 v[230:231], s[22:23], 0, v[156:157]
	s_mov_b32 m0, s49
	s_nop 0
	global_load_lds_dwordx4 v[230:231], off
	s_add_i32 s33, 0, 0x1c000
	v_add_u32_e32 v168, s33, v201
	ds_read_b128 v[230:233], v168
	ds_read_b128 v[234:237], v168 offset:1024
	ds_read_b128 v[238:241], v168 offset:2048
	ds_read_b128 v[242:245], v168 offset:3072
	s_waitcnt vmcnt(8)
	s_waitcnt lgkmcnt(0)
	s_barrier
	s_setprio 0
	v_mfma_f32_16x16x32_bf16 v[126:129], v[130:133], v[146:149], v[126:129]
	v_mfma_f32_16x16x32_bf16 v[118:121], v[138:141], v[146:149], v[118:121]
	v_mfma_f32_16x16x32_bf16 v[110:113], v[130:133], v[182:185], v[110:113]
	v_mfma_f32_16x16x32_bf16 v[102:105], v[138:141], v[182:185], v[102:105]
	v_mfma_f32_16x16x32_bf16 v[94:97], v[130:133], v[190:193], v[94:97]
	v_mfma_f32_16x16x32_bf16 v[86:89], v[138:141], v[190:193], v[86:89]
	v_mfma_f32_16x16x32_bf16 v[78:81], v[130:133], v[206:209], v[78:81]
	v_mfma_f32_16x16x32_bf16 v[70:73], v[138:141], v[206:209], v[70:73]
	v_mfma_f32_16x16x32_bf16 v[126:129], v[134:137], v[150:153], v[126:129]
	v_mfma_f32_16x16x32_bf16 v[118:121], v[142:145], v[150:153], v[118:121]
	v_mfma_f32_16x16x32_bf16 v[110:113], v[134:137], v[186:189], v[110:113]
	v_mfma_f32_16x16x32_bf16 v[102:105], v[142:145], v[186:189], v[102:105]
	v_mfma_f32_16x16x32_bf16 v[94:97], v[134:137], v[194:197], v[94:97]
	v_mfma_f32_16x16x32_bf16 v[86:89], v[142:145], v[194:197], v[86:89]
	v_mfma_f32_16x16x32_bf16 v[78:81], v[134:137], v[216:219], v[78:81]
	v_mfma_f32_16x16x32_bf16 v[70:73], v[142:145], v[216:219], v[70:73]
	v_mfma_f32_16x16x32_bf16 v[122:125], v[230:233], v[146:149], v[122:125]
	v_mfma_f32_16x16x32_bf16 v[114:117], v[238:241], v[146:149], v[114:117]
	v_mfma_f32_16x16x32_bf16 v[106:109], v[230:233], v[182:185], v[106:109]
	v_mfma_f32_16x16x32_bf16 v[98:101], v[238:241], v[182:185], v[98:101]
	v_mfma_f32_16x16x32_bf16 v[90:93], v[230:233], v[190:193], v[90:93]
	v_mfma_f32_16x16x32_bf16 v[82:85], v[238:241], v[190:193], v[82:85]
	v_mfma_f32_16x16x32_bf16 v[74:77], v[230:233], v[206:209], v[74:77]
	v_mfma_f32_16x16x32_bf16 v[66:69], v[238:241], v[206:209], v[66:69]
	v_mfma_f32_16x16x32_bf16 v[122:125], v[234:237], v[150:153], v[122:125]
	v_mfma_f32_16x16x32_bf16 v[114:117], v[242:245], v[150:153], v[114:117]
	v_mfma_f32_16x16x32_bf16 v[106:109], v[234:237], v[186:189], v[106:109]
	v_mfma_f32_16x16x32_bf16 v[98:101], v[242:245], v[186:189], v[98:101]
	v_mfma_f32_16x16x32_bf16 v[90:93], v[234:237], v[194:197], v[90:93]
	v_mfma_f32_16x16x32_bf16 v[82:85], v[242:245], v[194:197], v[82:85]
	v_mfma_f32_16x16x32_bf16 v[74:77], v[234:237], v[216:219], v[74:77]
	v_mfma_f32_16x16x32_bf16 v[66:69], v[242:245], v[216:219], v[66:69]
	s_setprio 1
	s_barrier
	ds_read_b128 v[146:149], v205 offset:49152
	ds_read_b128 v[150:153], v205 offset:50176
	ds_read_b128 v[182:185], v205 offset:51200
	ds_read_b128 v[186:189], v205 offset:52224
	ds_read_b128 v[190:193], v205 offset:53248
	ds_read_b128 v[194:197], v205 offset:54272
	ds_read_b128 v[206:209], v205 offset:55296
	ds_read_b128 v[216:219], v205 offset:56320
	s_add_i32 s1, s1, s17
	v_lshl_add_u64 v[176:177], v[176:177], 0, s[12:13]
	s_mov_b32 m0, s1
	s_nop 0
	global_load_lds_dwordx4 v[176:177], off
	v_lshl_add_u64 v[176:177], v[202:203], 0, s[12:13]
	s_add_i32 m0, s1, 0x2000
	s_nop 0
	global_load_lds_dwordx4 v[176:177], off
	s_mov_b32 m0, s20
	v_lshl_add_u64 v[176:177], v[220:221], 0, s[12:13]
	global_load_lds_dwordx4 v[176:177], off
	v_lshl_add_u64 v[176:177], v[246:247], 0, s[12:13]
	s_mov_b32 m0, s21
	s_nop 0
	global_load_lds_dwordx4 v[176:177], off
	s_add_u32 s22, s30, 0x40080
	s_addc_u32 s23, s31, 0
	s_add_i32 s1, s33, s17
	s_mov_b32 m0, s1
	s_nop 0
	global_load_lds_dwordx4 v0, s[22:23]
	s_add_i32 m0, s1, 0x2000
	s_nop 0
	global_load_lds_dwordx4 v154, s[22:23]
	s_waitcnt vmcnt(8)
	s_waitcnt lgkmcnt(0)
	s_barrier
	s_setprio 0
	v_mfma_f32_16x16x32_bf16 v[62:65], v[130:133], v[146:149], v[62:65]
	v_mfma_f32_16x16x32_bf16 v[54:57], v[138:141], v[146:149], v[54:57]
	v_mfma_f32_16x16x32_bf16 v[46:49], v[130:133], v[182:185], v[46:49]
	v_mfma_f32_16x16x32_bf16 v[38:41], v[138:141], v[182:185], v[38:41]
	v_mfma_f32_16x16x32_bf16 v[30:33], v[130:133], v[190:193], v[30:33]
	v_mfma_f32_16x16x32_bf16 v[22:25], v[138:141], v[190:193], v[22:25]
	v_mfma_f32_16x16x32_bf16 v[14:17], v[130:133], v[206:209], v[14:17]
	v_mfma_f32_16x16x32_bf16 v[6:9], v[138:141], v[206:209], v[6:9]
	v_mfma_f32_16x16x32_bf16 v[62:65], v[134:137], v[150:153], v[62:65]
	v_mfma_f32_16x16x32_bf16 v[54:57], v[142:145], v[150:153], v[54:57]
	v_mfma_f32_16x16x32_bf16 v[46:49], v[134:137], v[186:189], v[46:49]
	v_mfma_f32_16x16x32_bf16 v[38:41], v[142:145], v[186:189], v[38:41]
	v_mfma_f32_16x16x32_bf16 v[30:33], v[134:137], v[194:197], v[30:33]
	v_mfma_f32_16x16x32_bf16 v[22:25], v[142:145], v[194:197], v[22:25]
	v_mfma_f32_16x16x32_bf16 v[14:17], v[134:137], v[216:219], v[14:17]
	v_mfma_f32_16x16x32_bf16 v[6:9], v[142:145], v[216:219], v[6:9]
	v_mfma_f32_16x16x32_bf16 v[58:61], v[230:233], v[146:149], v[58:61]
	v_mfma_f32_16x16x32_bf16 v[50:53], v[238:241], v[146:149], v[50:53]
	v_mfma_f32_16x16x32_bf16 v[42:45], v[230:233], v[182:185], v[42:45]
	v_mfma_f32_16x16x32_bf16 v[34:37], v[238:241], v[182:185], v[34:37]
	v_mfma_f32_16x16x32_bf16 v[26:29], v[230:233], v[190:193], v[26:29]
	v_mfma_f32_16x16x32_bf16 v[18:21], v[238:241], v[190:193], v[18:21]
	v_mfma_f32_16x16x32_bf16 v[10:13], v[230:233], v[206:209], v[10:13]
	v_mfma_f32_16x16x32_bf16 v[2:5], v[238:241], v[206:209], v[2:5]
	v_mfma_f32_16x16x32_bf16 v[58:61], v[234:237], v[150:153], v[58:61]
	v_mfma_f32_16x16x32_bf16 v[50:53], v[242:245], v[150:153], v[50:53]
	v_mfma_f32_16x16x32_bf16 v[42:45], v[234:237], v[186:189], v[42:45]
	v_mfma_f32_16x16x32_bf16 v[34:37], v[242:245], v[186:189], v[34:37]
	v_mfma_f32_16x16x32_bf16 v[26:29], v[234:237], v[194:197], v[26:29]
	v_mfma_f32_16x16x32_bf16 v[18:21], v[242:245], v[194:197], v[18:21]
	v_mfma_f32_16x16x32_bf16 v[10:13], v[234:237], v[216:219], v[10:13]
	v_mfma_f32_16x16x32_bf16 v[2:5], v[242:245], v[216:219], v[2:5]
	s_setprio 1
	s_add_i32 s60, s60, 2
	s_add_u32 s28, s28, 0x100
	s_addc_u32 s29, s29, 0
	s_add_u32 s58, s58, 0x100
	s_addc_u32 s59, s59, 0
	s_cmp_gt_u32 s60, 13
	s_barrier
	s_cbranch_scc0 .LBB0_83
	s_cmpk_gt_u32 s0, 0xff
	s_cbranch_scc1 .Lrs_i2_post
	s_barrier

.Lrs_i3_pre:
	s_add_i32 s23, s22, 2
	s_add_u32 s1, s36, 0x80
	s_addc_u32 s30, s37, 0
	s_add_i32 s33, 0, 0x10000
	v_add_u32_e32 v142, s33, v203
	ds_read_b128 v[130:133], v142
	ds_read_b128 v[134:137], v142 offset:1024
	ds_read_b128 v[138:141], v142 offset:2048
	ds_read_b128 v[142:145], v142 offset:3072
	s_cmp_eq_u32 s69, s22
	s_cselect_b32 s31, s27, s30
	s_cselect_b32 s30, s26, s1
	s_cselect_b32 s47, s29, s49
	s_cselect_b32 s46, s28, s48
	v_lshl_add_u64 v[176:177], s[36:37], 0, v[180:181]
	s_add_i32 m0, s21, 0xc000
	ds_read_b128 v[146:149], v205
	ds_read_b128 v[150:153], v205 offset:1024
	ds_read_b128 v[154:157], v205 offset:2048
	ds_read_b128 v[184:187], v205 offset:3072
	ds_read_b128 v[188:191], v205 offset:4096
	ds_read_b128 v[192:195], v205 offset:5120
	ds_read_b128 v[196:199], v205 offset:6144
	ds_read_b128 v[206:209], v205 offset:7168
	global_load_lds_dwordx4 v[176:177], off
	v_lshl_add_u64 v[176:177], s[36:37], 0, v[182:183]
	s_add_i32 m0, s21, 0xe000
	s_nop 0
	global_load_lds_dwordx4 v[176:177], off
	s_add_i32 s1, 0, 0x14000
	v_add_u32_e32 v168, s1, v203
	ds_read_b128 v[216:219], v168
	ds_read_b128 v[230:233], v168 offset:1024
	ds_read_b128 v[234:237], v168 offset:2048
	ds_read_b128 v[238:241], v168 offset:3072
	s_waitcnt vmcnt(8)
	s_waitcnt lgkmcnt(0)
	s_barrier
	s_setprio 0
	v_mfma_f32_16x16x32_bf16 v[126:129], v[130:133], v[146:149], 0
	v_mfma_f32_16x16x32_bf16 v[122:125], v[138:141], v[146:149], 0
	v_mfma_f32_16x16x32_bf16 v[110:113], v[130:133], v[154:157], 0
	v_mfma_f32_16x16x32_bf16 v[106:109], v[138:141], v[154:157], 0
	v_mfma_f32_16x16x32_bf16 v[94:97], v[130:133], v[188:191], 0
	v_mfma_f32_16x16x32_bf16 v[90:93], v[138:141], v[188:191], 0
	v_mfma_f32_16x16x32_bf16 v[78:81], v[130:133], v[196:199], 0
	v_mfma_f32_16x16x32_bf16 v[74:77], v[138:141], v[196:199], 0
	v_mfma_f32_16x16x32_bf16 v[126:129], v[134:137], v[150:153], v[126:129]
	v_mfma_f32_16x16x32_bf16 v[122:125], v[142:145], v[150:153], v[122:125]
	v_mfma_f32_16x16x32_bf16 v[110:113], v[134:137], v[184:187], v[110:113]
	v_mfma_f32_16x16x32_bf16 v[106:109], v[142:145], v[184:187], v[106:109]
	v_mfma_f32_16x16x32_bf16 v[94:97], v[134:137], v[192:195], v[94:97]
	v_mfma_f32_16x16x32_bf16 v[90:93], v[142:145], v[192:195], v[90:93]
	v_mfma_f32_16x16x32_bf16 v[78:81], v[134:137], v[206:209], v[78:81]
	v_mfma_f32_16x16x32_bf16 v[74:77], v[142:145], v[206:209], v[74:77]
	v_mfma_f32_16x16x32_bf16 v[118:121], v[216:219], v[146:149], 0
	v_mfma_f32_16x16x32_bf16 v[114:117], v[234:237], v[146:149], 0
	v_mfma_f32_16x16x32_bf16 v[102:105], v[216:219], v[154:157], 0
	v_mfma_f32_16x16x32_bf16 v[98:101], v[234:237], v[154:157], 0
	v_mfma_f32_16x16x32_bf16 v[86:89], v[216:219], v[188:191], 0
	v_mfma_f32_16x16x32_bf16 v[82:85], v[234:237], v[188:191], 0
	v_mfma_f32_16x16x32_bf16 v[70:73], v[216:219], v[196:199], 0
	v_mfma_f32_16x16x32_bf16 v[66:69], v[234:237], v[196:199], 0
	v_mfma_f32_16x16x32_bf16 v[118:121], v[230:233], v[150:153], v[118:121]
	v_mfma_f32_16x16x32_bf16 v[114:117], v[238:241], v[150:153], v[114:117]
	v_mfma_f32_16x16x32_bf16 v[102:105], v[230:233], v[184:187], v[102:105]
	v_mfma_f32_16x16x32_bf16 v[98:101], v[238:241], v[184:187], v[98:101]
	v_mfma_f32_16x16x32_bf16 v[86:89], v[230:233], v[192:195], v[86:89]
	v_mfma_f32_16x16x32_bf16 v[82:85], v[238:241], v[192:195], v[82:85]
	v_mfma_f32_16x16x32_bf16 v[70:73], v[230:233], v[206:209], v[70:73]
	v_mfma_f32_16x16x32_bf16 v[66:69], v[238:241], v[206:209], v[66:69]
	s_setprio 1
	s_barrier
	ds_read_b128 v[146:149], v205 offset:16384
	ds_read_b128 v[150:153], v205 offset:17408
	ds_read_b128 v[154:157], v205 offset:18432
	ds_read_b128 v[184:187], v205 offset:19456
	ds_read_b128 v[188:191], v205 offset:20480
	ds_read_b128 v[192:195], v205 offset:21504
	ds_read_b128 v[196:199], v205 offset:22528
	ds_read_b128 v[206:209], v205 offset:23552
	s_add_i32 s22, s33, s20
	v_lshl_add_u64 v[176:177], s[46:47], 0, v[0:1]
	s_mov_b32 m0, s22
	s_nop 0
	global_load_lds_dwordx4 v[176:177], off
	v_lshl_add_u64 v[200:201], s[46:47], 0, v[158:159]
	s_add_i32 m0, s22, 0x2000
	s_nop 0
	global_load_lds_dwordx4 v[200:201], off
	s_mov_b32 m0, s21
	v_lshl_add_u64 v[220:221], s[30:31], 0, v[178:179]
	global_load_lds_dwordx4 v[220:221], off
	v_lshl_add_u64 v[242:243], s[30:31], 0, v[160:161]
	s_mov_b32 m0, s34
	s_nop 0
	global_load_lds_dwordx4 v[242:243], off
	s_add_u32 s46, s46, s6
	s_addc_u32 s47, s47, 0
	s_add_i32 s1, s1, s20
	v_lshl_add_u64 v[244:245], s[46:47], 0, v[0:1]
	s_mov_b32 m0, s1
	v_lshl_add_u64 v[246:247], s[46:47], 0, v[158:159]
	global_load_lds_dwordx4 v[244:245], off
	s_add_i32 m0, s1, 0x2000
	s_nop 0
	global_load_lds_dwordx4 v[246:247], off
	s_waitcnt vmcnt(8)
	s_waitcnt lgkmcnt(0)
	s_barrier
	s_setprio 0
	v_mfma_f32_16x16x32_bf16 v[62:65], v[130:133], v[146:149], 0
	v_mfma_f32_16x16x32_bf16 v[58:61], v[138:141], v[146:149], 0
	v_mfma_f32_16x16x32_bf16 v[46:49], v[130:133], v[154:157], 0
	v_mfma_f32_16x16x32_bf16 v[42:45], v[138:141], v[154:157], 0
	v_mfma_f32_16x16x32_bf16 v[30:33], v[130:133], v[188:191], 0
	v_mfma_f32_16x16x32_bf16 v[26:29], v[138:141], v[188:191], 0
	v_mfma_f32_16x16x32_bf16 v[14:17], v[130:133], v[196:199], 0
	v_mfma_f32_16x16x32_bf16 v[10:13], v[138:141], v[196:199], 0
	v_mfma_f32_16x16x32_bf16 v[62:65], v[134:137], v[150:153], v[62:65]
	v_mfma_f32_16x16x32_bf16 v[58:61], v[142:145], v[150:153], v[58:61]
	v_mfma_f32_16x16x32_bf16 v[46:49], v[134:137], v[184:187], v[46:49]
	v_mfma_f32_16x16x32_bf16 v[42:45], v[142:145], v[184:187], v[42:45]
	v_mfma_f32_16x16x32_bf16 v[30:33], v[134:137], v[192:195], v[30:33]
	v_mfma_f32_16x16x32_bf16 v[26:29], v[142:145], v[192:195], v[26:29]
	v_mfma_f32_16x16x32_bf16 v[14:17], v[134:137], v[206:209], v[14:17]
	v_mfma_f32_16x16x32_bf16 v[10:13], v[142:145], v[206:209], v[10:13]
	v_mfma_f32_16x16x32_bf16 v[54:57], v[216:219], v[146:149], 0
	v_mfma_f32_16x16x32_bf16 v[50:53], v[234:237], v[146:149], 0
	v_mfma_f32_16x16x32_bf16 v[38:41], v[216:219], v[154:157], 0
	v_mfma_f32_16x16x32_bf16 v[34:37], v[234:237], v[154:157], 0
	v_mfma_f32_16x16x32_bf16 v[22:25], v[216:219], v[188:191], 0
	v_mfma_f32_16x16x32_bf16 v[18:21], v[234:237], v[188:191], 0
	v_mfma_f32_16x16x32_bf16 v[6:9], v[216:219], v[196:199], 0
	v_mfma_f32_16x16x32_bf16 v[2:5], v[234:237], v[196:199], 0
	v_mfma_f32_16x16x32_bf16 v[54:57], v[230:233], v[150:153], v[54:57]
	v_mfma_f32_16x16x32_bf16 v[50:53], v[238:241], v[150:153], v[50:53]
	v_mfma_f32_16x16x32_bf16 v[38:41], v[230:233], v[184:187], v[38:41]
	v_mfma_f32_16x16x32_bf16 v[34:37], v[238:241], v[184:187], v[34:37]
	v_mfma_f32_16x16x32_bf16 v[22:25], v[230:233], v[192:195], v[22:25]
	v_mfma_f32_16x16x32_bf16 v[18:21], v[238:241], v[192:195], v[18:21]
	v_mfma_f32_16x16x32_bf16 v[6:9], v[230:233], v[206:209], v[6:9]
	v_mfma_f32_16x16x32_bf16 v[2:5], v[238:241], v[206:209], v[2:5]
	s_setprio 1
	s_barrier
	s_add_i32 s1, 0, 0x18000
	v_add_u32_e32 v142, s1, v203
	ds_read_b128 v[130:133], v142
	ds_read_b128 v[134:137], v142 offset:1024
	ds_read_b128 v[138:141], v142 offset:2048
	ds_read_b128 v[142:145], v142 offset:3072
	s_add_u32 s30, s30, s6
	s_addc_u32 s31, s31, 0
	s_mov_b32 m0, s63
	v_lshl_add_u64 v[216:217], s[30:31], 0, v[178:179]
	ds_read_b128 v[146:149], v205 offset:32768
	ds_read_b128 v[150:153], v205 offset:33792
	ds_read_b128 v[154:157], v205 offset:34816
	ds_read_b128 v[184:187], v205 offset:35840
	ds_read_b128 v[188:191], v205 offset:36864
	ds_read_b128 v[192:195], v205 offset:37888
	ds_read_b128 v[196:199], v205 offset:38912
	ds_read_b128 v[206:209], v205 offset:39936
	global_load_lds_dwordx4 v[216:217], off
	v_lshl_add_u64 v[216:217], s[30:31], 0, v[160:161]
	s_mov_b32 m0, s64
	s_nop 0
	global_load_lds_dwordx4 v[216:217], off
	s_add_i32 s22, 0, 0x1c000
	v_add_u32_e32 v168, s22, v203
	ds_read_b128 v[216:219], v168
	ds_read_b128 v[230:233], v168 offset:1024
	ds_read_b128 v[234:237], v168 offset:2048
	ds_read_b128 v[238:241], v168 offset:3072
	s_waitcnt vmcnt(8)
	s_waitcnt lgkmcnt(0)
	s_barrier
	s_setprio 0
	v_mfma_f32_16x16x32_bf16 v[126:129], v[130:133], v[146:149], v[126:129]
	v_mfma_f32_16x16x32_bf16 v[122:125], v[138:141], v[146:149], v[122:125]
	v_mfma_f32_16x16x32_bf16 v[110:113], v[130:133], v[154:157], v[110:113]
	v_mfma_f32_16x16x32_bf16 v[106:109], v[138:141], v[154:157], v[106:109]
	v_mfma_f32_16x16x32_bf16 v[94:97], v[130:133], v[188:191], v[94:97]
	v_mfma_f32_16x16x32_bf16 v[90:93], v[138:141], v[188:191], v[90:93]
	v_mfma_f32_16x16x32_bf16 v[78:81], v[130:133], v[196:199], v[78:81]
	v_mfma_f32_16x16x32_bf16 v[74:77], v[138:141], v[196:199], v[74:77]
	v_mfma_f32_16x16x32_bf16 v[126:129], v[134:137], v[150:153], v[126:129]
	v_mfma_f32_16x16x32_bf16 v[122:125], v[142:145], v[150:153], v[122:125]
	v_mfma_f32_16x16x32_bf16 v[110:113], v[134:137], v[184:187], v[110:113]
	v_mfma_f32_16x16x32_bf16 v[106:109], v[142:145], v[184:187], v[106:109]
	v_mfma_f32_16x16x32_bf16 v[94:97], v[134:137], v[192:195], v[94:97]
	v_mfma_f32_16x16x32_bf16 v[90:93], v[142:145], v[192:195], v[90:93]
	v_mfma_f32_16x16x32_bf16 v[78:81], v[134:137], v[206:209], v[78:81]
	v_mfma_f32_16x16x32_bf16 v[74:77], v[142:145], v[206:209], v[74:77]
	v_mfma_f32_16x16x32_bf16 v[118:121], v[216:219], v[146:149], v[118:121]
	v_mfma_f32_16x16x32_bf16 v[114:117], v[234:237], v[146:149], v[114:117]
	v_mfma_f32_16x16x32_bf16 v[102:105], v[216:219], v[154:157], v[102:105]
	v_mfma_f32_16x16x32_bf16 v[98:101], v[234:237], v[154:157], v[98:101]
	v_mfma_f32_16x16x32_bf16 v[86:89], v[216:219], v[188:191], v[86:89]
	v_mfma_f32_16x16x32_bf16 v[82:85], v[234:237], v[188:191], v[82:85]
	v_mfma_f32_16x16x32_bf16 v[70:73], v[216:219], v[196:199], v[70:73]
	v_mfma_f32_16x16x32_bf16 v[66:69], v[234:237], v[196:199], v[66:69]
	v_mfma_f32_16x16x32_bf16 v[118:121], v[230:233], v[150:153], v[118:121]
	v_mfma_f32_16x16x32_bf16 v[114:117], v[238:241], v[150:153], v[114:117]
	v_mfma_f32_16x16x32_bf16 v[102:105], v[230:233], v[184:187], v[102:105]
	v_mfma_f32_16x16x32_bf16 v[98:101], v[238:241], v[184:187], v[98:101]
	v_mfma_f32_16x16x32_bf16 v[86:89], v[230:233], v[192:195], v[86:89]
	v_mfma_f32_16x16x32_bf16 v[82:85], v[238:241], v[192:195], v[82:85]
	v_mfma_f32_16x16x32_bf16 v[70:73], v[230:233], v[206:209], v[70:73]
	v_mfma_f32_16x16x32_bf16 v[66:69], v[238:241], v[206:209], v[66:69]
	s_setprio 1
	s_barrier
	ds_read_b128 v[146:149], v205 offset:49152
	ds_read_b128 v[150:153], v205 offset:50176
	ds_read_b128 v[154:157], v205 offset:51200
	ds_read_b128 v[184:187], v205 offset:52224
	ds_read_b128 v[188:191], v205 offset:53248
	ds_read_b128 v[192:195], v205 offset:54272
	ds_read_b128 v[196:199], v205 offset:55296
	ds_read_b128 v[206:209], v205 offset:56320
	s_add_i32 s1, s1, s20
	v_lshl_add_u64 v[176:177], v[176:177], 0, s[12:13]
	s_mov_b32 m0, s1
	s_nop 0
	global_load_lds_dwordx4 v[176:177], off
	v_lshl_add_u64 v[176:177], v[200:201], 0, s[12:13]
	s_add_i32 m0, s1, 0x2000
	s_nop 0
	global_load_lds_dwordx4 v[176:177], off
	s_mov_b32 m0, s65
	v_lshl_add_u64 v[176:177], v[220:221], 0, s[12:13]
	global_load_lds_dwordx4 v[176:177], off
	v_lshl_add_u64 v[176:177], v[242:243], 0, s[12:13]
	s_mov_b32 m0, s66
	s_nop 0
	global_load_lds_dwordx4 v[176:177], off
	s_add_i32 s1, s22, s20
	v_lshl_add_u64 v[176:177], v[244:245], 0, s[12:13]
	s_mov_b32 m0, s1
	s_nop 0
	global_load_lds_dwordx4 v[176:177], off
	v_lshl_add_u64 v[176:177], v[246:247], 0, s[12:13]
	s_add_i32 m0, s1, 0x2000
	s_nop 0
	global_load_lds_dwordx4 v[176:177], off
	s_waitcnt vmcnt(8)
	s_waitcnt lgkmcnt(0)
	s_barrier
	s_setprio 0
	v_mfma_f32_16x16x32_bf16 v[62:65], v[130:133], v[146:149], v[62:65]
	v_mfma_f32_16x16x32_bf16 v[58:61], v[138:141], v[146:149], v[58:61]
	v_mfma_f32_16x16x32_bf16 v[46:49], v[130:133], v[154:157], v[46:49]
	v_mfma_f32_16x16x32_bf16 v[42:45], v[138:141], v[154:157], v[42:45]
	v_mfma_f32_16x16x32_bf16 v[30:33], v[130:133], v[188:191], v[30:33]
	v_mfma_f32_16x16x32_bf16 v[26:29], v[138:141], v[188:191], v[26:29]
	v_mfma_f32_16x16x32_bf16 v[14:17], v[130:133], v[196:199], v[14:17]
	v_mfma_f32_16x16x32_bf16 v[10:13], v[138:141], v[196:199], v[10:13]
	v_mfma_f32_16x16x32_bf16 v[62:65], v[134:137], v[150:153], v[62:65]
	v_mfma_f32_16x16x32_bf16 v[58:61], v[142:145], v[150:153], v[58:61]
	v_mfma_f32_16x16x32_bf16 v[46:49], v[134:137], v[184:187], v[46:49]
	v_mfma_f32_16x16x32_bf16 v[42:45], v[142:145], v[184:187], v[42:45]
	v_mfma_f32_16x16x32_bf16 v[30:33], v[134:137], v[192:195], v[30:33]
	v_mfma_f32_16x16x32_bf16 v[26:29], v[142:145], v[192:195], v[26:29]
	v_mfma_f32_16x16x32_bf16 v[14:17], v[134:137], v[206:209], v[14:17]
	v_mfma_f32_16x16x32_bf16 v[10:13], v[142:145], v[206:209], v[10:13]
	v_mfma_f32_16x16x32_bf16 v[54:57], v[216:219], v[146:149], v[54:57]
	v_mfma_f32_16x16x32_bf16 v[50:53], v[234:237], v[146:149], v[50:53]
	v_mfma_f32_16x16x32_bf16 v[38:41], v[216:219], v[154:157], v[38:41]
	v_mfma_f32_16x16x32_bf16 v[34:37], v[234:237], v[154:157], v[34:37]
	v_mfma_f32_16x16x32_bf16 v[22:25], v[216:219], v[188:191], v[22:25]
	v_mfma_f32_16x16x32_bf16 v[18:21], v[234:237], v[188:191], v[18:21]
	v_mfma_f32_16x16x32_bf16 v[6:9], v[216:219], v[196:199], v[6:9]
	v_mfma_f32_16x16x32_bf16 v[2:5], v[234:237], v[196:199], v[2:5]
	v_mfma_f32_16x16x32_bf16 v[54:57], v[230:233], v[150:153], v[54:57]
	v_mfma_f32_16x16x32_bf16 v[50:53], v[238:241], v[150:153], v[50:53]
	v_mfma_f32_16x16x32_bf16 v[38:41], v[230:233], v[184:187], v[38:41]
	v_mfma_f32_16x16x32_bf16 v[34:37], v[238:241], v[184:187], v[34:37]
	v_mfma_f32_16x16x32_bf16 v[22:25], v[230:233], v[192:195], v[22:25]
	v_mfma_f32_16x16x32_bf16 v[18:21], v[238:241], v[192:195], v[18:21]
	v_mfma_f32_16x16x32_bf16 v[6:9], v[230:233], v[206:209], v[6:9]
	v_mfma_f32_16x16x32_bf16 v[2:5], v[238:241], v[206:209], v[2:5]
	s_setprio 1
	s_add_u32 s36, s36, 0x100
	s_addc_u32 s37, s37, 0
	s_add_u32 s48, s48, 0x100
	s_addc_u32 s49, s49, 0
	s_cmp_ge_u32 s23, s68
	s_mov_b32 s22, s23
	s_barrier
.LBB0_120:
	s_add_i32 s23, s22, 2
	s_add_u32 s1, s36, 0x80
	s_addc_u32 s30, s37, 0
	s_add_i32 s33, 0, 0x10000
	v_add_u32_e32 v142, s33, v203
	ds_read_b128 v[130:133], v142
	ds_read_b128 v[134:137], v142 offset:1024
	ds_read_b128 v[138:141], v142 offset:2048
	ds_read_b128 v[142:145], v142 offset:3072
	s_cmp_eq_u32 s69, s22
	s_cselect_b32 s31, s27, s30
	s_cselect_b32 s30, s26, s1
	s_cselect_b32 s47, s29, s49
	s_cselect_b32 s46, s28, s48
	v_lshl_add_u64 v[176:177], s[36:37], 0, v[180:181]
	s_add_i32 m0, s21, 0xc000
	ds_read_b128 v[146:149], v205
	ds_read_b128 v[150:153], v205 offset:1024
	ds_read_b128 v[154:157], v205 offset:2048
	ds_read_b128 v[184:187], v205 offset:3072
	ds_read_b128 v[188:191], v205 offset:4096
	ds_read_b128 v[192:195], v205 offset:5120
	ds_read_b128 v[196:199], v205 offset:6144
	ds_read_b128 v[206:209], v205 offset:7168
	global_load_lds_dwordx4 v[176:177], off
	v_lshl_add_u64 v[176:177], s[36:37], 0, v[182:183]
	s_add_i32 m0, s21, 0xe000
	s_nop 0
	global_load_lds_dwordx4 v[176:177], off
	s_add_i32 s1, 0, 0x14000
	v_add_u32_e32 v168, s1, v203
	ds_read_b128 v[216:219], v168
	ds_read_b128 v[230:233], v168 offset:1024
	ds_read_b128 v[234:237], v168 offset:2048
	ds_read_b128 v[238:241], v168 offset:3072
	s_waitcnt vmcnt(8)
	s_waitcnt lgkmcnt(0)
	s_barrier
	s_setprio 0
	v_mfma_f32_16x16x32_bf16 v[126:129], v[130:133], v[146:149], v[126:129]
	v_mfma_f32_16x16x32_bf16 v[122:125], v[138:141], v[146:149], v[122:125]
	v_mfma_f32_16x16x32_bf16 v[110:113], v[130:133], v[154:157], v[110:113]
	v_mfma_f32_16x16x32_bf16 v[106:109], v[138:141], v[154:157], v[106:109]
	v_mfma_f32_16x16x32_bf16 v[94:97], v[130:133], v[188:191], v[94:97]
	v_mfma_f32_16x16x32_bf16 v[90:93], v[138:141], v[188:191], v[90:93]
	v_mfma_f32_16x16x32_bf16 v[78:81], v[130:133], v[196:199], v[78:81]
	v_mfma_f32_16x16x32_bf16 v[74:77], v[138:141], v[196:199], v[74:77]
	v_mfma_f32_16x16x32_bf16 v[126:129], v[134:137], v[150:153], v[126:129]
	v_mfma_f32_16x16x32_bf16 v[122:125], v[142:145], v[150:153], v[122:125]
	v_mfma_f32_16x16x32_bf16 v[110:113], v[134:137], v[184:187], v[110:113]
	v_mfma_f32_16x16x32_bf16 v[106:109], v[142:145], v[184:187], v[106:109]
	v_mfma_f32_16x16x32_bf16 v[94:97], v[134:137], v[192:195], v[94:97]
	v_mfma_f32_16x16x32_bf16 v[90:93], v[142:145], v[192:195], v[90:93]
	v_mfma_f32_16x16x32_bf16 v[78:81], v[134:137], v[206:209], v[78:81]
	v_mfma_f32_16x16x32_bf16 v[74:77], v[142:145], v[206:209], v[74:77]
	v_mfma_f32_16x16x32_bf16 v[118:121], v[216:219], v[146:149], v[118:121]
	v_mfma_f32_16x16x32_bf16 v[114:117], v[234:237], v[146:149], v[114:117]
	v_mfma_f32_16x16x32_bf16 v[102:105], v[216:219], v[154:157], v[102:105]
	v_mfma_f32_16x16x32_bf16 v[98:101], v[234:237], v[154:157], v[98:101]
	v_mfma_f32_16x16x32_bf16 v[86:89], v[216:219], v[188:191], v[86:89]
	v_mfma_f32_16x16x32_bf16 v[82:85], v[234:237], v[188:191], v[82:85]
	v_mfma_f32_16x16x32_bf16 v[70:73], v[216:219], v[196:199], v[70:73]
	v_mfma_f32_16x16x32_bf16 v[66:69], v[234:237], v[196:199], v[66:69]
	v_mfma_f32_16x16x32_bf16 v[118:121], v[230:233], v[150:153], v[118:121]
	v_mfma_f32_16x16x32_bf16 v[114:117], v[238:241], v[150:153], v[114:117]
	v_mfma_f32_16x16x32_bf16 v[102:105], v[230:233], v[184:187], v[102:105]
	v_mfma_f32_16x16x32_bf16 v[98:101], v[238:241], v[184:187], v[98:101]
	v_mfma_f32_16x16x32_bf16 v[86:89], v[230:233], v[192:195], v[86:89]
	v_mfma_f32_16x16x32_bf16 v[82:85], v[238:241], v[192:195], v[82:85]
	v_mfma_f32_16x16x32_bf16 v[70:73], v[230:233], v[206:209], v[70:73]
	v_mfma_f32_16x16x32_bf16 v[66:69], v[238:241], v[206:209], v[66:69]
	s_setprio 1
	s_barrier
	ds_read_b128 v[146:149], v205 offset:16384
	ds_read_b128 v[150:153], v205 offset:17408
	ds_read_b128 v[154:157], v205 offset:18432
	ds_read_b128 v[184:187], v205 offset:19456
	ds_read_b128 v[188:191], v205 offset:20480
	ds_read_b128 v[192:195], v205 offset:21504
	ds_read_b128 v[196:199], v205 offset:22528
	ds_read_b128 v[206:209], v205 offset:23552
	s_add_i32 s22, s33, s20
	v_lshl_add_u64 v[176:177], s[46:47], 0, v[0:1]
	s_mov_b32 m0, s22
	s_nop 0
	global_load_lds_dwordx4 v[176:177], off
	v_lshl_add_u64 v[200:201], s[46:47], 0, v[158:159]
	s_add_i32 m0, s22, 0x2000
	s_nop 0
	global_load_lds_dwordx4 v[200:201], off
	s_mov_b32 m0, s21
	v_lshl_add_u64 v[220:221], s[30:31], 0, v[178:179]
	global_load_lds_dwordx4 v[220:221], off
	v_lshl_add_u64 v[242:243], s[30:31], 0, v[160:161]
	s_mov_b32 m0, s34
	s_nop 0
	global_load_lds_dwordx4 v[242:243], off
	s_add_u32 s46, s46, s6
	s_addc_u32 s47, s47, 0
	s_add_i32 s1, s1, s20
	v_lshl_add_u64 v[244:245], s[46:47], 0, v[0:1]
	s_mov_b32 m0, s1
	v_lshl_add_u64 v[246:247], s[46:47], 0, v[158:159]
	global_load_lds_dwordx4 v[244:245], off
	s_add_i32 m0, s1, 0x2000
	s_nop 0
	global_load_lds_dwordx4 v[246:247], off
	s_waitcnt vmcnt(8)
	s_waitcnt lgkmcnt(0)
	s_barrier
	s_setprio 0
	v_mfma_f32_16x16x32_bf16 v[62:65], v[130:133], v[146:149], v[62:65]
	v_mfma_f32_16x16x32_bf16 v[58:61], v[138:141], v[146:149], v[58:61]
	v_mfma_f32_16x16x32_bf16 v[46:49], v[130:133], v[154:157], v[46:49]
	v_mfma_f32_16x16x32_bf16 v[42:45], v[138:141], v[154:157], v[42:45]
	v_mfma_f32_16x16x32_bf16 v[30:33], v[130:133], v[188:191], v[30:33]
	v_mfma_f32_16x16x32_bf16 v[26:29], v[138:141], v[188:191], v[26:29]
	v_mfma_f32_16x16x32_bf16 v[14:17], v[130:133], v[196:199], v[14:17]
	v_mfma_f32_16x16x32_bf16 v[10:13], v[138:141], v[196:199], v[10:13]
	v_mfma_f32_16x16x32_bf16 v[62:65], v[134:137], v[150:153], v[62:65]
	v_mfma_f32_16x16x32_bf16 v[58:61], v[142:145], v[150:153], v[58:61]
	v_mfma_f32_16x16x32_bf16 v[46:49], v[134:137], v[184:187], v[46:49]
	v_mfma_f32_16x16x32_bf16 v[42:45], v[142:145], v[184:187], v[42:45]
	v_mfma_f32_16x16x32_bf16 v[30:33], v[134:137], v[192:195], v[30:33]
	v_mfma_f32_16x16x32_bf16 v[26:29], v[142:145], v[192:195], v[26:29]
	v_mfma_f32_16x16x32_bf16 v[14:17], v[134:137], v[206:209], v[14:17]
	v_mfma_f32_16x16x32_bf16 v[10:13], v[142:145], v[206:209], v[10:13]
	v_mfma_f32_16x16x32_bf16 v[54:57], v[216:219], v[146:149], v[54:57]
	v_mfma_f32_16x16x32_bf16 v[50:53], v[234:237], v[146:149], v[50:53]
	v_mfma_f32_16x16x32_bf16 v[38:41], v[216:219], v[154:157], v[38:41]
	v_mfma_f32_16x16x32_bf16 v[34:37], v[234:237], v[154:157], v[34:37]
	v_mfma_f32_16x16x32_bf16 v[22:25], v[216:219], v[188:191], v[22:25]
	v_mfma_f32_16x16x32_bf16 v[18:21], v[234:237], v[188:191], v[18:21]
	v_mfma_f32_16x16x32_bf16 v[6:9], v[216:219], v[196:199], v[6:9]
	v_mfma_f32_16x16x32_bf16 v[2:5], v[234:237], v[196:199], v[2:5]
	v_mfma_f32_16x16x32_bf16 v[54:57], v[230:233], v[150:153], v[54:57]
	v_mfma_f32_16x16x32_bf16 v[50:53], v[238:241], v[150:153], v[50:53]
	v_mfma_f32_16x16x32_bf16 v[38:41], v[230:233], v[184:187], v[38:41]
	v_mfma_f32_16x16x32_bf16 v[34:37], v[238:241], v[184:187], v[34:37]
	v_mfma_f32_16x16x32_bf16 v[22:25], v[230:233], v[192:195], v[22:25]
	v_mfma_f32_16x16x32_bf16 v[18:21], v[238:241], v[192:195], v[18:21]
	v_mfma_f32_16x16x32_bf16 v[6:9], v[230:233], v[206:209], v[6:9]
	v_mfma_f32_16x16x32_bf16 v[2:5], v[238:241], v[206:209], v[2:5]
	s_setprio 1
	s_barrier
	s_add_i32 s1, 0, 0x18000
	v_add_u32_e32 v142, s1, v203
	ds_read_b128 v[130:133], v142
	ds_read_b128 v[134:137], v142 offset:1024
	ds_read_b128 v[138:141], v142 offset:2048
	ds_read_b128 v[142:145], v142 offset:3072
	s_add_u32 s30, s30, s6
	s_addc_u32 s31, s31, 0
	s_mov_b32 m0, s63
	v_lshl_add_u64 v[216:217], s[30:31], 0, v[178:179]
	ds_read_b128 v[146:149], v205 offset:32768
	ds_read_b128 v[150:153], v205 offset:33792
	ds_read_b128 v[154:157], v205 offset:34816
	ds_read_b128 v[184:187], v205 offset:35840
	ds_read_b128 v[188:191], v205 offset:36864
	ds_read_b128 v[192:195], v205 offset:37888
	ds_read_b128 v[196:199], v205 offset:38912
	ds_read_b128 v[206:209], v205 offset:39936
	global_load_lds_dwordx4 v[216:217], off
	v_lshl_add_u64 v[216:217], s[30:31], 0, v[160:161]
	s_mov_b32 m0, s64
	s_nop 0
	global_load_lds_dwordx4 v[216:217], off
	s_add_i32 s22, 0, 0x1c000
	v_add_u32_e32 v168, s22, v203
	ds_read_b128 v[216:219], v168
	ds_read_b128 v[230:233], v168 offset:1024
	ds_read_b128 v[234:237], v168 offset:2048
	ds_read_b128 v[238:241], v168 offset:3072
	s_waitcnt vmcnt(8)
	s_waitcnt lgkmcnt(0)
	s_barrier
	s_setprio 0
	v_mfma_f32_16x16x32_bf16 v[126:129], v[130:133], v[146:149], v[126:129]
	v_mfma_f32_16x16x32_bf16 v[122:125], v[138:141], v[146:149], v[122:125]
	v_mfma_f32_16x16x32_bf16 v[110:113], v[130:133], v[154:157], v[110:113]
	v_mfma_f32_16x16x32_bf16 v[106:109], v[138:141], v[154:157], v[106:109]
	v_mfma_f32_16x16x32_bf16 v[94:97], v[130:133], v[188:191], v[94:97]
	v_mfma_f32_16x16x32_bf16 v[90:93], v[138:141], v[188:191], v[90:93]
	v_mfma_f32_16x16x32_bf16 v[78:81], v[130:133], v[196:199], v[78:81]
	v_mfma_f32_16x16x32_bf16 v[74:77], v[138:141], v[196:199], v[74:77]
	v_mfma_f32_16x16x32_bf16 v[126:129], v[134:137], v[150:153], v[126:129]
	v_mfma_f32_16x16x32_bf16 v[122:125], v[142:145], v[150:153], v[122:125]
	v_mfma_f32_16x16x32_bf16 v[110:113], v[134:137], v[184:187], v[110:113]
	v_mfma_f32_16x16x32_bf16 v[106:109], v[142:145], v[184:187], v[106:109]
	v_mfma_f32_16x16x32_bf16 v[94:97], v[134:137], v[192:195], v[94:97]
	v_mfma_f32_16x16x32_bf16 v[90:93], v[142:145], v[192:195], v[90:93]
	v_mfma_f32_16x16x32_bf16 v[78:81], v[134:137], v[206:209], v[78:81]
	v_mfma_f32_16x16x32_bf16 v[74:77], v[142:145], v[206:209], v[74:77]
	v_mfma_f32_16x16x32_bf16 v[118:121], v[216:219], v[146:149], v[118:121]
	v_mfma_f32_16x16x32_bf16 v[114:117], v[234:237], v[146:149], v[114:117]
	v_mfma_f32_16x16x32_bf16 v[102:105], v[216:219], v[154:157], v[102:105]
	v_mfma_f32_16x16x32_bf16 v[98:101], v[234:237], v[154:157], v[98:101]
	v_mfma_f32_16x16x32_bf16 v[86:89], v[216:219], v[188:191], v[86:89]
	v_mfma_f32_16x16x32_bf16 v[82:85], v[234:237], v[188:191], v[82:85]
	v_mfma_f32_16x16x32_bf16 v[70:73], v[216:219], v[196:199], v[70:73]
	v_mfma_f32_16x16x32_bf16 v[66:69], v[234:237], v[196:199], v[66:69]
	v_mfma_f32_16x16x32_bf16 v[118:121], v[230:233], v[150:153], v[118:121]
	v_mfma_f32_16x16x32_bf16 v[114:117], v[238:241], v[150:153], v[114:117]
	v_mfma_f32_16x16x32_bf16 v[102:105], v[230:233], v[184:187], v[102:105]
	v_mfma_f32_16x16x32_bf16 v[98:101], v[238:241], v[184:187], v[98:101]
	v_mfma_f32_16x16x32_bf16 v[86:89], v[230:233], v[192:195], v[86:89]
	v_mfma_f32_16x16x32_bf16 v[82:85], v[238:241], v[192:195], v[82:85]
	v_mfma_f32_16x16x32_bf16 v[70:73], v[230:233], v[206:209], v[70:73]
	v_mfma_f32_16x16x32_bf16 v[66:69], v[238:241], v[206:209], v[66:69]
	s_setprio 1
	s_barrier
	ds_read_b128 v[146:149], v205 offset:49152
	ds_read_b128 v[150:153], v205 offset:50176
	ds_read_b128 v[154:157], v205 offset:51200
	ds_read_b128 v[184:187], v205 offset:52224
	ds_read_b128 v[188:191], v205 offset:53248
	ds_read_b128 v[192:195], v205 offset:54272
	ds_read_b128 v[196:199], v205 offset:55296
	ds_read_b128 v[206:209], v205 offset:56320
	s_add_i32 s1, s1, s20
	v_lshl_add_u64 v[176:177], v[176:177], 0, s[12:13]
	s_mov_b32 m0, s1
	s_nop 0
	global_load_lds_dwordx4 v[176:177], off
	v_lshl_add_u64 v[176:177], v[200:201], 0, s[12:13]
	s_add_i32 m0, s1, 0x2000
	s_nop 0
	global_load_lds_dwordx4 v[176:177], off
	s_mov_b32 m0, s65
	v_lshl_add_u64 v[176:177], v[220:221], 0, s[12:13]
	global_load_lds_dwordx4 v[176:177], off
	v_lshl_add_u64 v[176:177], v[242:243], 0, s[12:13]
	s_mov_b32 m0, s66
	s_nop 0
	global_load_lds_dwordx4 v[176:177], off
	s_add_i32 s1, s22, s20
	v_lshl_add_u64 v[176:177], v[244:245], 0, s[12:13]
	s_mov_b32 m0, s1
	s_nop 0
	global_load_lds_dwordx4 v[176:177], off
	v_lshl_add_u64 v[176:177], v[246:247], 0, s[12:13]
	s_add_i32 m0, s1, 0x2000
	s_nop 0
	global_load_lds_dwordx4 v[176:177], off
	s_waitcnt vmcnt(8)
	s_waitcnt lgkmcnt(0)
	s_barrier
	s_setprio 0
	v_mfma_f32_16x16x32_bf16 v[62:65], v[130:133], v[146:149], v[62:65]
	v_mfma_f32_16x16x32_bf16 v[58:61], v[138:141], v[146:149], v[58:61]
	v_mfma_f32_16x16x32_bf16 v[46:49], v[130:133], v[154:157], v[46:49]
	v_mfma_f32_16x16x32_bf16 v[42:45], v[138:141], v[154:157], v[42:45]
	v_mfma_f32_16x16x32_bf16 v[30:33], v[130:133], v[188:191], v[30:33]
	v_mfma_f32_16x16x32_bf16 v[26:29], v[138:141], v[188:191], v[26:29]
	v_mfma_f32_16x16x32_bf16 v[14:17], v[130:133], v[196:199], v[14:17]
	v_mfma_f32_16x16x32_bf16 v[10:13], v[138:141], v[196:199], v[10:13]
	v_mfma_f32_16x16x32_bf16 v[62:65], v[134:137], v[150:153], v[62:65]
	v_mfma_f32_16x16x32_bf16 v[58:61], v[142:145], v[150:153], v[58:61]
	v_mfma_f32_16x16x32_bf16 v[46:49], v[134:137], v[184:187], v[46:49]
	v_mfma_f32_16x16x32_bf16 v[42:45], v[142:145], v[184:187], v[42:45]
	v_mfma_f32_16x16x32_bf16 v[30:33], v[134:137], v[192:195], v[30:33]
	v_mfma_f32_16x16x32_bf16 v[26:29], v[142:145], v[192:195], v[26:29]
	v_mfma_f32_16x16x32_bf16 v[14:17], v[134:137], v[206:209], v[14:17]
	v_mfma_f32_16x16x32_bf16 v[10:13], v[142:145], v[206:209], v[10:13]
	v_mfma_f32_16x16x32_bf16 v[54:57], v[216:219], v[146:149], v[54:57]
	v_mfma_f32_16x16x32_bf16 v[50:53], v[234:237], v[146:149], v[50:53]
	v_mfma_f32_16x16x32_bf16 v[38:41], v[216:219], v[154:157], v[38:41]
	v_mfma_f32_16x16x32_bf16 v[34:37], v[234:237], v[154:157], v[34:37]
	v_mfma_f32_16x16x32_bf16 v[22:25], v[216:219], v[188:191], v[22:25]
	v_mfma_f32_16x16x32_bf16 v[18:21], v[234:237], v[188:191], v[18:21]
	v_mfma_f32_16x16x32_bf16 v[6:9], v[216:219], v[196:199], v[6:9]
	v_mfma_f32_16x16x32_bf16 v[2:5], v[234:237], v[196:199], v[2:5]
	v_mfma_f32_16x16x32_bf16 v[54:57], v[230:233], v[150:153], v[54:57]
	v_mfma_f32_16x16x32_bf16 v[50:53], v[238:241], v[150:153], v[50:53]
	v_mfma_f32_16x16x32_bf16 v[38:41], v[230:233], v[184:187], v[38:41]
	v_mfma_f32_16x16x32_bf16 v[34:37], v[238:241], v[184:187], v[34:37]
	v_mfma_f32_16x16x32_bf16 v[22:25], v[230:233], v[192:195], v[22:25]
	v_mfma_f32_16x16x32_bf16 v[18:21], v[238:241], v[192:195], v[18:21]
	v_mfma_f32_16x16x32_bf16 v[6:9], v[230:233], v[206:209], v[6:9]
	v_mfma_f32_16x16x32_bf16 v[2:5], v[238:241], v[206:209], v[2:5]
	s_setprio 1
	s_add_u32 s36, s36, 0x100
	s_addc_u32 s37, s37, 0
	s_add_u32 s48, s48, 0x100
	s_addc_u32 s49, s49, 0
	s_cmp_ge_u32 s23, s68
	s_mov_b32 s22, s23
	s_barrier
	s_cbranch_scc0 .LBB0_120
	s_cmpk_gt_u32 s16, 0xff
	s_cbranch_scc1 .Lrs_i3_post
	s_barrier

.Lrs_i4_pre:
	s_add_i32 s23, s22, 2
	s_add_u32 s1, s36, 0x80
	s_addc_u32 s30, s37, 0
	s_add_i32 s33, 0, 0x10000
	v_add_u32_e32 v142, s33, v181
	ds_read_b128 v[130:133], v142
	ds_read_b128 v[134:137], v142 offset:1024
	ds_read_b128 v[138:141], v142 offset:2048
	ds_read_b128 v[142:145], v142 offset:3072
	s_cmp_eq_u32 s68, s22
	s_cselect_b32 s31, s27, s30
	s_cselect_b32 s30, s26, s1
	s_cselect_b32 s47, s29, s49
	s_cselect_b32 s46, s28, s48
	v_lshl_add_u64 v[160:161], s[36:37], 0, v[152:153]
	s_add_i32 m0, s21, 0xc000
	ds_read_b128 v[156:159], v183
	ds_read_b128 v[184:187], v183 offset:1024
	ds_read_b128 v[188:191], v183 offset:2048
	ds_read_b128 v[192:195], v183 offset:3072
	ds_read_b128 v[196:199], v183 offset:4096
	ds_read_b128 v[200:203], v183 offset:5120
	ds_read_b128 v[204:207], v183 offset:6144
	ds_read_b128 v[216:219], v183 offset:7168
	global_load_lds_dwordx4 v[160:161], off
	v_lshl_add_u64 v[160:161], s[36:37], 0, v[154:155]
	s_add_i32 m0, s21, 0xe000
	s_nop 0
	global_load_lds_dwordx4 v[160:161], off
	s_add_i32 s1, 0, 0x14000
	v_add_u32_e32 v160, s1, v181
	ds_read_b128 v[230:233], v160
	ds_read_b128 v[234:237], v160 offset:1024
	ds_read_b128 v[238:241], v160 offset:2048
	ds_read_b128 v[242:245], v160 offset:3072
	s_waitcnt vmcnt(8)
	s_waitcnt lgkmcnt(0)
	s_barrier
	s_setprio 0
	v_mfma_f32_16x16x32_bf16 v[126:129], v[130:133], v[156:159], 0
	v_mfma_f32_16x16x32_bf16 v[122:125], v[138:141], v[156:159], 0
	v_mfma_f32_16x16x32_bf16 v[110:113], v[130:133], v[188:191], 0
	v_mfma_f32_16x16x32_bf16 v[106:109], v[138:141], v[188:191], 0
	v_mfma_f32_16x16x32_bf16 v[94:97], v[130:133], v[196:199], 0
	v_mfma_f32_16x16x32_bf16 v[90:93], v[138:141], v[196:199], 0
	v_mfma_f32_16x16x32_bf16 v[78:81], v[130:133], v[204:207], 0
	v_mfma_f32_16x16x32_bf16 v[74:77], v[138:141], v[204:207], 0
	v_mfma_f32_16x16x32_bf16 v[126:129], v[134:137], v[184:187], v[126:129]
	v_mfma_f32_16x16x32_bf16 v[122:125], v[142:145], v[184:187], v[122:125]
	v_mfma_f32_16x16x32_bf16 v[110:113], v[134:137], v[192:195], v[110:113]
	v_mfma_f32_16x16x32_bf16 v[106:109], v[142:145], v[192:195], v[106:109]
	v_mfma_f32_16x16x32_bf16 v[94:97], v[134:137], v[200:203], v[94:97]
	v_mfma_f32_16x16x32_bf16 v[90:93], v[142:145], v[200:203], v[90:93]
	v_mfma_f32_16x16x32_bf16 v[78:81], v[134:137], v[216:219], v[78:81]
	v_mfma_f32_16x16x32_bf16 v[74:77], v[142:145], v[216:219], v[74:77]
	v_mfma_f32_16x16x32_bf16 v[118:121], v[230:233], v[156:159], 0
	v_mfma_f32_16x16x32_bf16 v[114:117], v[238:241], v[156:159], 0
	v_mfma_f32_16x16x32_bf16 v[102:105], v[230:233], v[188:191], 0
	v_mfma_f32_16x16x32_bf16 v[98:101], v[238:241], v[188:191], 0
	v_mfma_f32_16x16x32_bf16 v[86:89], v[230:233], v[196:199], 0
	v_mfma_f32_16x16x32_bf16 v[82:85], v[238:241], v[196:199], 0
	v_mfma_f32_16x16x32_bf16 v[70:73], v[230:233], v[204:207], 0
	v_mfma_f32_16x16x32_bf16 v[66:69], v[238:241], v[204:207], 0
	v_mfma_f32_16x16x32_bf16 v[118:121], v[234:237], v[184:187], v[118:121]
	v_mfma_f32_16x16x32_bf16 v[114:117], v[242:245], v[184:187], v[114:117]
	v_mfma_f32_16x16x32_bf16 v[102:105], v[234:237], v[192:195], v[102:105]
	v_mfma_f32_16x16x32_bf16 v[98:101], v[242:245], v[192:195], v[98:101]
	v_mfma_f32_16x16x32_bf16 v[86:89], v[234:237], v[200:203], v[86:89]
	v_mfma_f32_16x16x32_bf16 v[82:85], v[242:245], v[200:203], v[82:85]
	v_mfma_f32_16x16x32_bf16 v[70:73], v[234:237], v[216:219], v[70:73]
	v_mfma_f32_16x16x32_bf16 v[66:69], v[242:245], v[216:219], v[66:69]
	s_setprio 1
	s_barrier
	ds_read_b128 v[156:159], v183 offset:16384
	ds_read_b128 v[184:187], v183 offset:17408
	ds_read_b128 v[188:191], v183 offset:18432
	ds_read_b128 v[192:195], v183 offset:19456
	ds_read_b128 v[196:199], v183 offset:20480
	ds_read_b128 v[200:203], v183 offset:21504
	ds_read_b128 v[204:207], v183 offset:22528
	ds_read_b128 v[216:219], v183 offset:23552
	s_add_i32 s22, s33, s20
	v_lshl_add_u64 v[160:161], s[46:47], 0, v[0:1]
	s_mov_b32 m0, s22
	v_lshl_add_u64 v[176:177], s[46:47], 0, v[146:147]
	global_load_lds_dwordx4 v[160:161], off
	s_add_i32 m0, s22, 0x2000
	s_nop 0
	global_load_lds_dwordx4 v[176:177], off
	s_mov_b32 m0, s21
	v_lshl_add_u64 v[178:179], s[30:31], 0, v[150:151]
	global_load_lds_dwordx4 v[178:179], off
	v_lshl_add_u64 v[208:209], s[30:31], 0, v[148:149]
	s_mov_b32 m0, s34
	s_nop 0
	global_load_lds_dwordx4 v[208:209], off
	s_add_u32 s46, s46, s6
	s_addc_u32 s47, s47, 0
	s_add_i32 s1, s1, s20
	v_lshl_add_u64 v[220:221], s[46:47], 0, v[0:1]
	s_mov_b32 m0, s1
	v_lshl_add_u64 v[246:247], s[46:47], 0, v[146:147]
	global_load_lds_dwordx4 v[220:221], off
	s_add_i32 m0, s1, 0x2000
	s_nop 0
	global_load_lds_dwordx4 v[246:247], off
	s_waitcnt vmcnt(8)
	s_waitcnt lgkmcnt(0)
	s_barrier
	s_setprio 0
	v_mfma_f32_16x16x32_bf16 v[62:65], v[130:133], v[156:159], 0
	v_mfma_f32_16x16x32_bf16 v[58:61], v[138:141], v[156:159], 0
	v_mfma_f32_16x16x32_bf16 v[46:49], v[130:133], v[188:191], 0
	v_mfma_f32_16x16x32_bf16 v[42:45], v[138:141], v[188:191], 0
	v_mfma_f32_16x16x32_bf16 v[30:33], v[130:133], v[196:199], 0
	v_mfma_f32_16x16x32_bf16 v[26:29], v[138:141], v[196:199], 0
	v_mfma_f32_16x16x32_bf16 v[14:17], v[130:133], v[204:207], 0
	v_mfma_f32_16x16x32_bf16 v[10:13], v[138:141], v[204:207], 0
	v_mfma_f32_16x16x32_bf16 v[62:65], v[134:137], v[184:187], v[62:65]
	v_mfma_f32_16x16x32_bf16 v[58:61], v[142:145], v[184:187], v[58:61]
	v_mfma_f32_16x16x32_bf16 v[46:49], v[134:137], v[192:195], v[46:49]
	v_mfma_f32_16x16x32_bf16 v[42:45], v[142:145], v[192:195], v[42:45]
	v_mfma_f32_16x16x32_bf16 v[30:33], v[134:137], v[200:203], v[30:33]
	v_mfma_f32_16x16x32_bf16 v[26:29], v[142:145], v[200:203], v[26:29]
	v_mfma_f32_16x16x32_bf16 v[14:17], v[134:137], v[216:219], v[14:17]
	v_mfma_f32_16x16x32_bf16 v[10:13], v[142:145], v[216:219], v[10:13]
	v_mfma_f32_16x16x32_bf16 v[54:57], v[230:233], v[156:159], 0
	v_mfma_f32_16x16x32_bf16 v[50:53], v[238:241], v[156:159], 0
	v_mfma_f32_16x16x32_bf16 v[38:41], v[230:233], v[188:191], 0
	v_mfma_f32_16x16x32_bf16 v[34:37], v[238:241], v[188:191], 0
	v_mfma_f32_16x16x32_bf16 v[22:25], v[230:233], v[196:199], 0
	v_mfma_f32_16x16x32_bf16 v[18:21], v[238:241], v[196:199], 0
	v_mfma_f32_16x16x32_bf16 v[6:9], v[230:233], v[204:207], 0
	v_mfma_f32_16x16x32_bf16 v[2:5], v[238:241], v[204:207], 0
	v_mfma_f32_16x16x32_bf16 v[54:57], v[234:237], v[184:187], v[54:57]
	v_mfma_f32_16x16x32_bf16 v[50:53], v[242:245], v[184:187], v[50:53]
	v_mfma_f32_16x16x32_bf16 v[38:41], v[234:237], v[192:195], v[38:41]
	v_mfma_f32_16x16x32_bf16 v[34:37], v[242:245], v[192:195], v[34:37]
	v_mfma_f32_16x16x32_bf16 v[22:25], v[234:237], v[200:203], v[22:25]
	v_mfma_f32_16x16x32_bf16 v[18:21], v[242:245], v[200:203], v[18:21]
	v_mfma_f32_16x16x32_bf16 v[6:9], v[234:237], v[216:219], v[6:9]
	v_mfma_f32_16x16x32_bf16 v[2:5], v[242:245], v[216:219], v[2:5]
	s_setprio 1
	s_barrier
	s_add_i32 s1, 0, 0x18000
	v_add_u32_e32 v142, s1, v181
	ds_read_b128 v[130:133], v142
	ds_read_b128 v[134:137], v142 offset:1024
	ds_read_b128 v[138:141], v142 offset:2048
	ds_read_b128 v[142:145], v142 offset:3072
	s_add_u32 s30, s30, s6
	s_addc_u32 s31, s31, 0
	s_mov_b32 m0, s63
	v_lshl_add_u64 v[230:231], s[30:31], 0, v[150:151]
	ds_read_b128 v[156:159], v183 offset:32768
	ds_read_b128 v[184:187], v183 offset:33792
	ds_read_b128 v[188:191], v183 offset:34816
	ds_read_b128 v[192:195], v183 offset:35840
	ds_read_b128 v[196:199], v183 offset:36864
	ds_read_b128 v[200:203], v183 offset:37888
	ds_read_b128 v[204:207], v183 offset:38912
	ds_read_b128 v[216:219], v183 offset:39936
	global_load_lds_dwordx4 v[230:231], off
	v_lshl_add_u64 v[230:231], s[30:31], 0, v[148:149]
	s_mov_b32 m0, s64
	s_nop 0
	global_load_lds_dwordx4 v[230:231], off
	s_add_i32 s22, 0, 0x1c000
	v_add_u32_e32 v168, s22, v181
	ds_read_b128 v[230:233], v168
	ds_read_b128 v[234:237], v168 offset:1024
	ds_read_b128 v[238:241], v168 offset:2048
	ds_read_b128 v[242:245], v168 offset:3072
	s_waitcnt vmcnt(8)
	s_waitcnt lgkmcnt(0)
	s_barrier
	s_setprio 0
	v_mfma_f32_16x16x32_bf16 v[126:129], v[130:133], v[156:159], v[126:129]
	v_mfma_f32_16x16x32_bf16 v[122:125], v[138:141], v[156:159], v[122:125]
	v_mfma_f32_16x16x32_bf16 v[110:113], v[130:133], v[188:191], v[110:113]
	v_mfma_f32_16x16x32_bf16 v[106:109], v[138:141], v[188:191], v[106:109]
	v_mfma_f32_16x16x32_bf16 v[94:97], v[130:133], v[196:199], v[94:97]
	v_mfma_f32_16x16x32_bf16 v[90:93], v[138:141], v[196:199], v[90:93]
	v_mfma_f32_16x16x32_bf16 v[78:81], v[130:133], v[204:207], v[78:81]
	v_mfma_f32_16x16x32_bf16 v[74:77], v[138:141], v[204:207], v[74:77]
	v_mfma_f32_16x16x32_bf16 v[126:129], v[134:137], v[184:187], v[126:129]
	v_mfma_f32_16x16x32_bf16 v[122:125], v[142:145], v[184:187], v[122:125]
	v_mfma_f32_16x16x32_bf16 v[110:113], v[134:137], v[192:195], v[110:113]
	v_mfma_f32_16x16x32_bf16 v[106:109], v[142:145], v[192:195], v[106:109]
	v_mfma_f32_16x16x32_bf16 v[94:97], v[134:137], v[200:203], v[94:97]
	v_mfma_f32_16x16x32_bf16 v[90:93], v[142:145], v[200:203], v[90:93]
	v_mfma_f32_16x16x32_bf16 v[78:81], v[134:137], v[216:219], v[78:81]
	v_mfma_f32_16x16x32_bf16 v[74:77], v[142:145], v[216:219], v[74:77]
	v_mfma_f32_16x16x32_bf16 v[118:121], v[230:233], v[156:159], v[118:121]
	v_mfma_f32_16x16x32_bf16 v[114:117], v[238:241], v[156:159], v[114:117]
	v_mfma_f32_16x16x32_bf16 v[102:105], v[230:233], v[188:191], v[102:105]
	v_mfma_f32_16x16x32_bf16 v[98:101], v[238:241], v[188:191], v[98:101]
	v_mfma_f32_16x16x32_bf16 v[86:89], v[230:233], v[196:199], v[86:89]
	v_mfma_f32_16x16x32_bf16 v[82:85], v[238:241], v[196:199], v[82:85]
	v_mfma_f32_16x16x32_bf16 v[70:73], v[230:233], v[204:207], v[70:73]
	v_mfma_f32_16x16x32_bf16 v[66:69], v[238:241], v[204:207], v[66:69]
	v_mfma_f32_16x16x32_bf16 v[118:121], v[234:237], v[184:187], v[118:121]
	v_mfma_f32_16x16x32_bf16 v[114:117], v[242:245], v[184:187], v[114:117]
	v_mfma_f32_16x16x32_bf16 v[102:105], v[234:237], v[192:195], v[102:105]
	v_mfma_f32_16x16x32_bf16 v[98:101], v[242:245], v[192:195], v[98:101]
	v_mfma_f32_16x16x32_bf16 v[86:89], v[234:237], v[200:203], v[86:89]
	v_mfma_f32_16x16x32_bf16 v[82:85], v[242:245], v[200:203], v[82:85]
	v_mfma_f32_16x16x32_bf16 v[70:73], v[234:237], v[216:219], v[70:73]
	v_mfma_f32_16x16x32_bf16 v[66:69], v[242:245], v[216:219], v[66:69]
	s_setprio 1
	s_barrier
	ds_read_b128 v[156:159], v183 offset:49152
	ds_read_b128 v[184:187], v183 offset:50176
	ds_read_b128 v[188:191], v183 offset:51200
	ds_read_b128 v[192:195], v183 offset:52224
	ds_read_b128 v[196:199], v183 offset:53248
	ds_read_b128 v[200:203], v183 offset:54272
	ds_read_b128 v[204:207], v183 offset:55296
	ds_read_b128 v[216:219], v183 offset:56320
	s_add_i32 s1, s1, s20
	v_lshl_add_u64 v[160:161], v[160:161], 0, s[12:13]
	s_mov_b32 m0, s1
	s_nop 0
	global_load_lds_dwordx4 v[160:161], off
	v_lshl_add_u64 v[160:161], v[176:177], 0, s[12:13]
	s_add_i32 m0, s1, 0x2000
	s_nop 0
	global_load_lds_dwordx4 v[160:161], off
	s_mov_b32 m0, s65
	v_lshl_add_u64 v[160:161], v[178:179], 0, s[12:13]
	global_load_lds_dwordx4 v[160:161], off
	v_lshl_add_u64 v[160:161], v[208:209], 0, s[12:13]
	s_mov_b32 m0, s66
	s_nop 0
	global_load_lds_dwordx4 v[160:161], off
	s_add_i32 s1, s22, s20
	v_lshl_add_u64 v[160:161], v[220:221], 0, s[12:13]
	s_mov_b32 m0, s1
	s_nop 0
	global_load_lds_dwordx4 v[160:161], off
	v_lshl_add_u64 v[160:161], v[246:247], 0, s[12:13]
	s_add_i32 m0, s1, 0x2000
	s_nop 0
	global_load_lds_dwordx4 v[160:161], off
	s_waitcnt vmcnt(8)
	s_waitcnt lgkmcnt(0)
	s_barrier
	s_setprio 0
	v_mfma_f32_16x16x32_bf16 v[62:65], v[130:133], v[156:159], v[62:65]
	v_mfma_f32_16x16x32_bf16 v[58:61], v[138:141], v[156:159], v[58:61]
	v_mfma_f32_16x16x32_bf16 v[46:49], v[130:133], v[188:191], v[46:49]
	v_mfma_f32_16x16x32_bf16 v[42:45], v[138:141], v[188:191], v[42:45]
	v_mfma_f32_16x16x32_bf16 v[30:33], v[130:133], v[196:199], v[30:33]
	v_mfma_f32_16x16x32_bf16 v[26:29], v[138:141], v[196:199], v[26:29]
	v_mfma_f32_16x16x32_bf16 v[14:17], v[130:133], v[204:207], v[14:17]
	v_mfma_f32_16x16x32_bf16 v[10:13], v[138:141], v[204:207], v[10:13]
	v_mfma_f32_16x16x32_bf16 v[62:65], v[134:137], v[184:187], v[62:65]
	v_mfma_f32_16x16x32_bf16 v[58:61], v[142:145], v[184:187], v[58:61]
	v_mfma_f32_16x16x32_bf16 v[46:49], v[134:137], v[192:195], v[46:49]
	v_mfma_f32_16x16x32_bf16 v[42:45], v[142:145], v[192:195], v[42:45]
	v_mfma_f32_16x16x32_bf16 v[30:33], v[134:137], v[200:203], v[30:33]
	v_mfma_f32_16x16x32_bf16 v[26:29], v[142:145], v[200:203], v[26:29]
	v_mfma_f32_16x16x32_bf16 v[14:17], v[134:137], v[216:219], v[14:17]
	v_mfma_f32_16x16x32_bf16 v[10:13], v[142:145], v[216:219], v[10:13]
	v_mfma_f32_16x16x32_bf16 v[54:57], v[230:233], v[156:159], v[54:57]
	v_mfma_f32_16x16x32_bf16 v[50:53], v[238:241], v[156:159], v[50:53]
	v_mfma_f32_16x16x32_bf16 v[38:41], v[230:233], v[188:191], v[38:41]
	v_mfma_f32_16x16x32_bf16 v[34:37], v[238:241], v[188:191], v[34:37]
	v_mfma_f32_16x16x32_bf16 v[22:25], v[230:233], v[196:199], v[22:25]
	v_mfma_f32_16x16x32_bf16 v[18:21], v[238:241], v[196:199], v[18:21]
	v_mfma_f32_16x16x32_bf16 v[6:9], v[230:233], v[204:207], v[6:9]
	v_mfma_f32_16x16x32_bf16 v[2:5], v[238:241], v[204:207], v[2:5]
	v_mfma_f32_16x16x32_bf16 v[54:57], v[234:237], v[184:187], v[54:57]
	v_mfma_f32_16x16x32_bf16 v[50:53], v[242:245], v[184:187], v[50:53]
	v_mfma_f32_16x16x32_bf16 v[38:41], v[234:237], v[192:195], v[38:41]
	v_mfma_f32_16x16x32_bf16 v[34:37], v[242:245], v[192:195], v[34:37]
	v_mfma_f32_16x16x32_bf16 v[22:25], v[234:237], v[200:203], v[22:25]
	v_mfma_f32_16x16x32_bf16 v[18:21], v[242:245], v[200:203], v[18:21]
	v_mfma_f32_16x16x32_bf16 v[6:9], v[234:237], v[216:219], v[6:9]
	v_mfma_f32_16x16x32_bf16 v[2:5], v[242:245], v[216:219], v[2:5]
	s_setprio 1
	s_add_u32 s36, s36, 0x100
	s_addc_u32 s37, s37, 0
	s_add_u32 s48, s48, 0x100
	s_addc_u32 s49, s49, 0
	s_cmp_ge_u32 s23, s0
	s_mov_b32 s22, s23
	s_barrier
.LBB0_159:
	s_add_i32 s23, s22, 2
	s_add_u32 s1, s36, 0x80
	s_addc_u32 s30, s37, 0
	s_add_i32 s33, 0, 0x10000
	v_add_u32_e32 v142, s33, v181
	ds_read_b128 v[130:133], v142
	ds_read_b128 v[134:137], v142 offset:1024
	ds_read_b128 v[138:141], v142 offset:2048
	ds_read_b128 v[142:145], v142 offset:3072
	s_cmp_eq_u32 s68, s22
	s_cselect_b32 s31, s27, s30
	s_cselect_b32 s30, s26, s1
	s_cselect_b32 s47, s29, s49
	s_cselect_b32 s46, s28, s48
	v_lshl_add_u64 v[160:161], s[36:37], 0, v[152:153]
	s_add_i32 m0, s21, 0xc000
	ds_read_b128 v[156:159], v183
	ds_read_b128 v[184:187], v183 offset:1024
	ds_read_b128 v[188:191], v183 offset:2048
	ds_read_b128 v[192:195], v183 offset:3072
	ds_read_b128 v[196:199], v183 offset:4096
	ds_read_b128 v[200:203], v183 offset:5120
	ds_read_b128 v[204:207], v183 offset:6144
	ds_read_b128 v[216:219], v183 offset:7168
	global_load_lds_dwordx4 v[160:161], off
	v_lshl_add_u64 v[160:161], s[36:37], 0, v[154:155]
	s_add_i32 m0, s21, 0xe000
	s_nop 0
	global_load_lds_dwordx4 v[160:161], off
	s_add_i32 s1, 0, 0x14000
	v_add_u32_e32 v160, s1, v181
	ds_read_b128 v[230:233], v160
	ds_read_b128 v[234:237], v160 offset:1024
	ds_read_b128 v[238:241], v160 offset:2048
	ds_read_b128 v[242:245], v160 offset:3072
	s_waitcnt vmcnt(8)
	s_waitcnt lgkmcnt(0)
	s_barrier
	s_setprio 0
	v_mfma_f32_16x16x32_bf16 v[126:129], v[130:133], v[156:159], v[126:129]
	v_mfma_f32_16x16x32_bf16 v[122:125], v[138:141], v[156:159], v[122:125]
	v_mfma_f32_16x16x32_bf16 v[110:113], v[130:133], v[188:191], v[110:113]
	v_mfma_f32_16x16x32_bf16 v[106:109], v[138:141], v[188:191], v[106:109]
	v_mfma_f32_16x16x32_bf16 v[94:97], v[130:133], v[196:199], v[94:97]
	v_mfma_f32_16x16x32_bf16 v[90:93], v[138:141], v[196:199], v[90:93]
	v_mfma_f32_16x16x32_bf16 v[78:81], v[130:133], v[204:207], v[78:81]
	v_mfma_f32_16x16x32_bf16 v[74:77], v[138:141], v[204:207], v[74:77]
	v_mfma_f32_16x16x32_bf16 v[126:129], v[134:137], v[184:187], v[126:129]
	v_mfma_f32_16x16x32_bf16 v[122:125], v[142:145], v[184:187], v[122:125]
	v_mfma_f32_16x16x32_bf16 v[110:113], v[134:137], v[192:195], v[110:113]
	v_mfma_f32_16x16x32_bf16 v[106:109], v[142:145], v[192:195], v[106:109]
	v_mfma_f32_16x16x32_bf16 v[94:97], v[134:137], v[200:203], v[94:97]
	v_mfma_f32_16x16x32_bf16 v[90:93], v[142:145], v[200:203], v[90:93]
	v_mfma_f32_16x16x32_bf16 v[78:81], v[134:137], v[216:219], v[78:81]
	v_mfma_f32_16x16x32_bf16 v[74:77], v[142:145], v[216:219], v[74:77]
	v_mfma_f32_16x16x32_bf16 v[118:121], v[230:233], v[156:159], v[118:121]
	v_mfma_f32_16x16x32_bf16 v[114:117], v[238:241], v[156:159], v[114:117]
	v_mfma_f32_16x16x32_bf16 v[102:105], v[230:233], v[188:191], v[102:105]
	v_mfma_f32_16x16x32_bf16 v[98:101], v[238:241], v[188:191], v[98:101]
	v_mfma_f32_16x16x32_bf16 v[86:89], v[230:233], v[196:199], v[86:89]
	v_mfma_f32_16x16x32_bf16 v[82:85], v[238:241], v[196:199], v[82:85]
	v_mfma_f32_16x16x32_bf16 v[70:73], v[230:233], v[204:207], v[70:73]
	v_mfma_f32_16x16x32_bf16 v[66:69], v[238:241], v[204:207], v[66:69]
	v_mfma_f32_16x16x32_bf16 v[118:121], v[234:237], v[184:187], v[118:121]
	v_mfma_f32_16x16x32_bf16 v[114:117], v[242:245], v[184:187], v[114:117]
	v_mfma_f32_16x16x32_bf16 v[102:105], v[234:237], v[192:195], v[102:105]
	v_mfma_f32_16x16x32_bf16 v[98:101], v[242:245], v[192:195], v[98:101]
	v_mfma_f32_16x16x32_bf16 v[86:89], v[234:237], v[200:203], v[86:89]
	v_mfma_f32_16x16x32_bf16 v[82:85], v[242:245], v[200:203], v[82:85]
	v_mfma_f32_16x16x32_bf16 v[70:73], v[234:237], v[216:219], v[70:73]
	v_mfma_f32_16x16x32_bf16 v[66:69], v[242:245], v[216:219], v[66:69]
	s_setprio 1
	s_barrier
	ds_read_b128 v[156:159], v183 offset:16384
	ds_read_b128 v[184:187], v183 offset:17408
	ds_read_b128 v[188:191], v183 offset:18432
	ds_read_b128 v[192:195], v183 offset:19456
	ds_read_b128 v[196:199], v183 offset:20480
	ds_read_b128 v[200:203], v183 offset:21504
	ds_read_b128 v[204:207], v183 offset:22528
	ds_read_b128 v[216:219], v183 offset:23552
	s_add_i32 s22, s33, s20
	v_lshl_add_u64 v[160:161], s[46:47], 0, v[0:1]
	s_mov_b32 m0, s22
	v_lshl_add_u64 v[176:177], s[46:47], 0, v[146:147]
	global_load_lds_dwordx4 v[160:161], off
	s_add_i32 m0, s22, 0x2000
	s_nop 0
	global_load_lds_dwordx4 v[176:177], off
	s_mov_b32 m0, s21
	v_lshl_add_u64 v[178:179], s[30:31], 0, v[150:151]
	global_load_lds_dwordx4 v[178:179], off
	v_lshl_add_u64 v[208:209], s[30:31], 0, v[148:149]
	s_mov_b32 m0, s34
	s_nop 0
	global_load_lds_dwordx4 v[208:209], off
	s_add_u32 s46, s46, s6
	s_addc_u32 s47, s47, 0
	s_add_i32 s1, s1, s20
	v_lshl_add_u64 v[220:221], s[46:47], 0, v[0:1]
	s_mov_b32 m0, s1
	v_lshl_add_u64 v[246:247], s[46:47], 0, v[146:147]
	global_load_lds_dwordx4 v[220:221], off
	s_add_i32 m0, s1, 0x2000
	s_nop 0
	global_load_lds_dwordx4 v[246:247], off
	s_waitcnt vmcnt(8)
	s_waitcnt lgkmcnt(0)
	s_barrier
	s_setprio 0
	v_mfma_f32_16x16x32_bf16 v[62:65], v[130:133], v[156:159], v[62:65]
	v_mfma_f32_16x16x32_bf16 v[58:61], v[138:141], v[156:159], v[58:61]
	v_mfma_f32_16x16x32_bf16 v[46:49], v[130:133], v[188:191], v[46:49]
	v_mfma_f32_16x16x32_bf16 v[42:45], v[138:141], v[188:191], v[42:45]
	v_mfma_f32_16x16x32_bf16 v[30:33], v[130:133], v[196:199], v[30:33]
	v_mfma_f32_16x16x32_bf16 v[26:29], v[138:141], v[196:199], v[26:29]
	v_mfma_f32_16x16x32_bf16 v[14:17], v[130:133], v[204:207], v[14:17]
	v_mfma_f32_16x16x32_bf16 v[10:13], v[138:141], v[204:207], v[10:13]
	v_mfma_f32_16x16x32_bf16 v[62:65], v[134:137], v[184:187], v[62:65]
	v_mfma_f32_16x16x32_bf16 v[58:61], v[142:145], v[184:187], v[58:61]
	v_mfma_f32_16x16x32_bf16 v[46:49], v[134:137], v[192:195], v[46:49]
	v_mfma_f32_16x16x32_bf16 v[42:45], v[142:145], v[192:195], v[42:45]
	v_mfma_f32_16x16x32_bf16 v[30:33], v[134:137], v[200:203], v[30:33]
	v_mfma_f32_16x16x32_bf16 v[26:29], v[142:145], v[200:203], v[26:29]
	v_mfma_f32_16x16x32_bf16 v[14:17], v[134:137], v[216:219], v[14:17]
	v_mfma_f32_16x16x32_bf16 v[10:13], v[142:145], v[216:219], v[10:13]
	v_mfma_f32_16x16x32_bf16 v[54:57], v[230:233], v[156:159], v[54:57]
	v_mfma_f32_16x16x32_bf16 v[50:53], v[238:241], v[156:159], v[50:53]
	v_mfma_f32_16x16x32_bf16 v[38:41], v[230:233], v[188:191], v[38:41]
	v_mfma_f32_16x16x32_bf16 v[34:37], v[238:241], v[188:191], v[34:37]
	v_mfma_f32_16x16x32_bf16 v[22:25], v[230:233], v[196:199], v[22:25]
	v_mfma_f32_16x16x32_bf16 v[18:21], v[238:241], v[196:199], v[18:21]
	v_mfma_f32_16x16x32_bf16 v[6:9], v[230:233], v[204:207], v[6:9]
	v_mfma_f32_16x16x32_bf16 v[2:5], v[238:241], v[204:207], v[2:5]
	v_mfma_f32_16x16x32_bf16 v[54:57], v[234:237], v[184:187], v[54:57]
	v_mfma_f32_16x16x32_bf16 v[50:53], v[242:245], v[184:187], v[50:53]
	v_mfma_f32_16x16x32_bf16 v[38:41], v[234:237], v[192:195], v[38:41]
	v_mfma_f32_16x16x32_bf16 v[34:37], v[242:245], v[192:195], v[34:37]
	v_mfma_f32_16x16x32_bf16 v[22:25], v[234:237], v[200:203], v[22:25]
	v_mfma_f32_16x16x32_bf16 v[18:21], v[242:245], v[200:203], v[18:21]
	v_mfma_f32_16x16x32_bf16 v[6:9], v[234:237], v[216:219], v[6:9]
	v_mfma_f32_16x16x32_bf16 v[2:5], v[242:245], v[216:219], v[2:5]
	s_setprio 1
	s_barrier
	s_add_i32 s1, 0, 0x18000
	v_add_u32_e32 v142, s1, v181
	ds_read_b128 v[130:133], v142
	ds_read_b128 v[134:137], v142 offset:1024
	ds_read_b128 v[138:141], v142 offset:2048
	ds_read_b128 v[142:145], v142 offset:3072
	s_add_u32 s30, s30, s6
	s_addc_u32 s31, s31, 0
	s_mov_b32 m0, s63
	v_lshl_add_u64 v[230:231], s[30:31], 0, v[150:151]
	ds_read_b128 v[156:159], v183 offset:32768
	ds_read_b128 v[184:187], v183 offset:33792
	ds_read_b128 v[188:191], v183 offset:34816
	ds_read_b128 v[192:195], v183 offset:35840
	ds_read_b128 v[196:199], v183 offset:36864
	ds_read_b128 v[200:203], v183 offset:37888
	ds_read_b128 v[204:207], v183 offset:38912
	ds_read_b128 v[216:219], v183 offset:39936
	global_load_lds_dwordx4 v[230:231], off
	v_lshl_add_u64 v[230:231], s[30:31], 0, v[148:149]
	s_mov_b32 m0, s64
	s_nop 0
	global_load_lds_dwordx4 v[230:231], off
	s_add_i32 s22, 0, 0x1c000
	v_add_u32_e32 v168, s22, v181
	ds_read_b128 v[230:233], v168
	ds_read_b128 v[234:237], v168 offset:1024
	ds_read_b128 v[238:241], v168 offset:2048
	ds_read_b128 v[242:245], v168 offset:3072
	s_waitcnt vmcnt(8)
	s_waitcnt lgkmcnt(0)
	s_barrier
	s_setprio 0
	v_mfma_f32_16x16x32_bf16 v[126:129], v[130:133], v[156:159], v[126:129]
	v_mfma_f32_16x16x32_bf16 v[122:125], v[138:141], v[156:159], v[122:125]
	v_mfma_f32_16x16x32_bf16 v[110:113], v[130:133], v[188:191], v[110:113]
	v_mfma_f32_16x16x32_bf16 v[106:109], v[138:141], v[188:191], v[106:109]
	v_mfma_f32_16x16x32_bf16 v[94:97], v[130:133], v[196:199], v[94:97]
	v_mfma_f32_16x16x32_bf16 v[90:93], v[138:141], v[196:199], v[90:93]
	v_mfma_f32_16x16x32_bf16 v[78:81], v[130:133], v[204:207], v[78:81]
	v_mfma_f32_16x16x32_bf16 v[74:77], v[138:141], v[204:207], v[74:77]
	v_mfma_f32_16x16x32_bf16 v[126:129], v[134:137], v[184:187], v[126:129]
	v_mfma_f32_16x16x32_bf16 v[122:125], v[142:145], v[184:187], v[122:125]
	v_mfma_f32_16x16x32_bf16 v[110:113], v[134:137], v[192:195], v[110:113]
	v_mfma_f32_16x16x32_bf16 v[106:109], v[142:145], v[192:195], v[106:109]
	v_mfma_f32_16x16x32_bf16 v[94:97], v[134:137], v[200:203], v[94:97]
	v_mfma_f32_16x16x32_bf16 v[90:93], v[142:145], v[200:203], v[90:93]
	v_mfma_f32_16x16x32_bf16 v[78:81], v[134:137], v[216:219], v[78:81]
	v_mfma_f32_16x16x32_bf16 v[74:77], v[142:145], v[216:219], v[74:77]
	v_mfma_f32_16x16x32_bf16 v[118:121], v[230:233], v[156:159], v[118:121]
	v_mfma_f32_16x16x32_bf16 v[114:117], v[238:241], v[156:159], v[114:117]
	v_mfma_f32_16x16x32_bf16 v[102:105], v[230:233], v[188:191], v[102:105]
	v_mfma_f32_16x16x32_bf16 v[98:101], v[238:241], v[188:191], v[98:101]
	v_mfma_f32_16x16x32_bf16 v[86:89], v[230:233], v[196:199], v[86:89]
	v_mfma_f32_16x16x32_bf16 v[82:85], v[238:241], v[196:199], v[82:85]
	v_mfma_f32_16x16x32_bf16 v[70:73], v[230:233], v[204:207], v[70:73]
	v_mfma_f32_16x16x32_bf16 v[66:69], v[238:241], v[204:207], v[66:69]
	v_mfma_f32_16x16x32_bf16 v[118:121], v[234:237], v[184:187], v[118:121]
	v_mfma_f32_16x16x32_bf16 v[114:117], v[242:245], v[184:187], v[114:117]
	v_mfma_f32_16x16x32_bf16 v[102:105], v[234:237], v[192:195], v[102:105]
	v_mfma_f32_16x16x32_bf16 v[98:101], v[242:245], v[192:195], v[98:101]
	v_mfma_f32_16x16x32_bf16 v[86:89], v[234:237], v[200:203], v[86:89]
	v_mfma_f32_16x16x32_bf16 v[82:85], v[242:245], v[200:203], v[82:85]
	v_mfma_f32_16x16x32_bf16 v[70:73], v[234:237], v[216:219], v[70:73]
	v_mfma_f32_16x16x32_bf16 v[66:69], v[242:245], v[216:219], v[66:69]
	s_setprio 1
	s_barrier
	ds_read_b128 v[156:159], v183 offset:49152
	ds_read_b128 v[184:187], v183 offset:50176
	ds_read_b128 v[188:191], v183 offset:51200
	ds_read_b128 v[192:195], v183 offset:52224
	ds_read_b128 v[196:199], v183 offset:53248
	ds_read_b128 v[200:203], v183 offset:54272
	ds_read_b128 v[204:207], v183 offset:55296
	ds_read_b128 v[216:219], v183 offset:56320
	s_add_i32 s1, s1, s20
	v_lshl_add_u64 v[160:161], v[160:161], 0, s[12:13]
	s_mov_b32 m0, s1
	s_nop 0
	global_load_lds_dwordx4 v[160:161], off
	v_lshl_add_u64 v[160:161], v[176:177], 0, s[12:13]
	s_add_i32 m0, s1, 0x2000
	s_nop 0
	global_load_lds_dwordx4 v[160:161], off
	s_mov_b32 m0, s65
	v_lshl_add_u64 v[160:161], v[178:179], 0, s[12:13]
	global_load_lds_dwordx4 v[160:161], off
	v_lshl_add_u64 v[160:161], v[208:209], 0, s[12:13]
	s_mov_b32 m0, s66
	s_nop 0
	global_load_lds_dwordx4 v[160:161], off
	s_add_i32 s1, s22, s20
	v_lshl_add_u64 v[160:161], v[220:221], 0, s[12:13]
	s_mov_b32 m0, s1
	s_nop 0
	global_load_lds_dwordx4 v[160:161], off
	v_lshl_add_u64 v[160:161], v[246:247], 0, s[12:13]
	s_add_i32 m0, s1, 0x2000
	s_nop 0
	global_load_lds_dwordx4 v[160:161], off
	s_waitcnt vmcnt(8)
	s_waitcnt lgkmcnt(0)
	s_barrier
	s_setprio 0
	v_mfma_f32_16x16x32_bf16 v[62:65], v[130:133], v[156:159], v[62:65]
	v_mfma_f32_16x16x32_bf16 v[58:61], v[138:141], v[156:159], v[58:61]
	v_mfma_f32_16x16x32_bf16 v[46:49], v[130:133], v[188:191], v[46:49]
	v_mfma_f32_16x16x32_bf16 v[42:45], v[138:141], v[188:191], v[42:45]
	v_mfma_f32_16x16x32_bf16 v[30:33], v[130:133], v[196:199], v[30:33]
	v_mfma_f32_16x16x32_bf16 v[26:29], v[138:141], v[196:199], v[26:29]
	v_mfma_f32_16x16x32_bf16 v[14:17], v[130:133], v[204:207], v[14:17]
	v_mfma_f32_16x16x32_bf16 v[10:13], v[138:141], v[204:207], v[10:13]
	v_mfma_f32_16x16x32_bf16 v[62:65], v[134:137], v[184:187], v[62:65]
	v_mfma_f32_16x16x32_bf16 v[58:61], v[142:145], v[184:187], v[58:61]
	v_mfma_f32_16x16x32_bf16 v[46:49], v[134:137], v[192:195], v[46:49]
	v_mfma_f32_16x16x32_bf16 v[42:45], v[142:145], v[192:195], v[42:45]
	v_mfma_f32_16x16x32_bf16 v[30:33], v[134:137], v[200:203], v[30:33]
	v_mfma_f32_16x16x32_bf16 v[26:29], v[142:145], v[200:203], v[26:29]
	v_mfma_f32_16x16x32_bf16 v[14:17], v[134:137], v[216:219], v[14:17]
	v_mfma_f32_16x16x32_bf16 v[10:13], v[142:145], v[216:219], v[10:13]
	v_mfma_f32_16x16x32_bf16 v[54:57], v[230:233], v[156:159], v[54:57]
	v_mfma_f32_16x16x32_bf16 v[50:53], v[238:241], v[156:159], v[50:53]
	v_mfma_f32_16x16x32_bf16 v[38:41], v[230:233], v[188:191], v[38:41]
	v_mfma_f32_16x16x32_bf16 v[34:37], v[238:241], v[188:191], v[34:37]
	v_mfma_f32_16x16x32_bf16 v[22:25], v[230:233], v[196:199], v[22:25]
	v_mfma_f32_16x16x32_bf16 v[18:21], v[238:241], v[196:199], v[18:21]
	v_mfma_f32_16x16x32_bf16 v[6:9], v[230:233], v[204:207], v[6:9]
	v_mfma_f32_16x16x32_bf16 v[2:5], v[238:241], v[204:207], v[2:5]
	v_mfma_f32_16x16x32_bf16 v[54:57], v[234:237], v[184:187], v[54:57]
	v_mfma_f32_16x16x32_bf16 v[50:53], v[242:245], v[184:187], v[50:53]
	v_mfma_f32_16x16x32_bf16 v[38:41], v[234:237], v[192:195], v[38:41]
	v_mfma_f32_16x16x32_bf16 v[34:37], v[242:245], v[192:195], v[34:37]
	v_mfma_f32_16x16x32_bf16 v[22:25], v[234:237], v[200:203], v[22:25]
	v_mfma_f32_16x16x32_bf16 v[18:21], v[242:245], v[200:203], v[18:21]
	v_mfma_f32_16x16x32_bf16 v[6:9], v[234:237], v[216:219], v[6:9]
	v_mfma_f32_16x16x32_bf16 v[2:5], v[242:245], v[216:219], v[2:5]
	s_setprio 1
	s_add_u32 s36, s36, 0x100
	s_addc_u32 s37, s37, 0
	s_add_u32 s48, s48, 0x100
	s_addc_u32 s49, s49, 0
	s_cmp_ge_u32 s23, s0
	s_mov_b32 s22, s23
	s_barrier
	s_cbranch_scc0 .LBB0_159
	s_cmpk_gt_u32 s16, 0xff
	s_cbranch_scc1 .Lrs_i4_post
	s_barrier

.Lrs_proj0_pre:
	s_add_u32 s1, s42, 0xfffc0080
	s_addc_u32 s22, s43, -1
	s_add_i32 s23, 0, 0x10000
	v_add_u32_e32 v142, s23, v217
	ds_read_b128 v[130:133], v142
	ds_read_b128 v[134:137], v142 offset:1024
	ds_read_b128 v[138:141], v142 offset:2048
	ds_read_b128 v[142:145], v142 offset:3072
	s_cmp_eq_u32 s54, 12
	s_cselect_b32 s45, s27, s22
	s_cselect_b32 s44, s50, s1
	s_cselect_b32 s31, s7, s53
	s_cselect_b32 s30, s51, s52
	v_lshl_add_u64 v[176:177], s[42:43], 0, v[190:191]
	s_add_i32 m0, s16, 0xc000
	ds_read_b128 v[146:149], v219
	ds_read_b128 v[150:153], v219 offset:1024
	ds_read_b128 v[154:157], v219 offset:2048
	ds_read_b128 v[158:161], v219 offset:3072
	ds_read_b128 v[194:197], v219 offset:4096
	ds_read_b128 v[198:201], v219 offset:5120
	ds_read_b128 v[202:205], v219 offset:6144
	ds_read_b128 v[206:209], v219 offset:7168
	global_load_lds_dwordx4 v[176:177], off
	v_lshl_add_u64 v[176:177], s[42:43], 0, v[192:193]
	s_add_i32 m0, s16, 0xe000
	s_nop 0
	global_load_lds_dwordx4 v[176:177], off
	s_add_i32 s1, 0, 0x14000
	v_add_u32_e32 v168, s1, v217
	ds_read_b128 v[230:233], v168
	ds_read_b128 v[234:237], v168 offset:1024
	ds_read_b128 v[238:241], v168 offset:2048
	ds_read_b128 v[242:245], v168 offset:3072
	s_waitcnt vmcnt(8)
	s_waitcnt lgkmcnt(0)
	s_barrier
	s_setprio 0
	v_mfma_f32_16x16x32_bf16 v[126:129], v[130:133], v[146:149], 0
	v_mfma_f32_16x16x32_bf16 v[122:125], v[138:141], v[146:149], 0
	v_mfma_f32_16x16x32_bf16 v[118:121], v[130:133], v[154:157], 0
	v_mfma_f32_16x16x32_bf16 v[110:113], v[138:141], v[154:157], 0
	v_mfma_f32_16x16x32_bf16 v[102:105], v[130:133], v[194:197], 0
	v_mfma_f32_16x16x32_bf16 v[94:97], v[138:141], v[194:197], 0
	v_mfma_f32_16x16x32_bf16 v[86:89], v[130:133], v[202:205], 0
	v_mfma_f32_16x16x32_bf16 v[78:81], v[138:141], v[202:205], 0
	v_mfma_f32_16x16x32_bf16 v[126:129], v[134:137], v[150:153], v[126:129]
	v_mfma_f32_16x16x32_bf16 v[122:125], v[142:145], v[150:153], v[122:125]
	v_mfma_f32_16x16x32_bf16 v[118:121], v[134:137], v[158:161], v[118:121]
	v_mfma_f32_16x16x32_bf16 v[110:113], v[142:145], v[158:161], v[110:113]
	v_mfma_f32_16x16x32_bf16 v[102:105], v[134:137], v[198:201], v[102:105]
	v_mfma_f32_16x16x32_bf16 v[94:97], v[142:145], v[198:201], v[94:97]
	v_mfma_f32_16x16x32_bf16 v[86:89], v[134:137], v[206:209], v[86:89]
	v_mfma_f32_16x16x32_bf16 v[78:81], v[142:145], v[206:209], v[78:81]
	v_mfma_f32_16x16x32_bf16 v[114:117], v[230:233], v[146:149], 0
	v_mfma_f32_16x16x32_bf16 v[106:109], v[238:241], v[146:149], 0
	v_mfma_f32_16x16x32_bf16 v[98:101], v[230:233], v[154:157], 0
	v_mfma_f32_16x16x32_bf16 v[90:93], v[238:241], v[154:157], 0
	v_mfma_f32_16x16x32_bf16 v[82:85], v[230:233], v[194:197], 0
	v_mfma_f32_16x16x32_bf16 v[74:77], v[238:241], v[194:197], 0
	v_mfma_f32_16x16x32_bf16 v[70:73], v[230:233], v[202:205], 0
	v_mfma_f32_16x16x32_bf16 v[66:69], v[238:241], v[202:205], 0
	v_mfma_f32_16x16x32_bf16 v[114:117], v[234:237], v[150:153], v[114:117]
	v_mfma_f32_16x16x32_bf16 v[106:109], v[242:245], v[150:153], v[106:109]
	v_mfma_f32_16x16x32_bf16 v[98:101], v[234:237], v[158:161], v[98:101]
	v_mfma_f32_16x16x32_bf16 v[90:93], v[242:245], v[158:161], v[90:93]
	v_mfma_f32_16x16x32_bf16 v[82:85], v[234:237], v[198:201], v[82:85]
	v_mfma_f32_16x16x32_bf16 v[74:77], v[242:245], v[198:201], v[74:77]
	v_mfma_f32_16x16x32_bf16 v[70:73], v[234:237], v[206:209], v[70:73]
	v_mfma_f32_16x16x32_bf16 v[66:69], v[242:245], v[206:209], v[66:69]
	s_setprio 1
	s_barrier
	ds_read_b128 v[146:149], v219 offset:16384
	ds_read_b128 v[150:153], v219 offset:17408
	ds_read_b128 v[154:157], v219 offset:18432
	ds_read_b128 v[158:161], v219 offset:19456
	ds_read_b128 v[194:197], v219 offset:20480
	ds_read_b128 v[198:201], v219 offset:21504
	ds_read_b128 v[202:205], v219 offset:22528
	ds_read_b128 v[206:209], v219 offset:23552
	s_add_i32 s22, s23, s4
	v_lshl_add_u64 v[176:177], s[30:31], 0, v[0:1]
	s_mov_b32 m0, s22
	s_nop 0
	global_load_lds_dwordx4 v[176:177], off
	v_lshl_add_u64 v[220:221], s[30:31], 0, v[178:179]
	s_add_i32 m0, s22, 0x2000
	s_nop 0
	global_load_lds_dwordx4 v[220:221], off
	s_mov_b32 m0, s16
	v_lshl_add_u64 v[246:247], s[44:45], 0, v[182:183]
	global_load_lds_dwordx4 v[246:247], off
	v_lshl_add_u64 v[248:249], s[44:45], 0, v[180:181]
	s_mov_b32 m0, s17
	s_nop 0
	global_load_lds_dwordx4 v[248:249], off
	s_add_u32 s22, s30, 0x40000
	s_addc_u32 s23, s31, 0
	s_add_i32 s1, s1, s4
	s_mov_b32 m0, s1
	s_nop 0
	global_load_lds_dwordx4 v0, s[22:23]
	s_add_i32 m0, s1, 0x2000
	s_nop 0
	global_load_lds_dwordx4 v178, s[22:23]
	s_waitcnt vmcnt(8)
	s_waitcnt lgkmcnt(0)
	s_barrier
	s_setprio 0
	v_mfma_f32_16x16x32_bf16 v[62:65], v[130:133], v[146:149], 0
	v_mfma_f32_16x16x32_bf16 v[58:61], v[138:141], v[146:149], 0
	v_mfma_f32_16x16x32_bf16 v[54:57], v[130:133], v[154:157], 0
	v_mfma_f32_16x16x32_bf16 v[46:49], v[138:141], v[154:157], 0
	v_mfma_f32_16x16x32_bf16 v[38:41], v[130:133], v[194:197], 0
	v_mfma_f32_16x16x32_bf16 v[30:33], v[138:141], v[194:197], 0
	v_mfma_f32_16x16x32_bf16 v[22:25], v[130:133], v[202:205], 0
	v_mfma_f32_16x16x32_bf16 v[14:17], v[138:141], v[202:205], 0
	v_mfma_f32_16x16x32_bf16 v[62:65], v[134:137], v[150:153], v[62:65]
	v_mfma_f32_16x16x32_bf16 v[58:61], v[142:145], v[150:153], v[58:61]
	v_mfma_f32_16x16x32_bf16 v[54:57], v[134:137], v[158:161], v[54:57]
	v_mfma_f32_16x16x32_bf16 v[46:49], v[142:145], v[158:161], v[46:49]
	v_mfma_f32_16x16x32_bf16 v[38:41], v[134:137], v[198:201], v[38:41]
	v_mfma_f32_16x16x32_bf16 v[30:33], v[142:145], v[198:201], v[30:33]
	v_mfma_f32_16x16x32_bf16 v[22:25], v[134:137], v[206:209], v[22:25]
	v_mfma_f32_16x16x32_bf16 v[14:17], v[142:145], v[206:209], v[14:17]
	v_mfma_f32_16x16x32_bf16 v[50:53], v[230:233], v[146:149], 0
	v_mfma_f32_16x16x32_bf16 v[42:45], v[238:241], v[146:149], 0
	v_mfma_f32_16x16x32_bf16 v[34:37], v[230:233], v[154:157], 0
	v_mfma_f32_16x16x32_bf16 v[26:29], v[238:241], v[154:157], 0
	v_mfma_f32_16x16x32_bf16 v[18:21], v[230:233], v[194:197], 0
	v_mfma_f32_16x16x32_bf16 v[10:13], v[238:241], v[194:197], 0
	v_mfma_f32_16x16x32_bf16 v[6:9], v[230:233], v[202:205], 0
	v_mfma_f32_16x16x32_bf16 v[2:5], v[238:241], v[202:205], 0
	v_mfma_f32_16x16x32_bf16 v[50:53], v[234:237], v[150:153], v[50:53]
	v_mfma_f32_16x16x32_bf16 v[42:45], v[242:245], v[150:153], v[42:45]
	v_mfma_f32_16x16x32_bf16 v[34:37], v[234:237], v[158:161], v[34:37]
	v_mfma_f32_16x16x32_bf16 v[26:29], v[242:245], v[158:161], v[26:29]
	v_mfma_f32_16x16x32_bf16 v[18:21], v[234:237], v[198:201], v[18:21]
	v_mfma_f32_16x16x32_bf16 v[10:13], v[242:245], v[198:201], v[10:13]
	v_mfma_f32_16x16x32_bf16 v[6:9], v[234:237], v[206:209], v[6:9]
	v_mfma_f32_16x16x32_bf16 v[2:5], v[242:245], v[206:209], v[2:5]
	s_setprio 1
	s_barrier
	s_add_i32 s1, 0, 0x18000
	v_add_u32_e32 v142, s1, v217
	ds_read_b128 v[130:133], v142
	ds_read_b128 v[134:137], v142 offset:1024
	ds_read_b128 v[138:141], v142 offset:2048
	ds_read_b128 v[142:145], v142 offset:3072
	s_add_u32 s22, s44, 0x40000
	s_addc_u32 s23, s45, 0
	s_mov_b32 m0, s20
	v_lshl_add_u64 v[230:231], s[22:23], 0, v[182:183]
	ds_read_b128 v[146:149], v219 offset:32768
	ds_read_b128 v[150:153], v219 offset:33792
	ds_read_b128 v[154:157], v219 offset:34816
	ds_read_b128 v[158:161], v219 offset:35840
	ds_read_b128 v[194:197], v219 offset:36864
	ds_read_b128 v[198:201], v219 offset:37888
	ds_read_b128 v[202:205], v219 offset:38912
	ds_read_b128 v[206:209], v219 offset:39936
	global_load_lds_dwordx4 v[230:231], off
	v_lshl_add_u64 v[230:231], s[22:23], 0, v[180:181]
	s_mov_b32 m0, s21
	s_nop 0
	global_load_lds_dwordx4 v[230:231], off
	s_add_i32 s33, 0, 0x1c000
	v_add_u32_e32 v168, s33, v217
	ds_read_b128 v[230:233], v168
	ds_read_b128 v[234:237], v168 offset:1024
	ds_read_b128 v[238:241], v168 offset:2048
	ds_read_b128 v[242:245], v168 offset:3072
	s_waitcnt vmcnt(8)
	s_waitcnt lgkmcnt(0)
	s_barrier
	s_setprio 0
	v_mfma_f32_16x16x32_bf16 v[126:129], v[130:133], v[146:149], v[126:129]
	v_mfma_f32_16x16x32_bf16 v[122:125], v[138:141], v[146:149], v[122:125]
	v_mfma_f32_16x16x32_bf16 v[118:121], v[130:133], v[154:157], v[118:121]
	v_mfma_f32_16x16x32_bf16 v[110:113], v[138:141], v[154:157], v[110:113]
	v_mfma_f32_16x16x32_bf16 v[102:105], v[130:133], v[194:197], v[102:105]
	v_mfma_f32_16x16x32_bf16 v[94:97], v[138:141], v[194:197], v[94:97]
	v_mfma_f32_16x16x32_bf16 v[86:89], v[130:133], v[202:205], v[86:89]
	v_mfma_f32_16x16x32_bf16 v[78:81], v[138:141], v[202:205], v[78:81]
	v_mfma_f32_16x16x32_bf16 v[126:129], v[134:137], v[150:153], v[126:129]
	v_mfma_f32_16x16x32_bf16 v[122:125], v[142:145], v[150:153], v[122:125]
	v_mfma_f32_16x16x32_bf16 v[118:121], v[134:137], v[158:161], v[118:121]
	v_mfma_f32_16x16x32_bf16 v[110:113], v[142:145], v[158:161], v[110:113]
	v_mfma_f32_16x16x32_bf16 v[102:105], v[134:137], v[198:201], v[102:105]
	v_mfma_f32_16x16x32_bf16 v[94:97], v[142:145], v[198:201], v[94:97]
	v_mfma_f32_16x16x32_bf16 v[86:89], v[134:137], v[206:209], v[86:89]
	v_mfma_f32_16x16x32_bf16 v[78:81], v[142:145], v[206:209], v[78:81]
	v_mfma_f32_16x16x32_bf16 v[114:117], v[230:233], v[146:149], v[114:117]
	v_mfma_f32_16x16x32_bf16 v[106:109], v[238:241], v[146:149], v[106:109]
	v_mfma_f32_16x16x32_bf16 v[98:101], v[230:233], v[154:157], v[98:101]
	v_mfma_f32_16x16x32_bf16 v[90:93], v[238:241], v[154:157], v[90:93]
	v_mfma_f32_16x16x32_bf16 v[82:85], v[230:233], v[194:197], v[82:85]
	v_mfma_f32_16x16x32_bf16 v[74:77], v[238:241], v[194:197], v[74:77]
	v_mfma_f32_16x16x32_bf16 v[70:73], v[230:233], v[202:205], v[70:73]
	v_mfma_f32_16x16x32_bf16 v[66:69], v[238:241], v[202:205], v[66:69]
	v_mfma_f32_16x16x32_bf16 v[114:117], v[234:237], v[150:153], v[114:117]
	v_mfma_f32_16x16x32_bf16 v[106:109], v[242:245], v[150:153], v[106:109]
	v_mfma_f32_16x16x32_bf16 v[98:101], v[234:237], v[158:161], v[98:101]
	v_mfma_f32_16x16x32_bf16 v[90:93], v[242:245], v[158:161], v[90:93]
	v_mfma_f32_16x16x32_bf16 v[82:85], v[234:237], v[198:201], v[82:85]
	v_mfma_f32_16x16x32_bf16 v[74:77], v[242:245], v[198:201], v[74:77]
	v_mfma_f32_16x16x32_bf16 v[70:73], v[234:237], v[206:209], v[70:73]
	v_mfma_f32_16x16x32_bf16 v[66:69], v[242:245], v[206:209], v[66:69]
	s_setprio 1
	s_barrier
	ds_read_b128 v[146:149], v219 offset:49152
	ds_read_b128 v[150:153], v219 offset:50176
	ds_read_b128 v[154:157], v219 offset:51200
	ds_read_b128 v[158:161], v219 offset:52224
	ds_read_b128 v[194:197], v219 offset:53248
	ds_read_b128 v[198:201], v219 offset:54272
	ds_read_b128 v[202:205], v219 offset:55296
	ds_read_b128 v[206:209], v219 offset:56320
	s_add_i32 s1, s1, s4
	v_lshl_add_u64 v[176:177], v[176:177], 0, s[12:13]
	s_mov_b32 m0, s1
	s_nop 0
	global_load_lds_dwordx4 v[176:177], off
	v_lshl_add_u64 v[176:177], v[220:221], 0, s[12:13]
	s_add_i32 m0, s1, 0x2000
	s_nop 0
	global_load_lds_dwordx4 v[176:177], off
	s_mov_b32 m0, s34
	v_lshl_add_u64 v[176:177], v[246:247], 0, s[12:13]
	global_load_lds_dwordx4 v[176:177], off
	v_lshl_add_u64 v[176:177], v[248:249], 0, s[12:13]
	s_mov_b32 m0, s46
	s_nop 0
	global_load_lds_dwordx4 v[176:177], off
	s_add_u32 s22, s30, 0x40080
	s_addc_u32 s23, s31, 0
	s_add_i32 s1, s33, s4
	s_mov_b32 m0, s1
	s_nop 0
	global_load_lds_dwordx4 v0, s[22:23]
	s_add_i32 m0, s1, 0x2000
	s_nop 0
	global_load_lds_dwordx4 v178, s[22:23]
	s_waitcnt vmcnt(8)
	s_waitcnt lgkmcnt(0)
	s_barrier
	s_setprio 0
	v_mfma_f32_16x16x32_bf16 v[62:65], v[130:133], v[146:149], v[62:65]
	v_mfma_f32_16x16x32_bf16 v[58:61], v[138:141], v[146:149], v[58:61]
	v_mfma_f32_16x16x32_bf16 v[54:57], v[130:133], v[154:157], v[54:57]
	v_mfma_f32_16x16x32_bf16 v[46:49], v[138:141], v[154:157], v[46:49]
	v_mfma_f32_16x16x32_bf16 v[38:41], v[130:133], v[194:197], v[38:41]
	v_mfma_f32_16x16x32_bf16 v[30:33], v[138:141], v[194:197], v[30:33]
	v_mfma_f32_16x16x32_bf16 v[22:25], v[130:133], v[202:205], v[22:25]
	v_mfma_f32_16x16x32_bf16 v[14:17], v[138:141], v[202:205], v[14:17]
	v_mfma_f32_16x16x32_bf16 v[62:65], v[134:137], v[150:153], v[62:65]
	v_mfma_f32_16x16x32_bf16 v[58:61], v[142:145], v[150:153], v[58:61]
	v_mfma_f32_16x16x32_bf16 v[54:57], v[134:137], v[158:161], v[54:57]
	v_mfma_f32_16x16x32_bf16 v[46:49], v[142:145], v[158:161], v[46:49]
	v_mfma_f32_16x16x32_bf16 v[38:41], v[134:137], v[198:201], v[38:41]
	v_mfma_f32_16x16x32_bf16 v[30:33], v[142:145], v[198:201], v[30:33]
	v_mfma_f32_16x16x32_bf16 v[22:25], v[134:137], v[206:209], v[22:25]
	v_mfma_f32_16x16x32_bf16 v[14:17], v[142:145], v[206:209], v[14:17]
	v_mfma_f32_16x16x32_bf16 v[50:53], v[230:233], v[146:149], v[50:53]
	v_mfma_f32_16x16x32_bf16 v[42:45], v[238:241], v[146:149], v[42:45]
	v_mfma_f32_16x16x32_bf16 v[34:37], v[230:233], v[154:157], v[34:37]
	v_mfma_f32_16x16x32_bf16 v[26:29], v[238:241], v[154:157], v[26:29]
	v_mfma_f32_16x16x32_bf16 v[18:21], v[230:233], v[194:197], v[18:21]
	v_mfma_f32_16x16x32_bf16 v[10:13], v[238:241], v[194:197], v[10:13]
	v_mfma_f32_16x16x32_bf16 v[6:9], v[230:233], v[202:205], v[6:9]
	v_mfma_f32_16x16x32_bf16 v[2:5], v[238:241], v[202:205], v[2:5]
	v_mfma_f32_16x16x32_bf16 v[50:53], v[234:237], v[150:153], v[50:53]
	v_mfma_f32_16x16x32_bf16 v[42:45], v[242:245], v[150:153], v[42:45]
	v_mfma_f32_16x16x32_bf16 v[34:37], v[234:237], v[158:161], v[34:37]
	v_mfma_f32_16x16x32_bf16 v[26:29], v[242:245], v[158:161], v[26:29]
	v_mfma_f32_16x16x32_bf16 v[18:21], v[234:237], v[198:201], v[18:21]
	v_mfma_f32_16x16x32_bf16 v[10:13], v[242:245], v[198:201], v[10:13]
	v_mfma_f32_16x16x32_bf16 v[6:9], v[234:237], v[206:209], v[6:9]
	v_mfma_f32_16x16x32_bf16 v[2:5], v[242:245], v[206:209], v[2:5]
	s_setprio 1
	s_add_i32 s54, s54, 2
	s_add_u32 s42, s42, 0x100
	s_addc_u32 s43, s43, 0
	s_add_u32 s52, s52, 0x100
	s_addc_u32 s53, s53, 0
	s_cmp_gt_u32 s54, 13
	s_barrier
.LBB0_289:
	s_add_u32 s1, s42, 0xfffc0080
	s_addc_u32 s22, s43, -1
	s_add_i32 s23, 0, 0x10000
	v_add_u32_e32 v142, s23, v217
	ds_read_b128 v[130:133], v142
	ds_read_b128 v[134:137], v142 offset:1024
	ds_read_b128 v[138:141], v142 offset:2048
	ds_read_b128 v[142:145], v142 offset:3072
	s_cmp_eq_u32 s54, 12
	s_cselect_b32 s45, s27, s22
	s_cselect_b32 s44, s50, s1
	s_cselect_b32 s31, s7, s53
	s_cselect_b32 s30, s51, s52
	v_lshl_add_u64 v[176:177], s[42:43], 0, v[190:191]
	s_add_i32 m0, s16, 0xc000
	ds_read_b128 v[146:149], v219
	ds_read_b128 v[150:153], v219 offset:1024
	ds_read_b128 v[154:157], v219 offset:2048
	ds_read_b128 v[158:161], v219 offset:3072
	ds_read_b128 v[194:197], v219 offset:4096
	ds_read_b128 v[198:201], v219 offset:5120
	ds_read_b128 v[202:205], v219 offset:6144
	ds_read_b128 v[206:209], v219 offset:7168
	global_load_lds_dwordx4 v[176:177], off
	v_lshl_add_u64 v[176:177], s[42:43], 0, v[192:193]
	s_add_i32 m0, s16, 0xe000
	s_nop 0
	global_load_lds_dwordx4 v[176:177], off
	s_add_i32 s1, 0, 0x14000
	v_add_u32_e32 v168, s1, v217
	ds_read_b128 v[230:233], v168
	ds_read_b128 v[234:237], v168 offset:1024
	ds_read_b128 v[238:241], v168 offset:2048
	ds_read_b128 v[242:245], v168 offset:3072
	s_waitcnt vmcnt(8)
	s_waitcnt lgkmcnt(0)
	s_barrier
	s_setprio 0
	v_mfma_f32_16x16x32_bf16 v[126:129], v[130:133], v[146:149], v[126:129]
	v_mfma_f32_16x16x32_bf16 v[122:125], v[138:141], v[146:149], v[122:125]
	v_mfma_f32_16x16x32_bf16 v[118:121], v[130:133], v[154:157], v[118:121]
	v_mfma_f32_16x16x32_bf16 v[110:113], v[138:141], v[154:157], v[110:113]
	v_mfma_f32_16x16x32_bf16 v[102:105], v[130:133], v[194:197], v[102:105]
	v_mfma_f32_16x16x32_bf16 v[94:97], v[138:141], v[194:197], v[94:97]
	v_mfma_f32_16x16x32_bf16 v[86:89], v[130:133], v[202:205], v[86:89]
	v_mfma_f32_16x16x32_bf16 v[78:81], v[138:141], v[202:205], v[78:81]
	v_mfma_f32_16x16x32_bf16 v[126:129], v[134:137], v[150:153], v[126:129]
	v_mfma_f32_16x16x32_bf16 v[122:125], v[142:145], v[150:153], v[122:125]
	v_mfma_f32_16x16x32_bf16 v[118:121], v[134:137], v[158:161], v[118:121]
	v_mfma_f32_16x16x32_bf16 v[110:113], v[142:145], v[158:161], v[110:113]
	v_mfma_f32_16x16x32_bf16 v[102:105], v[134:137], v[198:201], v[102:105]
	v_mfma_f32_16x16x32_bf16 v[94:97], v[142:145], v[198:201], v[94:97]
	v_mfma_f32_16x16x32_bf16 v[86:89], v[134:137], v[206:209], v[86:89]
	v_mfma_f32_16x16x32_bf16 v[78:81], v[142:145], v[206:209], v[78:81]
	v_mfma_f32_16x16x32_bf16 v[114:117], v[230:233], v[146:149], v[114:117]
	v_mfma_f32_16x16x32_bf16 v[106:109], v[238:241], v[146:149], v[106:109]
	v_mfma_f32_16x16x32_bf16 v[98:101], v[230:233], v[154:157], v[98:101]
	v_mfma_f32_16x16x32_bf16 v[90:93], v[238:241], v[154:157], v[90:93]
	v_mfma_f32_16x16x32_bf16 v[82:85], v[230:233], v[194:197], v[82:85]
	v_mfma_f32_16x16x32_bf16 v[74:77], v[238:241], v[194:197], v[74:77]
	v_mfma_f32_16x16x32_bf16 v[70:73], v[230:233], v[202:205], v[70:73]
	v_mfma_f32_16x16x32_bf16 v[66:69], v[238:241], v[202:205], v[66:69]
	v_mfma_f32_16x16x32_bf16 v[114:117], v[234:237], v[150:153], v[114:117]
	v_mfma_f32_16x16x32_bf16 v[106:109], v[242:245], v[150:153], v[106:109]
	v_mfma_f32_16x16x32_bf16 v[98:101], v[234:237], v[158:161], v[98:101]
	v_mfma_f32_16x16x32_bf16 v[90:93], v[242:245], v[158:161], v[90:93]
	v_mfma_f32_16x16x32_bf16 v[82:85], v[234:237], v[198:201], v[82:85]
	v_mfma_f32_16x16x32_bf16 v[74:77], v[242:245], v[198:201], v[74:77]
	v_mfma_f32_16x16x32_bf16 v[70:73], v[234:237], v[206:209], v[70:73]
	v_mfma_f32_16x16x32_bf16 v[66:69], v[242:245], v[206:209], v[66:69]
	s_setprio 1
	s_barrier
	ds_read_b128 v[146:149], v219 offset:16384
	ds_read_b128 v[150:153], v219 offset:17408
	ds_read_b128 v[154:157], v219 offset:18432
	ds_read_b128 v[158:161], v219 offset:19456
	ds_read_b128 v[194:197], v219 offset:20480
	ds_read_b128 v[198:201], v219 offset:21504
	ds_read_b128 v[202:205], v219 offset:22528
	ds_read_b128 v[206:209], v219 offset:23552
	s_add_i32 s22, s23, s4
	v_lshl_add_u64 v[176:177], s[30:31], 0, v[0:1]
	s_mov_b32 m0, s22
	s_nop 0
	global_load_lds_dwordx4 v[176:177], off
	v_lshl_add_u64 v[220:221], s[30:31], 0, v[178:179]
	s_add_i32 m0, s22, 0x2000
	s_nop 0
	global_load_lds_dwordx4 v[220:221], off
	s_mov_b32 m0, s16
	v_lshl_add_u64 v[246:247], s[44:45], 0, v[182:183]
	global_load_lds_dwordx4 v[246:247], off
	v_lshl_add_u64 v[248:249], s[44:45], 0, v[180:181]
	s_mov_b32 m0, s17
	s_nop 0
	global_load_lds_dwordx4 v[248:249], off
	s_add_u32 s22, s30, 0x40000
	s_addc_u32 s23, s31, 0
	s_add_i32 s1, s1, s4
	s_mov_b32 m0, s1
	s_nop 0
	global_load_lds_dwordx4 v0, s[22:23]
	s_add_i32 m0, s1, 0x2000
	s_nop 0
	global_load_lds_dwordx4 v178, s[22:23]
	s_waitcnt vmcnt(8)
	s_waitcnt lgkmcnt(0)
	s_barrier
	s_setprio 0
	v_mfma_f32_16x16x32_bf16 v[62:65], v[130:133], v[146:149], v[62:65]
	v_mfma_f32_16x16x32_bf16 v[58:61], v[138:141], v[146:149], v[58:61]
	v_mfma_f32_16x16x32_bf16 v[54:57], v[130:133], v[154:157], v[54:57]
	v_mfma_f32_16x16x32_bf16 v[46:49], v[138:141], v[154:157], v[46:49]
	v_mfma_f32_16x16x32_bf16 v[38:41], v[130:133], v[194:197], v[38:41]
	v_mfma_f32_16x16x32_bf16 v[30:33], v[138:141], v[194:197], v[30:33]
	v_mfma_f32_16x16x32_bf16 v[22:25], v[130:133], v[202:205], v[22:25]
	v_mfma_f32_16x16x32_bf16 v[14:17], v[138:141], v[202:205], v[14:17]
	v_mfma_f32_16x16x32_bf16 v[62:65], v[134:137], v[150:153], v[62:65]
	v_mfma_f32_16x16x32_bf16 v[58:61], v[142:145], v[150:153], v[58:61]
	v_mfma_f32_16x16x32_bf16 v[54:57], v[134:137], v[158:161], v[54:57]
	v_mfma_f32_16x16x32_bf16 v[46:49], v[142:145], v[158:161], v[46:49]
	v_mfma_f32_16x16x32_bf16 v[38:41], v[134:137], v[198:201], v[38:41]
	v_mfma_f32_16x16x32_bf16 v[30:33], v[142:145], v[198:201], v[30:33]
	v_mfma_f32_16x16x32_bf16 v[22:25], v[134:137], v[206:209], v[22:25]
	v_mfma_f32_16x16x32_bf16 v[14:17], v[142:145], v[206:209], v[14:17]
	v_mfma_f32_16x16x32_bf16 v[50:53], v[230:233], v[146:149], v[50:53]
	v_mfma_f32_16x16x32_bf16 v[42:45], v[238:241], v[146:149], v[42:45]
	v_mfma_f32_16x16x32_bf16 v[34:37], v[230:233], v[154:157], v[34:37]
	v_mfma_f32_16x16x32_bf16 v[26:29], v[238:241], v[154:157], v[26:29]
	v_mfma_f32_16x16x32_bf16 v[18:21], v[230:233], v[194:197], v[18:21]
	v_mfma_f32_16x16x32_bf16 v[10:13], v[238:241], v[194:197], v[10:13]
	v_mfma_f32_16x16x32_bf16 v[6:9], v[230:233], v[202:205], v[6:9]
	v_mfma_f32_16x16x32_bf16 v[2:5], v[238:241], v[202:205], v[2:5]
	v_mfma_f32_16x16x32_bf16 v[50:53], v[234:237], v[150:153], v[50:53]
	v_mfma_f32_16x16x32_bf16 v[42:45], v[242:245], v[150:153], v[42:45]
	v_mfma_f32_16x16x32_bf16 v[34:37], v[234:237], v[158:161], v[34:37]
	v_mfma_f32_16x16x32_bf16 v[26:29], v[242:245], v[158:161], v[26:29]
	v_mfma_f32_16x16x32_bf16 v[18:21], v[234:237], v[198:201], v[18:21]
	v_mfma_f32_16x16x32_bf16 v[10:13], v[242:245], v[198:201], v[10:13]
	v_mfma_f32_16x16x32_bf16 v[6:9], v[234:237], v[206:209], v[6:9]
	v_mfma_f32_16x16x32_bf16 v[2:5], v[242:245], v[206:209], v[2:5]
	s_setprio 1
	s_barrier
	s_add_i32 s1, 0, 0x18000
	v_add_u32_e32 v142, s1, v217
	ds_read_b128 v[130:133], v142
	ds_read_b128 v[134:137], v142 offset:1024
	ds_read_b128 v[138:141], v142 offset:2048
	ds_read_b128 v[142:145], v142 offset:3072
	s_add_u32 s22, s44, 0x40000
	s_addc_u32 s23, s45, 0
	s_mov_b32 m0, s20
	v_lshl_add_u64 v[230:231], s[22:23], 0, v[182:183]
	ds_read_b128 v[146:149], v219 offset:32768
	ds_read_b128 v[150:153], v219 offset:33792
	ds_read_b128 v[154:157], v219 offset:34816
	ds_read_b128 v[158:161], v219 offset:35840
	ds_read_b128 v[194:197], v219 offset:36864
	ds_read_b128 v[198:201], v219 offset:37888
	ds_read_b128 v[202:205], v219 offset:38912
	ds_read_b128 v[206:209], v219 offset:39936
	global_load_lds_dwordx4 v[230:231], off
	v_lshl_add_u64 v[230:231], s[22:23], 0, v[180:181]
	s_mov_b32 m0, s21
	s_nop 0
	global_load_lds_dwordx4 v[230:231], off
	s_add_i32 s33, 0, 0x1c000
	v_add_u32_e32 v168, s33, v217
	ds_read_b128 v[230:233], v168
	ds_read_b128 v[234:237], v168 offset:1024
	ds_read_b128 v[238:241], v168 offset:2048
	ds_read_b128 v[242:245], v168 offset:3072
	s_waitcnt vmcnt(8)
	s_waitcnt lgkmcnt(0)
	s_barrier
	s_setprio 0
	v_mfma_f32_16x16x32_bf16 v[126:129], v[130:133], v[146:149], v[126:129]
	v_mfma_f32_16x16x32_bf16 v[122:125], v[138:141], v[146:149], v[122:125]
	v_mfma_f32_16x16x32_bf16 v[118:121], v[130:133], v[154:157], v[118:121]
	v_mfma_f32_16x16x32_bf16 v[110:113], v[138:141], v[154:157], v[110:113]
	v_mfma_f32_16x16x32_bf16 v[102:105], v[130:133], v[194:197], v[102:105]
	v_mfma_f32_16x16x32_bf16 v[94:97], v[138:141], v[194:197], v[94:97]
	v_mfma_f32_16x16x32_bf16 v[86:89], v[130:133], v[202:205], v[86:89]
	v_mfma_f32_16x16x32_bf16 v[78:81], v[138:141], v[202:205], v[78:81]
	v_mfma_f32_16x16x32_bf16 v[126:129], v[134:137], v[150:153], v[126:129]
	v_mfma_f32_16x16x32_bf16 v[122:125], v[142:145], v[150:153], v[122:125]
	v_mfma_f32_16x16x32_bf16 v[118:121], v[134:137], v[158:161], v[118:121]
	v_mfma_f32_16x16x32_bf16 v[110:113], v[142:145], v[158:161], v[110:113]
	v_mfma_f32_16x16x32_bf16 v[102:105], v[134:137], v[198:201], v[102:105]
	v_mfma_f32_16x16x32_bf16 v[94:97], v[142:145], v[198:201], v[94:97]
	v_mfma_f32_16x16x32_bf16 v[86:89], v[134:137], v[206:209], v[86:89]
	v_mfma_f32_16x16x32_bf16 v[78:81], v[142:145], v[206:209], v[78:81]
	v_mfma_f32_16x16x32_bf16 v[114:117], v[230:233], v[146:149], v[114:117]
	v_mfma_f32_16x16x32_bf16 v[106:109], v[238:241], v[146:149], v[106:109]
	v_mfma_f32_16x16x32_bf16 v[98:101], v[230:233], v[154:157], v[98:101]
	v_mfma_f32_16x16x32_bf16 v[90:93], v[238:241], v[154:157], v[90:93]
	v_mfma_f32_16x16x32_bf16 v[82:85], v[230:233], v[194:197], v[82:85]
	v_mfma_f32_16x16x32_bf16 v[74:77], v[238:241], v[194:197], v[74:77]
	v_mfma_f32_16x16x32_bf16 v[70:73], v[230:233], v[202:205], v[70:73]
	v_mfma_f32_16x16x32_bf16 v[66:69], v[238:241], v[202:205], v[66:69]
	v_mfma_f32_16x16x32_bf16 v[114:117], v[234:237], v[150:153], v[114:117]
	v_mfma_f32_16x16x32_bf16 v[106:109], v[242:245], v[150:153], v[106:109]
	v_mfma_f32_16x16x32_bf16 v[98:101], v[234:237], v[158:161], v[98:101]
	v_mfma_f32_16x16x32_bf16 v[90:93], v[242:245], v[158:161], v[90:93]
	v_mfma_f32_16x16x32_bf16 v[82:85], v[234:237], v[198:201], v[82:85]
	v_mfma_f32_16x16x32_bf16 v[74:77], v[242:245], v[198:201], v[74:77]
	v_mfma_f32_16x16x32_bf16 v[70:73], v[234:237], v[206:209], v[70:73]
	v_mfma_f32_16x16x32_bf16 v[66:69], v[242:245], v[206:209], v[66:69]
	s_setprio 1
	s_barrier
	ds_read_b128 v[146:149], v219 offset:49152
	ds_read_b128 v[150:153], v219 offset:50176
	ds_read_b128 v[154:157], v219 offset:51200
	ds_read_b128 v[158:161], v219 offset:52224
	ds_read_b128 v[194:197], v219 offset:53248
	ds_read_b128 v[198:201], v219 offset:54272
	ds_read_b128 v[202:205], v219 offset:55296
	ds_read_b128 v[206:209], v219 offset:56320
	s_add_i32 s1, s1, s4
	v_lshl_add_u64 v[176:177], v[176:177], 0, s[12:13]
	s_mov_b32 m0, s1
	s_nop 0
	global_load_lds_dwordx4 v[176:177], off
	v_lshl_add_u64 v[176:177], v[220:221], 0, s[12:13]
	s_add_i32 m0, s1, 0x2000
	s_nop 0
	global_load_lds_dwordx4 v[176:177], off
	s_mov_b32 m0, s34
	v_lshl_add_u64 v[176:177], v[246:247], 0, s[12:13]
	global_load_lds_dwordx4 v[176:177], off
	v_lshl_add_u64 v[176:177], v[248:249], 0, s[12:13]
	s_mov_b32 m0, s46
	s_nop 0
	global_load_lds_dwordx4 v[176:177], off
	s_add_u32 s22, s30, 0x40080
	s_addc_u32 s23, s31, 0
	s_add_i32 s1, s33, s4
	s_mov_b32 m0, s1
	s_nop 0
	global_load_lds_dwordx4 v0, s[22:23]
	s_add_i32 m0, s1, 0x2000
	s_nop 0
	global_load_lds_dwordx4 v178, s[22:23]
	s_waitcnt vmcnt(8)
	s_waitcnt lgkmcnt(0)
	s_barrier
	s_setprio 0
	v_mfma_f32_16x16x32_bf16 v[62:65], v[130:133], v[146:149], v[62:65]
	v_mfma_f32_16x16x32_bf16 v[58:61], v[138:141], v[146:149], v[58:61]
	v_mfma_f32_16x16x32_bf16 v[54:57], v[130:133], v[154:157], v[54:57]
	v_mfma_f32_16x16x32_bf16 v[46:49], v[138:141], v[154:157], v[46:49]
	v_mfma_f32_16x16x32_bf16 v[38:41], v[130:133], v[194:197], v[38:41]
	v_mfma_f32_16x16x32_bf16 v[30:33], v[138:141], v[194:197], v[30:33]
	v_mfma_f32_16x16x32_bf16 v[22:25], v[130:133], v[202:205], v[22:25]
	v_mfma_f32_16x16x32_bf16 v[14:17], v[138:141], v[202:205], v[14:17]
	v_mfma_f32_16x16x32_bf16 v[62:65], v[134:137], v[150:153], v[62:65]
	v_mfma_f32_16x16x32_bf16 v[58:61], v[142:145], v[150:153], v[58:61]
	v_mfma_f32_16x16x32_bf16 v[54:57], v[134:137], v[158:161], v[54:57]
	v_mfma_f32_16x16x32_bf16 v[46:49], v[142:145], v[158:161], v[46:49]
	v_mfma_f32_16x16x32_bf16 v[38:41], v[134:137], v[198:201], v[38:41]
	v_mfma_f32_16x16x32_bf16 v[30:33], v[142:145], v[198:201], v[30:33]
	v_mfma_f32_16x16x32_bf16 v[22:25], v[134:137], v[206:209], v[22:25]
	v_mfma_f32_16x16x32_bf16 v[14:17], v[142:145], v[206:209], v[14:17]
	v_mfma_f32_16x16x32_bf16 v[50:53], v[230:233], v[146:149], v[50:53]
	v_mfma_f32_16x16x32_bf16 v[42:45], v[238:241], v[146:149], v[42:45]
	v_mfma_f32_16x16x32_bf16 v[34:37], v[230:233], v[154:157], v[34:37]
	v_mfma_f32_16x16x32_bf16 v[26:29], v[238:241], v[154:157], v[26:29]
	v_mfma_f32_16x16x32_bf16 v[18:21], v[230:233], v[194:197], v[18:21]
	v_mfma_f32_16x16x32_bf16 v[10:13], v[238:241], v[194:197], v[10:13]
	v_mfma_f32_16x16x32_bf16 v[6:9], v[230:233], v[202:205], v[6:9]
	v_mfma_f32_16x16x32_bf16 v[2:5], v[238:241], v[202:205], v[2:5]
	v_mfma_f32_16x16x32_bf16 v[50:53], v[234:237], v[150:153], v[50:53]
	v_mfma_f32_16x16x32_bf16 v[42:45], v[242:245], v[150:153], v[42:45]
	v_mfma_f32_16x16x32_bf16 v[34:37], v[234:237], v[158:161], v[34:37]
	v_mfma_f32_16x16x32_bf16 v[26:29], v[242:245], v[158:161], v[26:29]
	v_mfma_f32_16x16x32_bf16 v[18:21], v[234:237], v[198:201], v[18:21]
	v_mfma_f32_16x16x32_bf16 v[10:13], v[242:245], v[198:201], v[10:13]
	v_mfma_f32_16x16x32_bf16 v[6:9], v[234:237], v[206:209], v[6:9]
	v_mfma_f32_16x16x32_bf16 v[2:5], v[242:245], v[206:209], v[2:5]
	s_setprio 1
	s_add_i32 s54, s54, 2
	s_add_u32 s42, s42, 0x100
	s_addc_u32 s43, s43, 0
	s_add_u32 s52, s52, 0x100
	s_addc_u32 s53, s53, 0
	s_cmp_gt_u32 s54, 13
	s_barrier
	s_cbranch_scc0 .LBB0_289
	s_cmpk_gt_u32 s0, 0xff
	s_cbranch_scc1 .Lrs_proj0_post
	s_barrier

.Lrs_proj1_pre:
	s_add_u32 s1, s28, 0xfffc0080
	s_addc_u32 s22, s29, -1
	s_add_i32 s23, 0, 0x10000
	v_add_u32_e32 v158, s23, v181
	ds_read_b128 v[130:133], v158
	ds_read_b128 v[134:137], v158 offset:1024
	ds_read_b128 v[154:157], v158 offset:2048
	ds_read_b128 v[186:189], v158 offset:3072
	s_cmp_eq_u32 s44, 12
	s_cselect_b32 s43, s17, s22
	s_cselect_b32 s42, s20, s1
	s_cselect_b32 s31, s9, s34
	s_cselect_b32 s30, s21, s25
	v_lshl_add_u64 v[160:161], s[28:29], 0, v[150:151]
	s_add_i32 m0, s49, 0xc000
	ds_read_b128 v[190:193], v185
	ds_read_b128 v[194:197], v185 offset:1024
	ds_read_b128 v[198:201], v185 offset:2048
	ds_read_b128 v[202:205], v185 offset:3072
	ds_read_b128 v[206:209], v185 offset:4096
	ds_read_b128 v[216:219], v185 offset:5120
	ds_read_b128 v[230:233], v185 offset:6144
	ds_read_b128 v[234:237], v185 offset:7168
	global_load_lds_dwordx4 v[160:161], off
	v_lshl_add_u64 v[160:161], s[28:29], 0, v[152:153]
	s_add_i32 m0, s49, 0xe000
	s_nop 0
	global_load_lds_dwordx4 v[160:161], off
	s_add_i32 s1, 0, 0x14000
	v_add_u32_e32 v158, s1, v181
	ds_read_b128 v[238:241], v158
	ds_read_b128 v[242:245], v158 offset:1024
	ds_read_b128 v[246:249], v158 offset:2048
	ds_read_b128 v[176:179], v158 offset:3072
	s_waitcnt vmcnt(8)
	s_waitcnt lgkmcnt(0)
	s_barrier
	s_setprio 0
	v_mfma_f32_16x16x32_bf16 v[126:129], v[130:133], v[190:193], 0
	v_mfma_f32_16x16x32_bf16 v[122:125], v[154:157], v[190:193], 0
	v_mfma_f32_16x16x32_bf16 v[110:113], v[130:133], v[198:201], 0
	v_mfma_f32_16x16x32_bf16 v[106:109], v[154:157], v[198:201], 0
	v_mfma_f32_16x16x32_bf16 v[94:97], v[130:133], v[206:209], 0
	v_mfma_f32_16x16x32_bf16 v[90:93], v[154:157], v[206:209], 0
	v_mfma_f32_16x16x32_bf16 v[78:81], v[130:133], v[230:233], 0
	v_mfma_f32_16x16x32_bf16 v[74:77], v[154:157], v[230:233], 0
	v_mfma_f32_16x16x32_bf16 v[126:129], v[134:137], v[194:197], v[126:129]
	v_mfma_f32_16x16x32_bf16 v[122:125], v[186:189], v[194:197], v[122:125]
	v_mfma_f32_16x16x32_bf16 v[110:113], v[134:137], v[202:205], v[110:113]
	v_mfma_f32_16x16x32_bf16 v[106:109], v[186:189], v[202:205], v[106:109]
	v_mfma_f32_16x16x32_bf16 v[94:97], v[134:137], v[216:219], v[94:97]
	v_mfma_f32_16x16x32_bf16 v[90:93], v[186:189], v[216:219], v[90:93]
	v_mfma_f32_16x16x32_bf16 v[78:81], v[134:137], v[234:237], v[78:81]
	v_mfma_f32_16x16x32_bf16 v[74:77], v[186:189], v[234:237], v[74:77]
	v_mfma_f32_16x16x32_bf16 v[118:121], v[238:241], v[190:193], 0
	v_mfma_f32_16x16x32_bf16 v[114:117], v[246:249], v[190:193], 0
	v_mfma_f32_16x16x32_bf16 v[102:105], v[238:241], v[198:201], 0
	v_mfma_f32_16x16x32_bf16 v[98:101], v[246:249], v[198:201], 0
	v_mfma_f32_16x16x32_bf16 v[86:89], v[238:241], v[206:209], 0
	v_mfma_f32_16x16x32_bf16 v[82:85], v[246:249], v[206:209], 0
	v_mfma_f32_16x16x32_bf16 v[70:73], v[238:241], v[230:233], 0
	v_mfma_f32_16x16x32_bf16 v[66:69], v[246:249], v[230:233], 0
	v_mfma_f32_16x16x32_bf16 v[118:121], v[242:245], v[194:197], v[118:121]
	v_mfma_f32_16x16x32_bf16 v[114:117], v[176:179], v[194:197], v[114:117]
	v_mfma_f32_16x16x32_bf16 v[102:105], v[242:245], v[202:205], v[102:105]
	v_mfma_f32_16x16x32_bf16 v[98:101], v[176:179], v[202:205], v[98:101]
	v_mfma_f32_16x16x32_bf16 v[86:89], v[242:245], v[216:219], v[86:89]
	v_mfma_f32_16x16x32_bf16 v[82:85], v[176:179], v[216:219], v[82:85]
	v_mfma_f32_16x16x32_bf16 v[70:73], v[242:245], v[234:237], v[70:73]
	v_mfma_f32_16x16x32_bf16 v[66:69], v[176:179], v[234:237], v[66:69]
	s_setprio 1
	s_barrier
	ds_read_b128 v[190:193], v185 offset:16384
	ds_read_b128 v[194:197], v185 offset:17408
	ds_read_b128 v[198:201], v185 offset:18432
	ds_read_b128 v[202:205], v185 offset:19456
	ds_read_b128 v[206:209], v185 offset:20480
	ds_read_b128 v[216:219], v185 offset:21504
	ds_read_b128 v[230:233], v185 offset:22528
	ds_read_b128 v[234:237], v185 offset:23552
	s_add_i32 s22, s23, s48
	v_lshl_add_u64 v[160:161], s[30:31], 0, v[0:1]
	s_mov_b32 m0, s22
	s_nop 0
	global_load_lds_dwordx4 v[160:161], off
	v_lshl_add_u64 v[220:221], s[30:31], 0, v[138:139]
	s_add_i32 m0, s22, 0x2000
	s_nop 0
	global_load_lds_dwordx4 v[220:221], off
	s_mov_b32 m0, s49
	v_lshl_add_u64 v[250:251], s[42:43], 0, v[142:143]
	global_load_lds_dwordx4 v[250:251], off
	v_lshl_add_u64 v[168:169], s[42:43], 0, v[140:141]
	s_mov_b32 m0, s50
	s_nop 0
	global_load_lds_dwordx4 v[168:169], off
	s_add_u32 s22, s30, 0x40000
	s_addc_u32 s23, s31, 0
	s_add_i32 s1, s1, s48
	s_mov_b32 m0, s1
	s_nop 0
	global_load_lds_dwordx4 v0, s[22:23]
	s_add_i32 m0, s1, 0x2000
	s_nop 0
	global_load_lds_dwordx4 v138, s[22:23]
	s_waitcnt vmcnt(8)
	s_waitcnt lgkmcnt(0)
	s_barrier
	s_setprio 0
	v_mfma_f32_16x16x32_bf16 v[62:65], v[130:133], v[190:193], 0
	v_mfma_f32_16x16x32_bf16 v[58:61], v[154:157], v[190:193], 0
	v_mfma_f32_16x16x32_bf16 v[46:49], v[130:133], v[198:201], 0
	v_mfma_f32_16x16x32_bf16 v[42:45], v[154:157], v[198:201], 0
	v_mfma_f32_16x16x32_bf16 v[30:33], v[130:133], v[206:209], 0
	v_mfma_f32_16x16x32_bf16 v[26:29], v[154:157], v[206:209], 0
	v_mfma_f32_16x16x32_bf16 v[14:17], v[130:133], v[230:233], 0
	v_mfma_f32_16x16x32_bf16 v[10:13], v[154:157], v[230:233], 0
	v_mfma_f32_16x16x32_bf16 v[62:65], v[134:137], v[194:197], v[62:65]
	v_mfma_f32_16x16x32_bf16 v[58:61], v[186:189], v[194:197], v[58:61]
	v_mfma_f32_16x16x32_bf16 v[46:49], v[134:137], v[202:205], v[46:49]
	v_mfma_f32_16x16x32_bf16 v[42:45], v[186:189], v[202:205], v[42:45]
	v_mfma_f32_16x16x32_bf16 v[30:33], v[134:137], v[216:219], v[30:33]
	v_mfma_f32_16x16x32_bf16 v[26:29], v[186:189], v[216:219], v[26:29]
	v_mfma_f32_16x16x32_bf16 v[14:17], v[134:137], v[234:237], v[14:17]
	v_mfma_f32_16x16x32_bf16 v[10:13], v[186:189], v[234:237], v[10:13]
	v_mfma_f32_16x16x32_bf16 v[54:57], v[238:241], v[190:193], 0
	v_mfma_f32_16x16x32_bf16 v[50:53], v[246:249], v[190:193], 0
	v_mfma_f32_16x16x32_bf16 v[38:41], v[238:241], v[198:201], 0
	v_mfma_f32_16x16x32_bf16 v[34:37], v[246:249], v[198:201], 0
	v_mfma_f32_16x16x32_bf16 v[22:25], v[238:241], v[206:209], 0
	v_mfma_f32_16x16x32_bf16 v[18:21], v[246:249], v[206:209], 0
	v_mfma_f32_16x16x32_bf16 v[6:9], v[238:241], v[230:233], 0
	v_mfma_f32_16x16x32_bf16 v[2:5], v[246:249], v[230:233], 0
	v_mfma_f32_16x16x32_bf16 v[54:57], v[242:245], v[194:197], v[54:57]
	v_mfma_f32_16x16x32_bf16 v[50:53], v[176:179], v[194:197], v[50:53]
	v_mfma_f32_16x16x32_bf16 v[38:41], v[242:245], v[202:205], v[38:41]
	v_mfma_f32_16x16x32_bf16 v[34:37], v[176:179], v[202:205], v[34:37]
	v_mfma_f32_16x16x32_bf16 v[22:25], v[242:245], v[216:219], v[22:25]
	v_mfma_f32_16x16x32_bf16 v[18:21], v[176:179], v[216:219], v[18:21]
	v_mfma_f32_16x16x32_bf16 v[6:9], v[242:245], v[234:237], v[6:9]
	v_mfma_f32_16x16x32_bf16 v[2:5], v[176:179], v[234:237], v[2:5]
	s_setprio 1
	s_barrier
	s_add_i32 s1, 0, 0x18000
	v_add_u32_e32 v158, s1, v181
	ds_read_b128 v[130:133], v158
	ds_read_b128 v[134:137], v158 offset:1024
	ds_read_b128 v[154:157], v158 offset:2048
	ds_read_b128 v[176:179], v158 offset:3072
	s_add_u32 s22, s42, 0x40000
	s_addc_u32 s23, s43, 0
	s_mov_b32 m0, s51
	v_lshl_add_u64 v[234:235], s[22:23], 0, v[142:143]
	ds_read_b128 v[186:189], v185 offset:32768
	ds_read_b128 v[190:193], v185 offset:33792
	ds_read_b128 v[194:197], v185 offset:34816
	ds_read_b128 v[198:201], v185 offset:35840
	ds_read_b128 v[202:205], v185 offset:36864
	ds_read_b128 v[206:209], v185 offset:37888
	ds_read_b128 v[216:219], v185 offset:38912
	ds_read_b128 v[230:233], v185 offset:39936
	global_load_lds_dwordx4 v[234:235], off
	v_lshl_add_u64 v[234:235], s[22:23], 0, v[140:141]
	s_mov_b32 m0, s52
	s_nop 0
	global_load_lds_dwordx4 v[234:235], off
	s_add_i32 s33, 0, 0x1c000
	v_add_u32_e32 v158, s33, v181
	ds_read_b128 v[234:237], v158
	ds_read_b128 v[238:241], v158 offset:1024
	ds_read_b128 v[242:245], v158 offset:2048
	ds_read_b128 v[246:249], v158 offset:3072
	s_waitcnt vmcnt(8)
	s_waitcnt lgkmcnt(0)
	s_barrier
	s_setprio 0
	v_mfma_f32_16x16x32_bf16 v[126:129], v[130:133], v[186:189], v[126:129]
	v_mfma_f32_16x16x32_bf16 v[122:125], v[154:157], v[186:189], v[122:125]
	v_mfma_f32_16x16x32_bf16 v[110:113], v[130:133], v[194:197], v[110:113]
	v_mfma_f32_16x16x32_bf16 v[106:109], v[154:157], v[194:197], v[106:109]
	v_mfma_f32_16x16x32_bf16 v[94:97], v[130:133], v[202:205], v[94:97]
	v_mfma_f32_16x16x32_bf16 v[90:93], v[154:157], v[202:205], v[90:93]
	v_mfma_f32_16x16x32_bf16 v[78:81], v[130:133], v[216:219], v[78:81]
	v_mfma_f32_16x16x32_bf16 v[74:77], v[154:157], v[216:219], v[74:77]
	v_mfma_f32_16x16x32_bf16 v[126:129], v[134:137], v[190:193], v[126:129]
	v_mfma_f32_16x16x32_bf16 v[122:125], v[176:179], v[190:193], v[122:125]
	v_mfma_f32_16x16x32_bf16 v[110:113], v[134:137], v[198:201], v[110:113]
	v_mfma_f32_16x16x32_bf16 v[106:109], v[176:179], v[198:201], v[106:109]
	v_mfma_f32_16x16x32_bf16 v[94:97], v[134:137], v[206:209], v[94:97]
	v_mfma_f32_16x16x32_bf16 v[90:93], v[176:179], v[206:209], v[90:93]
	v_mfma_f32_16x16x32_bf16 v[78:81], v[134:137], v[230:233], v[78:81]
	v_mfma_f32_16x16x32_bf16 v[74:77], v[176:179], v[230:233], v[74:77]
	v_mfma_f32_16x16x32_bf16 v[118:121], v[234:237], v[186:189], v[118:121]
	v_mfma_f32_16x16x32_bf16 v[114:117], v[242:245], v[186:189], v[114:117]
	v_mfma_f32_16x16x32_bf16 v[102:105], v[234:237], v[194:197], v[102:105]
	v_mfma_f32_16x16x32_bf16 v[98:101], v[242:245], v[194:197], v[98:101]
	v_mfma_f32_16x16x32_bf16 v[86:89], v[234:237], v[202:205], v[86:89]
	v_mfma_f32_16x16x32_bf16 v[82:85], v[242:245], v[202:205], v[82:85]
	v_mfma_f32_16x16x32_bf16 v[70:73], v[234:237], v[216:219], v[70:73]
	v_mfma_f32_16x16x32_bf16 v[66:69], v[242:245], v[216:219], v[66:69]
	v_mfma_f32_16x16x32_bf16 v[118:121], v[238:241], v[190:193], v[118:121]
	v_mfma_f32_16x16x32_bf16 v[114:117], v[246:249], v[190:193], v[114:117]
	v_mfma_f32_16x16x32_bf16 v[102:105], v[238:241], v[198:201], v[102:105]
	v_mfma_f32_16x16x32_bf16 v[98:101], v[246:249], v[198:201], v[98:101]
	v_mfma_f32_16x16x32_bf16 v[86:89], v[238:241], v[206:209], v[86:89]
	v_mfma_f32_16x16x32_bf16 v[82:85], v[246:249], v[206:209], v[82:85]
	v_mfma_f32_16x16x32_bf16 v[70:73], v[238:241], v[230:233], v[70:73]
	v_mfma_f32_16x16x32_bf16 v[66:69], v[246:249], v[230:233], v[66:69]
	s_setprio 1
	s_barrier
	ds_read_b128 v[186:189], v185 offset:49152
	ds_read_b128 v[190:193], v185 offset:50176
	ds_read_b128 v[194:197], v185 offset:51200
	ds_read_b128 v[198:201], v185 offset:52224
	ds_read_b128 v[202:205], v185 offset:53248
	ds_read_b128 v[206:209], v185 offset:54272
	ds_read_b128 v[216:219], v185 offset:55296
	ds_read_b128 v[230:233], v185 offset:56320
	s_add_i32 s1, s1, s48
	v_lshl_add_u64 v[160:161], v[160:161], 0, s[12:13]
	s_mov_b32 m0, s1
	s_nop 0
	global_load_lds_dwordx4 v[160:161], off
	v_lshl_add_u64 v[160:161], v[220:221], 0, s[12:13]
	s_add_i32 m0, s1, 0x2000
	s_nop 0
	global_load_lds_dwordx4 v[160:161], off
	s_mov_b32 m0, s55
	v_lshl_add_u64 v[160:161], v[250:251], 0, s[12:13]
	global_load_lds_dwordx4 v[160:161], off
	v_lshl_add_u64 v[160:161], v[168:169], 0, s[12:13]
	s_mov_b32 m0, s56
	s_nop 0
	global_load_lds_dwordx4 v[160:161], off
	s_add_u32 s22, s30, 0x40080
	s_addc_u32 s23, s31, 0
	s_add_i32 s1, s33, s48
	s_mov_b32 m0, s1
	s_nop 0
	global_load_lds_dwordx4 v0, s[22:23]
	s_add_i32 m0, s1, 0x2000
	s_nop 0
	global_load_lds_dwordx4 v138, s[22:23]
	s_waitcnt vmcnt(8)
	s_waitcnt lgkmcnt(0)
	s_barrier
	s_setprio 0
	v_mfma_f32_16x16x32_bf16 v[62:65], v[130:133], v[186:189], v[62:65]
	v_mfma_f32_16x16x32_bf16 v[58:61], v[154:157], v[186:189], v[58:61]
	v_mfma_f32_16x16x32_bf16 v[46:49], v[130:133], v[194:197], v[46:49]
	v_mfma_f32_16x16x32_bf16 v[42:45], v[154:157], v[194:197], v[42:45]
	v_mfma_f32_16x16x32_bf16 v[30:33], v[130:133], v[202:205], v[30:33]
	v_mfma_f32_16x16x32_bf16 v[26:29], v[154:157], v[202:205], v[26:29]
	v_mfma_f32_16x16x32_bf16 v[14:17], v[130:133], v[216:219], v[14:17]
	v_mfma_f32_16x16x32_bf16 v[10:13], v[154:157], v[216:219], v[10:13]
	v_mfma_f32_16x16x32_bf16 v[62:65], v[134:137], v[190:193], v[62:65]
	v_mfma_f32_16x16x32_bf16 v[58:61], v[176:179], v[190:193], v[58:61]
	v_mfma_f32_16x16x32_bf16 v[46:49], v[134:137], v[198:201], v[46:49]
	v_mfma_f32_16x16x32_bf16 v[42:45], v[176:179], v[198:201], v[42:45]
	v_mfma_f32_16x16x32_bf16 v[30:33], v[134:137], v[206:209], v[30:33]
	v_mfma_f32_16x16x32_bf16 v[26:29], v[176:179], v[206:209], v[26:29]
	v_mfma_f32_16x16x32_bf16 v[14:17], v[134:137], v[230:233], v[14:17]
	v_mfma_f32_16x16x32_bf16 v[10:13], v[176:179], v[230:233], v[10:13]
	v_mfma_f32_16x16x32_bf16 v[54:57], v[234:237], v[186:189], v[54:57]
	v_mfma_f32_16x16x32_bf16 v[50:53], v[242:245], v[186:189], v[50:53]
	v_mfma_f32_16x16x32_bf16 v[38:41], v[234:237], v[194:197], v[38:41]
	v_mfma_f32_16x16x32_bf16 v[34:37], v[242:245], v[194:197], v[34:37]
	v_mfma_f32_16x16x32_bf16 v[22:25], v[234:237], v[202:205], v[22:25]
	v_mfma_f32_16x16x32_bf16 v[18:21], v[242:245], v[202:205], v[18:21]
	v_mfma_f32_16x16x32_bf16 v[6:9], v[234:237], v[216:219], v[6:9]
	v_mfma_f32_16x16x32_bf16 v[2:5], v[242:245], v[216:219], v[2:5]
	v_mfma_f32_16x16x32_bf16 v[54:57], v[238:241], v[190:193], v[54:57]
	v_mfma_f32_16x16x32_bf16 v[50:53], v[246:249], v[190:193], v[50:53]
	v_mfma_f32_16x16x32_bf16 v[38:41], v[238:241], v[198:201], v[38:41]
	v_mfma_f32_16x16x32_bf16 v[34:37], v[246:249], v[198:201], v[34:37]
	v_mfma_f32_16x16x32_bf16 v[22:25], v[238:241], v[206:209], v[22:25]
	v_mfma_f32_16x16x32_bf16 v[18:21], v[246:249], v[206:209], v[18:21]
	v_mfma_f32_16x16x32_bf16 v[6:9], v[238:241], v[230:233], v[6:9]
	v_mfma_f32_16x16x32_bf16 v[2:5], v[246:249], v[230:233], v[2:5]
	s_setprio 1
	s_add_i32 s44, s44, 2
	s_add_u32 s28, s28, 0x100
	s_addc_u32 s29, s29, 0
	s_add_u32 s25, s25, 0x100
	s_addc_u32 s34, s34, 0
	s_cmp_gt_u32 s44, 13
	s_barrier
.LBB0_362:
	s_add_u32 s1, s28, 0xfffc0080
	s_addc_u32 s22, s29, -1
	s_add_i32 s23, 0, 0x10000
	v_add_u32_e32 v158, s23, v181
	ds_read_b128 v[130:133], v158
	ds_read_b128 v[134:137], v158 offset:1024
	ds_read_b128 v[154:157], v158 offset:2048
	ds_read_b128 v[186:189], v158 offset:3072
	s_cmp_eq_u32 s44, 12
	s_cselect_b32 s43, s17, s22
	s_cselect_b32 s42, s20, s1
	s_cselect_b32 s31, s9, s34
	s_cselect_b32 s30, s21, s25
	v_lshl_add_u64 v[160:161], s[28:29], 0, v[150:151]
	s_add_i32 m0, s49, 0xc000
	ds_read_b128 v[190:193], v185
	ds_read_b128 v[194:197], v185 offset:1024
	ds_read_b128 v[198:201], v185 offset:2048
	ds_read_b128 v[202:205], v185 offset:3072
	ds_read_b128 v[206:209], v185 offset:4096
	ds_read_b128 v[216:219], v185 offset:5120
	ds_read_b128 v[230:233], v185 offset:6144
	ds_read_b128 v[234:237], v185 offset:7168
	global_load_lds_dwordx4 v[160:161], off
	v_lshl_add_u64 v[160:161], s[28:29], 0, v[152:153]
	s_add_i32 m0, s49, 0xe000
	s_nop 0
	global_load_lds_dwordx4 v[160:161], off
	s_add_i32 s1, 0, 0x14000
	v_add_u32_e32 v158, s1, v181
	ds_read_b128 v[238:241], v158
	ds_read_b128 v[242:245], v158 offset:1024
	ds_read_b128 v[246:249], v158 offset:2048
	ds_read_b128 v[176:179], v158 offset:3072
	s_waitcnt vmcnt(8)
	s_waitcnt lgkmcnt(0)
	s_barrier
	s_setprio 0
	v_mfma_f32_16x16x32_bf16 v[126:129], v[130:133], v[190:193], v[126:129]
	v_mfma_f32_16x16x32_bf16 v[122:125], v[154:157], v[190:193], v[122:125]
	v_mfma_f32_16x16x32_bf16 v[110:113], v[130:133], v[198:201], v[110:113]
	v_mfma_f32_16x16x32_bf16 v[106:109], v[154:157], v[198:201], v[106:109]
	v_mfma_f32_16x16x32_bf16 v[94:97], v[130:133], v[206:209], v[94:97]
	v_mfma_f32_16x16x32_bf16 v[90:93], v[154:157], v[206:209], v[90:93]
	v_mfma_f32_16x16x32_bf16 v[78:81], v[130:133], v[230:233], v[78:81]
	v_mfma_f32_16x16x32_bf16 v[74:77], v[154:157], v[230:233], v[74:77]
	v_mfma_f32_16x16x32_bf16 v[126:129], v[134:137], v[194:197], v[126:129]
	v_mfma_f32_16x16x32_bf16 v[122:125], v[186:189], v[194:197], v[122:125]
	v_mfma_f32_16x16x32_bf16 v[110:113], v[134:137], v[202:205], v[110:113]
	v_mfma_f32_16x16x32_bf16 v[106:109], v[186:189], v[202:205], v[106:109]
	v_mfma_f32_16x16x32_bf16 v[94:97], v[134:137], v[216:219], v[94:97]
	v_mfma_f32_16x16x32_bf16 v[90:93], v[186:189], v[216:219], v[90:93]
	v_mfma_f32_16x16x32_bf16 v[78:81], v[134:137], v[234:237], v[78:81]
	v_mfma_f32_16x16x32_bf16 v[74:77], v[186:189], v[234:237], v[74:77]
	v_mfma_f32_16x16x32_bf16 v[118:121], v[238:241], v[190:193], v[118:121]
	v_mfma_f32_16x16x32_bf16 v[114:117], v[246:249], v[190:193], v[114:117]
	v_mfma_f32_16x16x32_bf16 v[102:105], v[238:241], v[198:201], v[102:105]
	v_mfma_f32_16x16x32_bf16 v[98:101], v[246:249], v[198:201], v[98:101]
	v_mfma_f32_16x16x32_bf16 v[86:89], v[238:241], v[206:209], v[86:89]
	v_mfma_f32_16x16x32_bf16 v[82:85], v[246:249], v[206:209], v[82:85]
	v_mfma_f32_16x16x32_bf16 v[70:73], v[238:241], v[230:233], v[70:73]
	v_mfma_f32_16x16x32_bf16 v[66:69], v[246:249], v[230:233], v[66:69]
	v_mfma_f32_16x16x32_bf16 v[118:121], v[242:245], v[194:197], v[118:121]
	v_mfma_f32_16x16x32_bf16 v[114:117], v[176:179], v[194:197], v[114:117]
	v_mfma_f32_16x16x32_bf16 v[102:105], v[242:245], v[202:205], v[102:105]
	v_mfma_f32_16x16x32_bf16 v[98:101], v[176:179], v[202:205], v[98:101]
	v_mfma_f32_16x16x32_bf16 v[86:89], v[242:245], v[216:219], v[86:89]
	v_mfma_f32_16x16x32_bf16 v[82:85], v[176:179], v[216:219], v[82:85]
	v_mfma_f32_16x16x32_bf16 v[70:73], v[242:245], v[234:237], v[70:73]
	v_mfma_f32_16x16x32_bf16 v[66:69], v[176:179], v[234:237], v[66:69]
	s_setprio 1
	s_barrier
	ds_read_b128 v[190:193], v185 offset:16384
	ds_read_b128 v[194:197], v185 offset:17408
	ds_read_b128 v[198:201], v185 offset:18432
	ds_read_b128 v[202:205], v185 offset:19456
	ds_read_b128 v[206:209], v185 offset:20480
	ds_read_b128 v[216:219], v185 offset:21504
	ds_read_b128 v[230:233], v185 offset:22528
	ds_read_b128 v[234:237], v185 offset:23552
	s_add_i32 s22, s23, s48
	v_lshl_add_u64 v[160:161], s[30:31], 0, v[0:1]
	s_mov_b32 m0, s22
	s_nop 0
	global_load_lds_dwordx4 v[160:161], off
	v_lshl_add_u64 v[220:221], s[30:31], 0, v[138:139]
	s_add_i32 m0, s22, 0x2000
	s_nop 0
	global_load_lds_dwordx4 v[220:221], off
	s_mov_b32 m0, s49
	v_lshl_add_u64 v[250:251], s[42:43], 0, v[142:143]
	global_load_lds_dwordx4 v[250:251], off
	v_lshl_add_u64 v[168:169], s[42:43], 0, v[140:141]
	s_mov_b32 m0, s50
	s_nop 0
	global_load_lds_dwordx4 v[168:169], off
	s_add_u32 s22, s30, 0x40000
	s_addc_u32 s23, s31, 0
	s_add_i32 s1, s1, s48
	s_mov_b32 m0, s1
	s_nop 0
	global_load_lds_dwordx4 v0, s[22:23]
	s_add_i32 m0, s1, 0x2000
	s_nop 0
	global_load_lds_dwordx4 v138, s[22:23]
	s_waitcnt vmcnt(8)
	s_waitcnt lgkmcnt(0)
	s_barrier
	s_setprio 0
	v_mfma_f32_16x16x32_bf16 v[62:65], v[130:133], v[190:193], v[62:65]
	v_mfma_f32_16x16x32_bf16 v[58:61], v[154:157], v[190:193], v[58:61]
	v_mfma_f32_16x16x32_bf16 v[46:49], v[130:133], v[198:201], v[46:49]
	v_mfma_f32_16x16x32_bf16 v[42:45], v[154:157], v[198:201], v[42:45]
	v_mfma_f32_16x16x32_bf16 v[30:33], v[130:133], v[206:209], v[30:33]
	v_mfma_f32_16x16x32_bf16 v[26:29], v[154:157], v[206:209], v[26:29]
	v_mfma_f32_16x16x32_bf16 v[14:17], v[130:133], v[230:233], v[14:17]
	v_mfma_f32_16x16x32_bf16 v[10:13], v[154:157], v[230:233], v[10:13]
	v_mfma_f32_16x16x32_bf16 v[62:65], v[134:137], v[194:197], v[62:65]
	v_mfma_f32_16x16x32_bf16 v[58:61], v[186:189], v[194:197], v[58:61]
	v_mfma_f32_16x16x32_bf16 v[46:49], v[134:137], v[202:205], v[46:49]
	v_mfma_f32_16x16x32_bf16 v[42:45], v[186:189], v[202:205], v[42:45]
	v_mfma_f32_16x16x32_bf16 v[30:33], v[134:137], v[216:219], v[30:33]
	v_mfma_f32_16x16x32_bf16 v[26:29], v[186:189], v[216:219], v[26:29]
	v_mfma_f32_16x16x32_bf16 v[14:17], v[134:137], v[234:237], v[14:17]
	v_mfma_f32_16x16x32_bf16 v[10:13], v[186:189], v[234:237], v[10:13]
	v_mfma_f32_16x16x32_bf16 v[54:57], v[238:241], v[190:193], v[54:57]
	v_mfma_f32_16x16x32_bf16 v[50:53], v[246:249], v[190:193], v[50:53]
	v_mfma_f32_16x16x32_bf16 v[38:41], v[238:241], v[198:201], v[38:41]
	v_mfma_f32_16x16x32_bf16 v[34:37], v[246:249], v[198:201], v[34:37]
	v_mfma_f32_16x16x32_bf16 v[22:25], v[238:241], v[206:209], v[22:25]
	v_mfma_f32_16x16x32_bf16 v[18:21], v[246:249], v[206:209], v[18:21]
	v_mfma_f32_16x16x32_bf16 v[6:9], v[238:241], v[230:233], v[6:9]
	v_mfma_f32_16x16x32_bf16 v[2:5], v[246:249], v[230:233], v[2:5]
	v_mfma_f32_16x16x32_bf16 v[54:57], v[242:245], v[194:197], v[54:57]
	v_mfma_f32_16x16x32_bf16 v[50:53], v[176:179], v[194:197], v[50:53]
	v_mfma_f32_16x16x32_bf16 v[38:41], v[242:245], v[202:205], v[38:41]
	v_mfma_f32_16x16x32_bf16 v[34:37], v[176:179], v[202:205], v[34:37]
	v_mfma_f32_16x16x32_bf16 v[22:25], v[242:245], v[216:219], v[22:25]
	v_mfma_f32_16x16x32_bf16 v[18:21], v[176:179], v[216:219], v[18:21]
	v_mfma_f32_16x16x32_bf16 v[6:9], v[242:245], v[234:237], v[6:9]
	v_mfma_f32_16x16x32_bf16 v[2:5], v[176:179], v[234:237], v[2:5]
	s_setprio 1
	s_barrier
	s_add_i32 s1, 0, 0x18000
	v_add_u32_e32 v158, s1, v181
	ds_read_b128 v[130:133], v158
	ds_read_b128 v[134:137], v158 offset:1024
	ds_read_b128 v[154:157], v158 offset:2048
	ds_read_b128 v[176:179], v158 offset:3072
	s_add_u32 s22, s42, 0x40000
	s_addc_u32 s23, s43, 0
	s_mov_b32 m0, s51
	v_lshl_add_u64 v[234:235], s[22:23], 0, v[142:143]
	ds_read_b128 v[186:189], v185 offset:32768
	ds_read_b128 v[190:193], v185 offset:33792
	ds_read_b128 v[194:197], v185 offset:34816
	ds_read_b128 v[198:201], v185 offset:35840
	ds_read_b128 v[202:205], v185 offset:36864
	ds_read_b128 v[206:209], v185 offset:37888
	ds_read_b128 v[216:219], v185 offset:38912
	ds_read_b128 v[230:233], v185 offset:39936
	global_load_lds_dwordx4 v[234:235], off
	v_lshl_add_u64 v[234:235], s[22:23], 0, v[140:141]
	s_mov_b32 m0, s52
	s_nop 0
	global_load_lds_dwordx4 v[234:235], off
	s_add_i32 s33, 0, 0x1c000
	v_add_u32_e32 v158, s33, v181
	ds_read_b128 v[234:237], v158
	ds_read_b128 v[238:241], v158 offset:1024
	ds_read_b128 v[242:245], v158 offset:2048
	ds_read_b128 v[246:249], v158 offset:3072
	s_waitcnt vmcnt(8)
	s_waitcnt lgkmcnt(0)
	s_barrier
	s_setprio 0
	v_mfma_f32_16x16x32_bf16 v[126:129], v[130:133], v[186:189], v[126:129]
	v_mfma_f32_16x16x32_bf16 v[122:125], v[154:157], v[186:189], v[122:125]
	v_mfma_f32_16x16x32_bf16 v[110:113], v[130:133], v[194:197], v[110:113]
	v_mfma_f32_16x16x32_bf16 v[106:109], v[154:157], v[194:197], v[106:109]
	v_mfma_f32_16x16x32_bf16 v[94:97], v[130:133], v[202:205], v[94:97]
	v_mfma_f32_16x16x32_bf16 v[90:93], v[154:157], v[202:205], v[90:93]
	v_mfma_f32_16x16x32_bf16 v[78:81], v[130:133], v[216:219], v[78:81]
	v_mfma_f32_16x16x32_bf16 v[74:77], v[154:157], v[216:219], v[74:77]
	v_mfma_f32_16x16x32_bf16 v[126:129], v[134:137], v[190:193], v[126:129]
	v_mfma_f32_16x16x32_bf16 v[122:125], v[176:179], v[190:193], v[122:125]
	v_mfma_f32_16x16x32_bf16 v[110:113], v[134:137], v[198:201], v[110:113]
	v_mfma_f32_16x16x32_bf16 v[106:109], v[176:179], v[198:201], v[106:109]
	v_mfma_f32_16x16x32_bf16 v[94:97], v[134:137], v[206:209], v[94:97]
	v_mfma_f32_16x16x32_bf16 v[90:93], v[176:179], v[206:209], v[90:93]
	v_mfma_f32_16x16x32_bf16 v[78:81], v[134:137], v[230:233], v[78:81]
	v_mfma_f32_16x16x32_bf16 v[74:77], v[176:179], v[230:233], v[74:77]
	v_mfma_f32_16x16x32_bf16 v[118:121], v[234:237], v[186:189], v[118:121]
	v_mfma_f32_16x16x32_bf16 v[114:117], v[242:245], v[186:189], v[114:117]
	v_mfma_f32_16x16x32_bf16 v[102:105], v[234:237], v[194:197], v[102:105]
	v_mfma_f32_16x16x32_bf16 v[98:101], v[242:245], v[194:197], v[98:101]
	v_mfma_f32_16x16x32_bf16 v[86:89], v[234:237], v[202:205], v[86:89]
	v_mfma_f32_16x16x32_bf16 v[82:85], v[242:245], v[202:205], v[82:85]
	v_mfma_f32_16x16x32_bf16 v[70:73], v[234:237], v[216:219], v[70:73]
	v_mfma_f32_16x16x32_bf16 v[66:69], v[242:245], v[216:219], v[66:69]
	v_mfma_f32_16x16x32_bf16 v[118:121], v[238:241], v[190:193], v[118:121]
	v_mfma_f32_16x16x32_bf16 v[114:117], v[246:249], v[190:193], v[114:117]
	v_mfma_f32_16x16x32_bf16 v[102:105], v[238:241], v[198:201], v[102:105]
	v_mfma_f32_16x16x32_bf16 v[98:101], v[246:249], v[198:201], v[98:101]
	v_mfma_f32_16x16x32_bf16 v[86:89], v[238:241], v[206:209], v[86:89]
	v_mfma_f32_16x16x32_bf16 v[82:85], v[246:249], v[206:209], v[82:85]
	v_mfma_f32_16x16x32_bf16 v[70:73], v[238:241], v[230:233], v[70:73]
	v_mfma_f32_16x16x32_bf16 v[66:69], v[246:249], v[230:233], v[66:69]
	s_setprio 1
	s_barrier
	ds_read_b128 v[186:189], v185 offset:49152
	ds_read_b128 v[190:193], v185 offset:50176
	ds_read_b128 v[194:197], v185 offset:51200
	ds_read_b128 v[198:201], v185 offset:52224
	ds_read_b128 v[202:205], v185 offset:53248
	ds_read_b128 v[206:209], v185 offset:54272
	ds_read_b128 v[216:219], v185 offset:55296
	ds_read_b128 v[230:233], v185 offset:56320
	s_add_i32 s1, s1, s48
	v_lshl_add_u64 v[160:161], v[160:161], 0, s[12:13]
	s_mov_b32 m0, s1
	s_nop 0
	global_load_lds_dwordx4 v[160:161], off
	v_lshl_add_u64 v[160:161], v[220:221], 0, s[12:13]
	s_add_i32 m0, s1, 0x2000
	s_nop 0
	global_load_lds_dwordx4 v[160:161], off
	s_mov_b32 m0, s55
	v_lshl_add_u64 v[160:161], v[250:251], 0, s[12:13]
	global_load_lds_dwordx4 v[160:161], off
	v_lshl_add_u64 v[160:161], v[168:169], 0, s[12:13]
	s_mov_b32 m0, s56
	s_nop 0
	global_load_lds_dwordx4 v[160:161], off
	s_add_u32 s22, s30, 0x40080
	s_addc_u32 s23, s31, 0
	s_add_i32 s1, s33, s48
	s_mov_b32 m0, s1
	s_nop 0
	global_load_lds_dwordx4 v0, s[22:23]
	s_add_i32 m0, s1, 0x2000
	s_nop 0
	global_load_lds_dwordx4 v138, s[22:23]
	s_waitcnt vmcnt(8)
	s_waitcnt lgkmcnt(0)
	s_barrier
	s_setprio 0
	v_mfma_f32_16x16x32_bf16 v[62:65], v[130:133], v[186:189], v[62:65]
	v_mfma_f32_16x16x32_bf16 v[58:61], v[154:157], v[186:189], v[58:61]
	v_mfma_f32_16x16x32_bf16 v[46:49], v[130:133], v[194:197], v[46:49]
	v_mfma_f32_16x16x32_bf16 v[42:45], v[154:157], v[194:197], v[42:45]
	v_mfma_f32_16x16x32_bf16 v[30:33], v[130:133], v[202:205], v[30:33]
	v_mfma_f32_16x16x32_bf16 v[26:29], v[154:157], v[202:205], v[26:29]
	v_mfma_f32_16x16x32_bf16 v[14:17], v[130:133], v[216:219], v[14:17]
	v_mfma_f32_16x16x32_bf16 v[10:13], v[154:157], v[216:219], v[10:13]
	v_mfma_f32_16x16x32_bf16 v[62:65], v[134:137], v[190:193], v[62:65]
	v_mfma_f32_16x16x32_bf16 v[58:61], v[176:179], v[190:193], v[58:61]
	v_mfma_f32_16x16x32_bf16 v[46:49], v[134:137], v[198:201], v[46:49]
	v_mfma_f32_16x16x32_bf16 v[42:45], v[176:179], v[198:201], v[42:45]
	v_mfma_f32_16x16x32_bf16 v[30:33], v[134:137], v[206:209], v[30:33]
	v_mfma_f32_16x16x32_bf16 v[26:29], v[176:179], v[206:209], v[26:29]
	v_mfma_f32_16x16x32_bf16 v[14:17], v[134:137], v[230:233], v[14:17]
	v_mfma_f32_16x16x32_bf16 v[10:13], v[176:179], v[230:233], v[10:13]
	v_mfma_f32_16x16x32_bf16 v[54:57], v[234:237], v[186:189], v[54:57]
	v_mfma_f32_16x16x32_bf16 v[50:53], v[242:245], v[186:189], v[50:53]
	v_mfma_f32_16x16x32_bf16 v[38:41], v[234:237], v[194:197], v[38:41]
	v_mfma_f32_16x16x32_bf16 v[34:37], v[242:245], v[194:197], v[34:37]
	v_mfma_f32_16x16x32_bf16 v[22:25], v[234:237], v[202:205], v[22:25]
	v_mfma_f32_16x16x32_bf16 v[18:21], v[242:245], v[202:205], v[18:21]
	v_mfma_f32_16x16x32_bf16 v[6:9], v[234:237], v[216:219], v[6:9]
	v_mfma_f32_16x16x32_bf16 v[2:5], v[242:245], v[216:219], v[2:5]
	v_mfma_f32_16x16x32_bf16 v[54:57], v[238:241], v[190:193], v[54:57]
	v_mfma_f32_16x16x32_bf16 v[50:53], v[246:249], v[190:193], v[50:53]
	v_mfma_f32_16x16x32_bf16 v[38:41], v[238:241], v[198:201], v[38:41]
	v_mfma_f32_16x16x32_bf16 v[34:37], v[246:249], v[198:201], v[34:37]
	v_mfma_f32_16x16x32_bf16 v[22:25], v[238:241], v[206:209], v[22:25]
	v_mfma_f32_16x16x32_bf16 v[18:21], v[246:249], v[206:209], v[18:21]
	v_mfma_f32_16x16x32_bf16 v[6:9], v[238:241], v[230:233], v[6:9]
	v_mfma_f32_16x16x32_bf16 v[2:5], v[246:249], v[230:233], v[2:5]
	s_setprio 1
	s_add_i32 s44, s44, 2
	s_add_u32 s28, s28, 0x100
	s_addc_u32 s29, s29, 0
	s_add_u32 s25, s25, 0x100
	s_addc_u32 s34, s34, 0
	s_cmp_gt_u32 s44, 13
	s_barrier
	s_cbranch_scc0 .LBB0_362
	s_cmpk_gt_u32 s4, 0xff
	s_cbranch_scc1 .Lrs_proj1_post
	s_barrier
